# work queue + compact exact 64-bit-key top-k rank loop + redundant scan nops removed
# speedup vs baseline: 1.0092x; 1.0092x over previous
; DI void attn_item(const Args& a, int l, int item, LAS unsigned char* lds, bool dry = false) {
;     ...
;     for (int k = 0; k < 8; ++k) {
;         const int tk = wid * 8 + k;
;         float val = (imp[(0 * 64 + tk) * 64 + lane] * linv[tk] + imp[(1 * 64 + tk) * 64 + lane] * linv[64 + tk]) + (imp[(2 * 64 + tk) * 64 + lane] * linv[128 + tk] + imp[(3 * 64 + tk) * 64 + lane] * linv[192 + tk]);
;         const bool causal = lane <= qb, forced = (lane == 0) || (lane == qb) || (lane == qb - 1);
;         val = causal ? val + (forced ? 1000.f : 0.f) : -1.f;
;         int rank = 0;
; #pragma unroll
;         for (int j = 0; j < 64; ++j) { const float vj = __builtin_bit_cast(float, __builtin_amdgcn_readlane(__builtin_bit_cast(int, val), j)); rank += (vj > val || (vj == val && j < lane)) ? 1 : 0; }
;         const unsigned long long mk = __ballot(rank < 16 && causal);
;         if (lane == 0) selm[tk] = mk;
;     }
.LBB0_363:
	v_add_u32_e32 v41, 0, v80
	v_add_u32_e32 v39, 0, v35
	v_add_u32_e32 v38, 0x10200, v41
	v_add_u32_e32 v40, 0x10300, v41
	ds_read2st64_b32 v[36:37], v39 offset1:64
	ds_read_b32 v38, v38
	ds_read_b32 v40, v40
	ds_read2st64_b32 v[42:43], v39 offset0:128 offset1:192
	v_add_u32_e32 v39, 0x10400, v41
	v_add_u32_e32 v41, 0x10500, v41
	ds_read_b32 v39, v39
	ds_read_b32 v41, v41
	s_waitcnt lgkmcnt(2)
	v_mov_b32_e32 v45, v42
	v_mov_b32_e32 v42, v37
	v_mov_b32_e32 v44, v36
	s_waitcnt lgkmcnt(0)
	v_pk_mul_f32 v[36:37], v[42:43], v[40:41]
	s_nop 0
	v_pk_fma_f32 v[36:37], v[44:45], v[38:39], v[36:37]
	s_nop 0
	v_pk_add_f32 v[36:37], v[36:37], v[36:37] op_sel:[0,1] op_sel_hi:[1,0]
	s_nop 0
	v_add_f32_e32 v36, v33, v36
	v_cndmask_b32_e64 v36, -1.0, v36, s[74:75]
	s_nop 0
	v_mov_b32_e32 v37, 0
	v_sub_u32_e32 v38, 63, v32
	v_mov_b32_e32 v39, v36
	v_readlane_b32 s59, v36, 0
	v_readlane_b32 s61, v36, 1
	v_readlane_b32 s63, v36, 2
	v_readlane_b32 s65, v36, 3
	s_mov_b32 s58, 63
	s_mov_b32 s60, 62
	s_mov_b32 s62, 61
	s_mov_b32 s64, 60
	v_cmp_gt_i64_e64 s[66:67], s[58:59], v[38:39]
	v_cmp_gt_i64_e64 s[68:69], s[60:61], v[38:39]
	v_cmp_gt_i64_e64 s[70:71], s[62:63], v[38:39]
	v_cmp_gt_i64_e64 s[80:81], s[64:65], v[38:39]
	v_addc_co_u32_e64 v37, s[2:3], 0, v37, s[66:67]
	v_addc_co_u32_e64 v37, s[2:3], 0, v37, s[68:69]
	v_addc_co_u32_e64 v37, s[2:3], 0, v37, s[70:71]
	v_addc_co_u32_e64 v37, s[2:3], 0, v37, s[80:81]
	v_readlane_b32 s59, v36, 4
	v_readlane_b32 s61, v36, 5
	v_readlane_b32 s63, v36, 6
	v_readlane_b32 s65, v36, 7
	s_mov_b32 s58, 59
	s_mov_b32 s60, 58
	s_mov_b32 s62, 57
	s_mov_b32 s64, 56
	v_cmp_gt_i64_e64 s[66:67], s[58:59], v[38:39]
	v_cmp_gt_i64_e64 s[68:69], s[60:61], v[38:39]
	v_cmp_gt_i64_e64 s[70:71], s[62:63], v[38:39]
	v_cmp_gt_i64_e64 s[80:81], s[64:65], v[38:39]
	v_addc_co_u32_e64 v37, s[2:3], 0, v37, s[66:67]
	v_addc_co_u32_e64 v37, s[2:3], 0, v37, s[68:69]
	v_addc_co_u32_e64 v37, s[2:3], 0, v37, s[70:71]
	v_addc_co_u32_e64 v37, s[2:3], 0, v37, s[80:81]
	v_readlane_b32 s59, v36, 8
	v_readlane_b32 s61, v36, 9
	v_readlane_b32 s63, v36, 10
	v_readlane_b32 s65, v36, 11
	s_mov_b32 s58, 55
	s_mov_b32 s60, 54
	s_mov_b32 s62, 53
	s_mov_b32 s64, 52
	v_cmp_gt_i64_e64 s[66:67], s[58:59], v[38:39]
	v_cmp_gt_i64_e64 s[68:69], s[60:61], v[38:39]
	v_cmp_gt_i64_e64 s[70:71], s[62:63], v[38:39]
	v_cmp_gt_i64_e64 s[80:81], s[64:65], v[38:39]
	v_addc_co_u32_e64 v37, s[2:3], 0, v37, s[66:67]
	v_addc_co_u32_e64 v37, s[2:3], 0, v37, s[68:69]
	v_addc_co_u32_e64 v37, s[2:3], 0, v37, s[70:71]
	v_addc_co_u32_e64 v37, s[2:3], 0, v37, s[80:81]
	v_readlane_b32 s59, v36, 12
	v_readlane_b32 s61, v36, 13
	v_readlane_b32 s63, v36, 14
	v_readlane_b32 s65, v36, 15
	s_mov_b32 s58, 51
	s_mov_b32 s60, 50
	s_mov_b32 s62, 49
	s_mov_b32 s64, 48
	v_cmp_gt_i64_e64 s[66:67], s[58:59], v[38:39]
	v_cmp_gt_i64_e64 s[68:69], s[60:61], v[38:39]
	v_cmp_gt_i64_e64 s[70:71], s[62:63], v[38:39]
	v_cmp_gt_i64_e64 s[80:81], s[64:65], v[38:39]
	v_addc_co_u32_e64 v37, s[2:3], 0, v37, s[66:67]
	v_addc_co_u32_e64 v37, s[2:3], 0, v37, s[68:69]
	v_addc_co_u32_e64 v37, s[2:3], 0, v37, s[70:71]
	v_addc_co_u32_e64 v37, s[2:3], 0, v37, s[80:81]
	v_readlane_b32 s59, v36, 16
	v_readlane_b32 s61, v36, 17
	v_readlane_b32 s63, v36, 18
	v_readlane_b32 s65, v36, 19
	s_mov_b32 s58, 47
	s_mov_b32 s60, 46
	s_mov_b32 s62, 45
	s_mov_b32 s64, 44
	v_cmp_gt_i64_e64 s[66:67], s[58:59], v[38:39]
	v_cmp_gt_i64_e64 s[68:69], s[60:61], v[38:39]
	v_cmp_gt_i64_e64 s[70:71], s[62:63], v[38:39]
	v_cmp_gt_i64_e64 s[80:81], s[64:65], v[38:39]
	v_addc_co_u32_e64 v37, s[2:3], 0, v37, s[66:67]
	v_addc_co_u32_e64 v37, s[2:3], 0, v37, s[68:69]
	v_addc_co_u32_e64 v37, s[2:3], 0, v37, s[70:71]
	v_addc_co_u32_e64 v37, s[2:3], 0, v37, s[80:81]
	v_readlane_b32 s59, v36, 20
	v_readlane_b32 s61, v36, 21
	v_readlane_b32 s63, v36, 22
	v_readlane_b32 s65, v36, 23
	s_mov_b32 s58, 43
	s_mov_b32 s60, 42
	s_mov_b32 s62, 41
	s_mov_b32 s64, 40
	v_cmp_gt_i64_e64 s[66:67], s[58:59], v[38:39]
	v_cmp_gt_i64_e64 s[68:69], s[60:61], v[38:39]
	v_cmp_gt_i64_e64 s[70:71], s[62:63], v[38:39]
	v_cmp_gt_i64_e64 s[80:81], s[64:65], v[38:39]
	v_addc_co_u32_e64 v37, s[2:3], 0, v37, s[66:67]
	v_addc_co_u32_e64 v37, s[2:3], 0, v37, s[68:69]
	v_addc_co_u32_e64 v37, s[2:3], 0, v37, s[70:71]
	v_addc_co_u32_e64 v37, s[2:3], 0, v37, s[80:81]
	v_readlane_b32 s59, v36, 24
	v_readlane_b32 s61, v36, 25
	v_readlane_b32 s63, v36, 26
	v_readlane_b32 s65, v36, 27
	s_mov_b32 s58, 39
	s_mov_b32 s60, 38
	s_mov_b32 s62, 37
	s_mov_b32 s64, 36
	v_cmp_gt_i64_e64 s[66:67], s[58:59], v[38:39]
	v_cmp_gt_i64_e64 s[68:69], s[60:61], v[38:39]
	v_cmp_gt_i64_e64 s[70:71], s[62:63], v[38:39]
	v_cmp_gt_i64_e64 s[80:81], s[64:65], v[38:39]
	v_addc_co_u32_e64 v37, s[2:3], 0, v37, s[66:67]
	v_addc_co_u32_e64 v37, s[2:3], 0, v37, s[68:69]
	v_addc_co_u32_e64 v37, s[2:3], 0, v37, s[70:71]
	v_addc_co_u32_e64 v37, s[2:3], 0, v37, s[80:81]
	v_readlane_b32 s59, v36, 28
	v_readlane_b32 s61, v36, 29
	v_readlane_b32 s63, v36, 30
	v_readlane_b32 s65, v36, 31
	s_mov_b32 s58, 35
	s_mov_b32 s60, 34
	s_mov_b32 s62, 33
	s_mov_b32 s64, 32
	v_cmp_gt_i64_e64 s[66:67], s[58:59], v[38:39]
	v_cmp_gt_i64_e64 s[68:69], s[60:61], v[38:39]
	v_cmp_gt_i64_e64 s[70:71], s[62:63], v[38:39]
; DI void attn_item(const Args& a, int l, int item, LAS unsigned char* lds, bool dry = false) {
;     ...
;         for (int j = 0; j < 64; ++j) { const float vj = __builtin_bit_cast(float, __builtin_amdgcn_readlane(__builtin_bit_cast(int, val), j)); rank += (vj > val || (vj == val && j < lane)) ? 1 : 0; }
;         const unsigned long long mk = __ballot(rank < 16 && causal);
;         if (lane == 0) selm[tk] = mk;
;     }
	v_cmp_gt_i64_e64 s[80:81], s[64:65], v[38:39]
	v_addc_co_u32_e64 v37, s[2:3], 0, v37, s[66:67]
	v_addc_co_u32_e64 v37, s[2:3], 0, v37, s[68:69]
	v_addc_co_u32_e64 v37, s[2:3], 0, v37, s[70:71]
	v_addc_co_u32_e64 v37, s[2:3], 0, v37, s[80:81]
	v_readlane_b32 s59, v36, 32
	v_readlane_b32 s61, v36, 33
	v_readlane_b32 s63, v36, 34
	v_readlane_b32 s65, v36, 35
	s_mov_b32 s58, 31
	s_mov_b32 s60, 30
	s_mov_b32 s62, 29
	s_mov_b32 s64, 28
	v_cmp_gt_i64_e64 s[66:67], s[58:59], v[38:39]
	v_cmp_gt_i64_e64 s[68:69], s[60:61], v[38:39]
	v_cmp_gt_i64_e64 s[70:71], s[62:63], v[38:39]
	v_cmp_gt_i64_e64 s[80:81], s[64:65], v[38:39]
	v_addc_co_u32_e64 v37, s[2:3], 0, v37, s[66:67]
	v_addc_co_u32_e64 v37, s[2:3], 0, v37, s[68:69]
	v_addc_co_u32_e64 v37, s[2:3], 0, v37, s[70:71]
	v_addc_co_u32_e64 v37, s[2:3], 0, v37, s[80:81]
	v_readlane_b32 s59, v36, 36
	v_readlane_b32 s61, v36, 37
	v_readlane_b32 s63, v36, 38
	v_readlane_b32 s65, v36, 39
	s_mov_b32 s58, 27
	s_mov_b32 s60, 26
	s_mov_b32 s62, 25
	s_mov_b32 s64, 24
	v_cmp_gt_i64_e64 s[66:67], s[58:59], v[38:39]
	v_cmp_gt_i64_e64 s[68:69], s[60:61], v[38:39]
	v_cmp_gt_i64_e64 s[70:71], s[62:63], v[38:39]
	v_cmp_gt_i64_e64 s[80:81], s[64:65], v[38:39]
	v_addc_co_u32_e64 v37, s[2:3], 0, v37, s[66:67]
	v_addc_co_u32_e64 v37, s[2:3], 0, v37, s[68:69]
	v_addc_co_u32_e64 v37, s[2:3], 0, v37, s[70:71]
	v_addc_co_u32_e64 v37, s[2:3], 0, v37, s[80:81]
	v_readlane_b32 s59, v36, 40
	v_readlane_b32 s61, v36, 41
	v_readlane_b32 s63, v36, 42
	v_readlane_b32 s65, v36, 43
	s_mov_b32 s58, 23
	s_mov_b32 s60, 22
	s_mov_b32 s62, 21
	s_mov_b32 s64, 20
	v_cmp_gt_i64_e64 s[66:67], s[58:59], v[38:39]
	v_cmp_gt_i64_e64 s[68:69], s[60:61], v[38:39]
	v_cmp_gt_i64_e64 s[70:71], s[62:63], v[38:39]
	v_cmp_gt_i64_e64 s[80:81], s[64:65], v[38:39]
	v_addc_co_u32_e64 v37, s[2:3], 0, v37, s[66:67]
	v_addc_co_u32_e64 v37, s[2:3], 0, v37, s[68:69]
	v_addc_co_u32_e64 v37, s[2:3], 0, v37, s[70:71]
	v_addc_co_u32_e64 v37, s[2:3], 0, v37, s[80:81]
	v_readlane_b32 s59, v36, 44
	v_readlane_b32 s61, v36, 45
	v_readlane_b32 s63, v36, 46
	v_readlane_b32 s65, v36, 47
	s_mov_b32 s58, 19
	s_mov_b32 s60, 18
	s_mov_b32 s62, 17
	s_mov_b32 s64, 16
	v_cmp_gt_i64_e64 s[66:67], s[58:59], v[38:39]
	v_cmp_gt_i64_e64 s[68:69], s[60:61], v[38:39]
	v_cmp_gt_i64_e64 s[70:71], s[62:63], v[38:39]
	v_cmp_gt_i64_e64 s[80:81], s[64:65], v[38:39]
	v_addc_co_u32_e64 v37, s[2:3], 0, v37, s[66:67]
	v_addc_co_u32_e64 v37, s[2:3], 0, v37, s[68:69]
	v_addc_co_u32_e64 v37, s[2:3], 0, v37, s[70:71]
	v_addc_co_u32_e64 v37, s[2:3], 0, v37, s[80:81]
	v_readlane_b32 s59, v36, 48
	v_readlane_b32 s61, v36, 49
	v_readlane_b32 s63, v36, 50
	v_readlane_b32 s65, v36, 51
	s_mov_b32 s58, 15
	s_mov_b32 s60, 14
	s_mov_b32 s62, 13
	s_mov_b32 s64, 12
	v_cmp_gt_i64_e64 s[66:67], s[58:59], v[38:39]
	v_cmp_gt_i64_e64 s[68:69], s[60:61], v[38:39]
	v_cmp_gt_i64_e64 s[70:71], s[62:63], v[38:39]
	v_cmp_gt_i64_e64 s[80:81], s[64:65], v[38:39]
	v_addc_co_u32_e64 v37, s[2:3], 0, v37, s[66:67]
	v_addc_co_u32_e64 v37, s[2:3], 0, v37, s[68:69]
	v_addc_co_u32_e64 v37, s[2:3], 0, v37, s[70:71]
	v_addc_co_u32_e64 v37, s[2:3], 0, v37, s[80:81]
	v_readlane_b32 s59, v36, 52
	v_readlane_b32 s61, v36, 53
	v_readlane_b32 s63, v36, 54
	v_readlane_b32 s65, v36, 55
	s_mov_b32 s58, 11
	s_mov_b32 s60, 10
	s_mov_b32 s62, 9
	s_mov_b32 s64, 8
	v_cmp_gt_i64_e64 s[66:67], s[58:59], v[38:39]
	v_cmp_gt_i64_e64 s[68:69], s[60:61], v[38:39]
	v_cmp_gt_i64_e64 s[70:71], s[62:63], v[38:39]
	v_cmp_gt_i64_e64 s[80:81], s[64:65], v[38:39]
	v_addc_co_u32_e64 v37, s[2:3], 0, v37, s[66:67]
	v_addc_co_u32_e64 v37, s[2:3], 0, v37, s[68:69]
	v_addc_co_u32_e64 v37, s[2:3], 0, v37, s[70:71]
	v_addc_co_u32_e64 v37, s[2:3], 0, v37, s[80:81]
	v_readlane_b32 s59, v36, 56
	v_readlane_b32 s61, v36, 57
	v_readlane_b32 s63, v36, 58
	v_readlane_b32 s65, v36, 59
	s_mov_b32 s58, 7
	s_mov_b32 s60, 6
	s_mov_b32 s62, 5
	s_mov_b32 s64, 4
	v_cmp_gt_i64_e64 s[66:67], s[58:59], v[38:39]
	v_cmp_gt_i64_e64 s[68:69], s[60:61], v[38:39]
	v_cmp_gt_i64_e64 s[70:71], s[62:63], v[38:39]
	v_cmp_gt_i64_e64 s[80:81], s[64:65], v[38:39]
	v_addc_co_u32_e64 v37, s[2:3], 0, v37, s[66:67]
	v_addc_co_u32_e64 v37, s[2:3], 0, v37, s[68:69]
	v_addc_co_u32_e64 v37, s[2:3], 0, v37, s[70:71]
	v_addc_co_u32_e64 v37, s[2:3], 0, v37, s[80:81]
	v_readlane_b32 s59, v36, 60
	v_readlane_b32 s61, v36, 61
	v_readlane_b32 s63, v36, 62
	v_readlane_b32 s65, v36, 63
	s_mov_b32 s58, 3
	s_mov_b32 s60, 2
	s_mov_b32 s62, 1
	s_mov_b32 s64, 0
	v_cmp_gt_i64_e64 s[66:67], s[58:59], v[38:39]
	v_cmp_gt_i64_e64 s[68:69], s[60:61], v[38:39]
	v_cmp_gt_i64_e64 s[70:71], s[62:63], v[38:39]
	v_cmp_gt_i64_e64 s[80:81], s[64:65], v[38:39]
	v_addc_co_u32_e64 v37, s[2:3], 0, v37, s[66:67]
	v_addc_co_u32_e64 v37, s[2:3], 0, v37, s[68:69]
	v_addc_co_u32_e64 v37, s[2:3], 0, v37, s[70:71]
	v_addc_co_u32_e64 v37, s[2:3], 0, v37, s[80:81]
	v_mov_b32_e32 v36, v37
	v_cmp_gt_u32_e32 vcc, 16, v36
	s_and_b64 s[2:3], s[74:75], vcc
	v_cndmask_b32_e64 v36, 0, 1, s[2:3]
	v_cmp_ne_u32_e32 vcc, 0, v36
	s_and_saveexec_b64 s[2:3], s[38:39]
	s_cbranch_execz .LBB0_362
	v_add_u32_e32 v36, 0, v34
	v_mov_b64_e32 v[38:39], vcc
	ds_write_b64 v36, v[38:39]
	s_branch .LBB0_362

; #define LAS __attribute__((address_space(3)))
; DI unsigned pk2(float a, float b) { f32x2 v = {a, b}; bf2_t r = __builtin_convertvector(v, bf2_t); return __builtin_bit_cast(unsigned, r); }
; #define DPP_ADD2(a, b, ctrl) asm("s_nop 1\n\tv_add_f32_dpp %0, %0, %0 " ctrl " row_mask:0xf bank_mask:0xf bound_ctrl:1\n\tv_add_f32_dpp %1, %1, %1 " ctrl " row_mask:0xf bank_mask:0xf bound_ctrl:1" : "+v"(a), "+v"(b))
; DI f32x2 red16p(f32x2 x) { float a = x.x, b = x.y; red16x2(a, b); return (f32x2){a, b}; }
; DI void red16x2(float& a, float& b) { DPP_ADD2(a, b, "quad_perm:[1,0,3,2]"); DPP_ADD2(a, b, "quad_perm:[2,3,0,1]"); DPP_ADD2(a, b, "row_half_mirror"); DPP_ADD2(a, b, "row_mirror"); }
; DI void scan_bh2(const Args& a, int l, int bh, int halfsel, LAS unsigned char* lds) {
;     ...
;             for (int st = 0; st < T; ++st) {
;                 f32x4 nr4, nd4, nk4, nkk4, nb4; f32x2 nv2;
;                 if (st < T - 1) {
;                     const LAS float* o = cur + (st + 1) * 384;
;                     nr4 = *(const LAS f32x4*)(o + kq * 4); nd4 = *(const LAS f32x4*)(o + 64 + kq * 4); nk4 = *(const LAS f32x4*)(o + 128 + kq * 4);
;                     nkk4 = *(const LAS f32x4*)(o + 192 + kq * 4); nb4 = *(const LAS f32x4*)(o + 256 + kq * 4); nv2 = *(const LAS f32x2*)(o + 320 + row0);
;                 }
;                 f32x2 sa = S[0] * kk4[0]; sa += S[1] * kk4[1]; f32x2 sb = S[2] * kk4[2]; sb += S[3] * kk4[3]; sa += sb;
;                 sa = red16p(sa); sa = -sa;
; #pragma unroll
;                 for (int j = 0; j < 4; ++j) S[j] = S[j] * d4[j] + sa * b4[j] + v2 * k4[j];
;                 f32x2 y = S[0] * r4[0]; y += S[1] * r4[1]; f32x2 yc = S[2] * r4[2]; yc += S[3] * r4[3]; y += yc;
;                 y = red16p(y);
;                 *(LAS unsigned*)(yb + st * 128 + row0 * 2) = pk2(y.x, y.y);
;                 if (st < T - 1) { r4 = nr4; d4 = nd4; k4 = nk4; kk4 = nkk4; b4 = nb4; v2 = nv2; }
;             }
.LBB0_497:
	s_and_b32 s2, s4, 1
	s_mul_i32 s3, s2, 0xc000
	s_add_i32 s3, s3, 0
	v_lshl_add_u32 v15, v11, 2, s3
	ds_read_b128 v[18:21], v15
	ds_read_b128 v[22:25], v15 offset:256
	ds_read_b128 v[26:29], v15 offset:512
	ds_read_b128 v[30:33], v15 offset:768
	v_lshl_add_u32 v16, v10, 2, s3
	v_add_u32_e32 v14, 0x100, v16
	ds_read2st64_b64 v[34:37], v14 offset0:2 offset1:5
	ds_read_b128 v[38:41], v15 offset:1024
	ds_read_b128 v[42:45], v15 offset:1536
	ds_read_b128 v[46:49], v15 offset:1792
	ds_read_b128 v[50:53], v15 offset:2048
	ds_read_b128 v[54:57], v15 offset:2304
	ds_read_b128 v[58:61], v15 offset:2560
	s_waitcnt lgkmcnt(7)
	v_pk_mul_f32 v[62:63], v[4:5], v[30:31] op_sel:[0,1]
	s_lshl_b32 s2, s2, 12
	v_pk_fma_f32 v[30:31], v[2:3], v[30:31], v[62:63] op_sel_hi:[1,0,1]
	v_mov_b32_e32 v62, v33
	v_pk_mul_f32 v[62:63], v[8:9], v[62:63] op_sel_hi:[1,0]
	s_add_i32 s5, s2, 0
	v_pk_fma_f32 v[32:33], v[6:7], v[32:33], v[62:63] op_sel_hi:[1,0,1]
	s_add_i32 s5, s5, 0x18000
	v_pk_add_f32 v[30:31], v[30:31], v[32:33]
	v_add_u32_e32 v14, s5, v12
	s_nop 1
	v_add_f32_dpp v30, v30, v30 quad_perm:[1,0,3,2] row_mask:0xf bank_mask:0xf bound_ctrl:1
	v_add_f32_dpp v31, v31, v31 quad_perm:[1,0,3,2] row_mask:0xf bank_mask:0xf bound_ctrl:1
	s_nop 1
	v_add_f32_dpp v30, v30, v30 quad_perm:[2,3,0,1] row_mask:0xf bank_mask:0xf bound_ctrl:1
	v_add_f32_dpp v31, v31, v31 quad_perm:[2,3,0,1] row_mask:0xf bank_mask:0xf bound_ctrl:1
	s_nop 1
	v_add_f32_dpp v30, v30, v30 row_half_mirror row_mask:0xf bank_mask:0xf bound_ctrl:1
	v_add_f32_dpp v31, v31, v31 row_half_mirror row_mask:0xf bank_mask:0xf bound_ctrl:1
	s_nop 1
	v_add_f32_dpp v30, v30, v30 row_mirror row_mask:0xf bank_mask:0xf bound_ctrl:1
	v_add_f32_dpp v31, v31, v31 row_mirror row_mask:0xf bank_mask:0xf bound_ctrl:1
	s_waitcnt lgkmcnt(5)
	v_pk_mul_f32 v[32:33], v[38:39], v[30:31] op_sel_hi:[0,1]
	v_pk_fma_f32 v[2:3], v[2:3], v[22:23], v[32:33] op_sel_hi:[1,0,1] neg_lo:[0,0,1] neg_hi:[0,0,1]
	s_nop 0
	v_pk_fma_f32 v[32:33], v[26:27], v[34:35], v[2:3] op_sel_hi:[0,1,1]
	v_pk_mul_f32 v[2:3], v[38:39], v[30:31] op_sel:[1,0]
	s_nop 0
	v_pk_fma_f32 v[2:3], v[4:5], v[22:23], v[2:3] op_sel:[0,1,0] neg_lo:[0,0,1] neg_hi:[0,0,1]
	v_mov_b32_e32 v4, v41
	v_pk_fma_f32 v[38:39], v[26:27], v[34:35], v[2:3] op_sel:[1,0,0]
	v_pk_mul_f32 v[2:3], v[40:41], v[30:31] op_sel_hi:[0,1]
	v_pk_fma_f32 v[2:3], v[6:7], v[24:25], v[2:3] op_sel_hi:[1,0,1] neg_lo:[0,0,1] neg_hi:[0,0,1]
	v_pk_mul_f32 v[4:5], v[4:5], v[30:31] op_sel_hi:[0,1]
	v_pk_fma_f32 v[62:63], v[28:29], v[34:35], v[2:3] op_sel_hi:[0,1,1]
	v_mov_b32_e32 v2, v25
	v_pk_fma_f32 v[2:3], v[8:9], v[2:3], v[4:5] op_sel_hi:[1,0,1] neg_lo:[0,0,1] neg_hi:[0,0,1]
	v_mov_b32_e32 v4, v29
	v_pk_fma_f32 v[30:31], v[4:5], v[34:35], v[2:3] op_sel_hi:[0,1,1]
	s_waitcnt lgkmcnt(1)
	v_mov_b32_e32 v40, v57
	v_mov_b32_e32 v4, v21
	v_pk_mul_f32 v[34:35], v[54:55], v[38:39] op_sel:[1,0]
	v_pk_mul_f32 v[40:41], v[40:41], v[30:31] op_sel_hi:[0,1]
	v_pk_mul_f32 v[2:3], v[18:19], v[38:39] op_sel:[1,0]
	v_pk_mul_f32 v[4:5], v[4:5], v[30:31] op_sel_hi:[0,1]
	v_pk_fma_f32 v[34:35], v[54:55], v[32:33], v[34:35] op_sel_hi:[0,1,1]
	v_pk_fma_f32 v[40:41], v[56:57], v[62:63], v[40:41] op_sel_hi:[0,1,1]
	v_pk_fma_f32 v[2:3], v[18:19], v[32:33], v[2:3] op_sel_hi:[0,1,1]
	v_pk_fma_f32 v[4:5], v[20:21], v[62:63], v[4:5] op_sel_hi:[0,1,1]
	v_pk_add_f32 v[34:35], v[34:35], v[40:41]
	v_pk_add_f32 v[2:3], v[2:3], v[4:5]
	s_nop 1
	v_add_f32_dpp v34, v34, v34 quad_perm:[1,0,3,2] row_mask:0xf bank_mask:0xf bound_ctrl:1
	v_add_f32_dpp v35, v35, v35 quad_perm:[1,0,3,2] row_mask:0xf bank_mask:0xf bound_ctrl:1
	s_nop 1
	v_add_f32_dpp v2, v2, v2 quad_perm:[1,0,3,2] row_mask:0xf bank_mask:0xf bound_ctrl:1
	v_add_f32_dpp v3, v3, v3 quad_perm:[1,0,3,2] row_mask:0xf bank_mask:0xf bound_ctrl:1
	s_nop 1
	v_add_f32_dpp v34, v34, v34 quad_perm:[2,3,0,1] row_mask:0xf bank_mask:0xf bound_ctrl:1
	v_add_f32_dpp v35, v35, v35 quad_perm:[2,3,0,1] row_mask:0xf bank_mask:0xf bound_ctrl:1
	s_nop 1
	v_add_f32_dpp v2, v2, v2 quad_perm:[2,3,0,1] row_mask:0xf bank_mask:0xf bound_ctrl:1
	v_add_f32_dpp v3, v3, v3 quad_perm:[2,3,0,1] row_mask:0xf bank_mask:0xf bound_ctrl:1
	s_nop 1
	v_add_f32_dpp v34, v34, v34 row_half_mirror row_mask:0xf bank_mask:0xf bound_ctrl:1
	v_add_f32_dpp v35, v35, v35 row_half_mirror row_mask:0xf bank_mask:0xf bound_ctrl:1
	s_nop 1
	v_add_f32_dpp v2, v2, v2 row_half_mirror row_mask:0xf bank_mask:0xf bound_ctrl:1
	v_add_f32_dpp v3, v3, v3 row_half_mirror row_mask:0xf bank_mask:0xf bound_ctrl:1
	s_nop 1
	v_add_f32_dpp v34, v34, v34 row_mirror row_mask:0xf bank_mask:0xf bound_ctrl:1
	v_add_f32_dpp v35, v35, v35 row_mirror row_mask:0xf bank_mask:0xf bound_ctrl:1
	s_waitcnt lgkmcnt(0)
	v_pk_mul_f32 v[40:41], v[58:59], v[34:35] op_sel_hi:[0,1]
	s_nop 1
	v_add_f32_dpp v2, v2, v2 row_mirror row_mask:0xf bank_mask:0xf bound_ctrl:1
	v_add_f32_dpp v3, v3, v3 row_mirror row_mask:0xf bank_mask:0xf bound_ctrl:1
	v_pk_fma_f32 v[32:33], v[46:47], v[32:33], v[40:41] op_sel_hi:[0,1,1] neg_lo:[0,0,1] neg_hi:[0,0,1]
	v_cvt_pk_bf16_f32 v2, v2, v3
	v_pk_fma_f32 v[54:55], v[50:51], v[36:37], v[32:33] op_sel_hi:[0,1,1]
	v_pk_mul_f32 v[32:33], v[58:59], v[34:35] op_sel:[1,0]
	ds_write_b32 v14, v2
	v_pk_fma_f32 v[32:33], v[46:47], v[38:39], v[32:33] op_sel:[1,0,0] neg_lo:[0,0,1] neg_hi:[0,0,1]
	ds_read_b128 v[2:5], v15 offset:3072
	ds_read_b128 v[6:9], v15 offset:3328
	ds_read_b128 v[18:21], v15 offset:3584
	ds_read_b128 v[22:25], v15 offset:3840
	ds_read_b128 v[26:29], v15 offset:4096
	ds_read_b64 v[64:65], v16 offset:4352
	v_pk_fma_f32 v[50:51], v[50:51], v[36:37], v[32:33] op_sel:[1,0,0]
	v_pk_mul_f32 v[32:33], v[60:61], v[34:35] op_sel_hi:[0,1]
	v_pk_fma_f32 v[32:33], v[48:49], v[62:63], v[32:33] op_sel_hi:[0,1,1] neg_lo:[0,0,1] neg_hi:[0,0,1]
	v_mov_b32_e32 v38, v61
	v_pk_fma_f32 v[56:57], v[52:53], v[36:37], v[32:33] op_sel_hi:[0,1,1]
	v_mov_b32_e32 v32, v49
	v_pk_mul_f32 v[34:35], v[38:39], v[34:35] op_sel_hi:[0,1]
	v_pk_fma_f32 v[30:31], v[32:33], v[30:31], v[34:35] op_sel_hi:[0,1,1] neg_lo:[0,0,1] neg_hi:[0,0,1]
	v_mov_b32_e32 v32, v53
	s_waitcnt lgkmcnt(2)
; #define LAS __attribute__((address_space(3)))
; DI unsigned pk2(float a, float b) { f32x2 v = {a, b}; bf2_t r = __builtin_convertvector(v, bf2_t); return __builtin_bit_cast(unsigned, r); }
; #define DPP_ADD2(a, b, ctrl) asm("s_nop 1\n\tv_add_f32_dpp %0, %0, %0 " ctrl " row_mask:0xf bank_mask:0xf bound_ctrl:1\n\tv_add_f32_dpp %1, %1, %1 " ctrl " row_mask:0xf bank_mask:0xf bound_ctrl:1" : "+v"(a), "+v"(b))
; DI f32x2 red16p(f32x2 x) { float a = x.x, b = x.y; red16x2(a, b); return (f32x2){a, b}; }
; DI void red16x2(float& a, float& b) { DPP_ADD2(a, b, "quad_perm:[1,0,3,2]"); DPP_ADD2(a, b, "quad_perm:[2,3,0,1]"); DPP_ADD2(a, b, "row_half_mirror"); DPP_ADD2(a, b, "row_mirror"); }
; DI void scan_bh2(const Args& a, int l, int bh, int halfsel, LAS unsigned char* lds) {
;     ...
;             for (int st = 0; st < T; ++st) {
;                 f32x4 nr4, nd4, nk4, nkk4, nb4; f32x2 nv2;
;                 if (st < T - 1) {
;                     const LAS float* o = cur + (st + 1) * 384;
;                     nr4 = *(const LAS f32x4*)(o + kq * 4); nd4 = *(const LAS f32x4*)(o + 64 + kq * 4); nk4 = *(const LAS f32x4*)(o + 128 + kq * 4);
;                     nkk4 = *(const LAS f32x4*)(o + 192 + kq * 4); nb4 = *(const LAS f32x4*)(o + 256 + kq * 4); nv2 = *(const LAS f32x2*)(o + 320 + row0);
;                 }
;                 f32x2 sa = S[0] * kk4[0]; sa += S[1] * kk4[1]; f32x2 sb = S[2] * kk4[2]; sb += S[3] * kk4[3]; sa += sb;
;                 sa = red16p(sa); sa = -sa;
; #pragma unroll
;                 for (int j = 0; j < 4; ++j) S[j] = S[j] * d4[j] + sa * b4[j] + v2 * k4[j];
;                 f32x2 y = S[0] * r4[0]; y += S[1] * r4[1]; f32x2 yc = S[2] * r4[2]; yc += S[3] * r4[3]; y += yc;
;                 y = red16p(y);
;                 *(LAS unsigned*)(yb + st * 128 + row0 * 2) = pk2(y.x, y.y);
;                 if (st < T - 1) { r4 = nr4; d4 = nd4; k4 = nk4; kk4 = nkk4; b4 = nb4; v2 = nv2; }
;             }
	v_pk_mul_f32 v[60:61], v[22:23], v[50:51] op_sel:[1,0]
	v_pk_fma_f32 v[52:53], v[32:33], v[36:37], v[30:31] op_sel_hi:[0,1,1]
	v_pk_fma_f32 v[22:23], v[22:23], v[54:55], v[60:61] op_sel_hi:[0,1,1]
	v_mov_b32_e32 v60, v25
	v_pk_mul_f32 v[60:61], v[60:61], v[52:53] op_sel_hi:[0,1]
	v_mov_b32_e32 v32, v45
	v_pk_fma_f32 v[24:25], v[24:25], v[56:57], v[60:61] op_sel_hi:[0,1,1]
	v_pk_mul_f32 v[30:31], v[42:43], v[50:51] op_sel:[1,0]
	v_pk_mul_f32 v[32:33], v[32:33], v[52:53] op_sel_hi:[0,1]
	v_pk_add_f32 v[22:23], v[22:23], v[24:25]
	v_pk_fma_f32 v[30:31], v[42:43], v[54:55], v[30:31] op_sel_hi:[0,1,1]
	v_pk_fma_f32 v[32:33], v[44:45], v[56:57], v[32:33] op_sel_hi:[0,1,1]
	s_nop 1
	v_add_f32_dpp v22, v22, v22 quad_perm:[1,0,3,2] row_mask:0xf bank_mask:0xf bound_ctrl:1
	v_add_f32_dpp v23, v23, v23 quad_perm:[1,0,3,2] row_mask:0xf bank_mask:0xf bound_ctrl:1
	v_pk_add_f32 v[30:31], v[30:31], v[32:33]
	s_nop 1
	v_add_f32_dpp v22, v22, v22 quad_perm:[2,3,0,1] row_mask:0xf bank_mask:0xf bound_ctrl:1
	v_add_f32_dpp v23, v23, v23 quad_perm:[2,3,0,1] row_mask:0xf bank_mask:0xf bound_ctrl:1
	s_nop 1
	v_add_f32_dpp v30, v30, v30 quad_perm:[1,0,3,2] row_mask:0xf bank_mask:0xf bound_ctrl:1
	v_add_f32_dpp v31, v31, v31 quad_perm:[1,0,3,2] row_mask:0xf bank_mask:0xf bound_ctrl:1
	s_nop 1
	v_add_f32_dpp v22, v22, v22 row_half_mirror row_mask:0xf bank_mask:0xf bound_ctrl:1
	v_add_f32_dpp v23, v23, v23 row_half_mirror row_mask:0xf bank_mask:0xf bound_ctrl:1
	s_nop 1
	v_add_f32_dpp v30, v30, v30 quad_perm:[2,3,0,1] row_mask:0xf bank_mask:0xf bound_ctrl:1
	v_add_f32_dpp v31, v31, v31 quad_perm:[2,3,0,1] row_mask:0xf bank_mask:0xf bound_ctrl:1
	s_nop 1
	v_add_f32_dpp v22, v22, v22 row_mirror row_mask:0xf bank_mask:0xf bound_ctrl:1
	v_add_f32_dpp v23, v23, v23 row_mirror row_mask:0xf bank_mask:0xf bound_ctrl:1
	s_waitcnt lgkmcnt(1)
	v_pk_mul_f32 v[24:25], v[26:27], v[22:23] op_sel_hi:[0,1]
	s_nop 1
	v_add_f32_dpp v30, v30, v30 row_half_mirror row_mask:0xf bank_mask:0xf bound_ctrl:1
	v_add_f32_dpp v31, v31, v31 row_half_mirror row_mask:0xf bank_mask:0xf bound_ctrl:1
	v_pk_fma_f32 v[24:25], v[6:7], v[54:55], v[24:25] op_sel_hi:[0,1,1] neg_lo:[0,0,1] neg_hi:[0,0,1]
	s_nop 1
	v_add_f32_dpp v30, v30, v30 row_mirror row_mask:0xf bank_mask:0xf bound_ctrl:1
	v_add_f32_dpp v31, v31, v31 row_mirror row_mask:0xf bank_mask:0xf bound_ctrl:1
	s_waitcnt lgkmcnt(0)
	v_pk_fma_f32 v[54:55], v[18:19], v[64:65], v[24:25] op_sel_hi:[0,1,1]
	v_cvt_pk_bf16_f32 v17, v30, v31
	v_pk_mul_f32 v[24:25], v[26:27], v[22:23] op_sel:[1,0]
	ds_write_b32 v14, v17 offset:128
	v_pk_fma_f32 v[6:7], v[6:7], v[50:51], v[24:25] op_sel:[1,0,0] neg_lo:[0,0,1] neg_hi:[0,0,1]
	ds_read_b128 v[30:33], v15 offset:4608
	ds_read_b128 v[34:37], v15 offset:4864
	ds_read_b128 v[38:41], v15 offset:5120
	ds_read_b128 v[42:45], v15 offset:5376
	ds_read_b128 v[46:49], v15 offset:5632
	ds_read_b64 v[58:59], v16 offset:5888
	v_pk_fma_f32 v[50:51], v[18:19], v[64:65], v[6:7] op_sel:[1,0,0]
	v_pk_mul_f32 v[6:7], v[28:29], v[22:23] op_sel_hi:[0,1]
	v_pk_fma_f32 v[6:7], v[8:9], v[56:57], v[6:7] op_sel_hi:[0,1,1] neg_lo:[0,0,1] neg_hi:[0,0,1]
	v_mov_b32_e32 v8, v29
	v_pk_fma_f32 v[56:57], v[20:21], v[64:65], v[6:7] op_sel_hi:[0,1,1]
	v_mov_b32_e32 v6, v9
	v_pk_mul_f32 v[8:9], v[8:9], v[22:23] op_sel_hi:[0,1]
	v_pk_fma_f32 v[6:7], v[6:7], v[52:53], v[8:9] op_sel_hi:[0,1,1] neg_lo:[0,0,1] neg_hi:[0,0,1]
	v_mov_b32_e32 v8, v21
	s_waitcnt lgkmcnt(2)
	v_pk_mul_f32 v[62:63], v[42:43], v[50:51] op_sel:[1,0]
	v_pk_fma_f32 v[52:53], v[8:9], v[64:65], v[6:7] op_sel_hi:[0,1,1]
	v_pk_mul_f32 v[6:7], v[2:3], v[50:51] op_sel:[1,0]
	v_pk_fma_f32 v[42:43], v[42:43], v[54:55], v[62:63] op_sel_hi:[0,1,1]
	v_mov_b32_e32 v62, v45
	v_pk_fma_f32 v[2:3], v[2:3], v[54:55], v[6:7] op_sel_hi:[0,1,1]
	v_mov_b32_e32 v6, v5
	v_pk_mul_f32 v[62:63], v[62:63], v[52:53] op_sel_hi:[0,1]
	v_pk_mul_f32 v[6:7], v[6:7], v[52:53] op_sel_hi:[0,1]
	v_pk_fma_f32 v[44:45], v[44:45], v[56:57], v[62:63] op_sel_hi:[0,1,1]
	v_pk_fma_f32 v[4:5], v[4:5], v[56:57], v[6:7] op_sel_hi:[0,1,1]
	v_pk_add_f32 v[42:43], v[42:43], v[44:45]
	v_pk_add_f32 v[2:3], v[2:3], v[4:5]
	s_nop 1
	v_add_f32_dpp v42, v42, v42 quad_perm:[1,0,3,2] row_mask:0xf bank_mask:0xf bound_ctrl:1
	v_add_f32_dpp v43, v43, v43 quad_perm:[1,0,3,2] row_mask:0xf bank_mask:0xf bound_ctrl:1
	s_nop 1
	v_add_f32_dpp v2, v2, v2 quad_perm:[1,0,3,2] row_mask:0xf bank_mask:0xf bound_ctrl:1
	v_add_f32_dpp v3, v3, v3 quad_perm:[1,0,3,2] row_mask:0xf bank_mask:0xf bound_ctrl:1
	s_nop 1
	v_add_f32_dpp v42, v42, v42 quad_perm:[2,3,0,1] row_mask:0xf bank_mask:0xf bound_ctrl:1
	v_add_f32_dpp v43, v43, v43 quad_perm:[2,3,0,1] row_mask:0xf bank_mask:0xf bound_ctrl:1
	s_nop 1
	v_add_f32_dpp v2, v2, v2 quad_perm:[2,3,0,1] row_mask:0xf bank_mask:0xf bound_ctrl:1
	v_add_f32_dpp v3, v3, v3 quad_perm:[2,3,0,1] row_mask:0xf bank_mask:0xf bound_ctrl:1
	s_nop 1
	v_add_f32_dpp v42, v42, v42 row_half_mirror row_mask:0xf bank_mask:0xf bound_ctrl:1
	v_add_f32_dpp v43, v43, v43 row_half_mirror row_mask:0xf bank_mask:0xf bound_ctrl:1
	s_nop 1
	v_add_f32_dpp v2, v2, v2 row_half_mirror row_mask:0xf bank_mask:0xf bound_ctrl:1
	v_add_f32_dpp v3, v3, v3 row_half_mirror row_mask:0xf bank_mask:0xf bound_ctrl:1
	s_nop 1
	v_add_f32_dpp v42, v42, v42 row_mirror row_mask:0xf bank_mask:0xf bound_ctrl:1
	v_add_f32_dpp v43, v43, v43 row_mirror row_mask:0xf bank_mask:0xf bound_ctrl:1
	s_waitcnt lgkmcnt(1)
	v_pk_mul_f32 v[44:45], v[46:47], v[42:43] op_sel_hi:[0,1]
	s_nop 1
	v_add_f32_dpp v2, v2, v2 row_mirror row_mask:0xf bank_mask:0xf bound_ctrl:1
	v_add_f32_dpp v3, v3, v3 row_mirror row_mask:0xf bank_mask:0xf bound_ctrl:1
	v_pk_fma_f32 v[44:45], v[34:35], v[54:55], v[44:45] op_sel_hi:[0,1,1] neg_lo:[0,0,1] neg_hi:[0,0,1]
	v_cvt_pk_bf16_f32 v2, v2, v3
	s_waitcnt lgkmcnt(0)
; #define LAS __attribute__((address_space(3)))
; DI unsigned pk2(float a, float b) { f32x2 v = {a, b}; bf2_t r = __builtin_convertvector(v, bf2_t); return __builtin_bit_cast(unsigned, r); }
; #define DPP_ADD2(a, b, ctrl) asm("s_nop 1\n\tv_add_f32_dpp %0, %0, %0 " ctrl " row_mask:0xf bank_mask:0xf bound_ctrl:1\n\tv_add_f32_dpp %1, %1, %1 " ctrl " row_mask:0xf bank_mask:0xf bound_ctrl:1" : "+v"(a), "+v"(b))
; DI f32x2 red16p(f32x2 x) { float a = x.x, b = x.y; red16x2(a, b); return (f32x2){a, b}; }
; DI void red16x2(float& a, float& b) { DPP_ADD2(a, b, "quad_perm:[1,0,3,2]"); DPP_ADD2(a, b, "quad_perm:[2,3,0,1]"); DPP_ADD2(a, b, "row_half_mirror"); DPP_ADD2(a, b, "row_mirror"); }
; DI void scan_bh2(const Args& a, int l, int bh, int halfsel, LAS unsigned char* lds) {
;     ...
;             for (int st = 0; st < T; ++st) {
;                 f32x4 nr4, nd4, nk4, nkk4, nb4; f32x2 nv2;
;                 if (st < T - 1) {
;                     const LAS float* o = cur + (st + 1) * 384;
;                     nr4 = *(const LAS f32x4*)(o + kq * 4); nd4 = *(const LAS f32x4*)(o + 64 + kq * 4); nk4 = *(const LAS f32x4*)(o + 128 + kq * 4);
;                     nkk4 = *(const LAS f32x4*)(o + 192 + kq * 4); nb4 = *(const LAS f32x4*)(o + 256 + kq * 4); nv2 = *(const LAS f32x2*)(o + 320 + row0);
;                 }
;                 f32x2 sa = S[0] * kk4[0]; sa += S[1] * kk4[1]; f32x2 sb = S[2] * kk4[2]; sb += S[3] * kk4[3]; sa += sb;
;                 sa = red16p(sa); sa = -sa;
; #pragma unroll
;                 for (int j = 0; j < 4; ++j) S[j] = S[j] * d4[j] + sa * b4[j] + v2 * k4[j];
;                 f32x2 y = S[0] * r4[0]; y += S[1] * r4[1]; f32x2 yc = S[2] * r4[2]; yc += S[3] * r4[3]; y += yc;
;                 y = red16p(y);
;                 *(LAS unsigned*)(yb + st * 128 + row0 * 2) = pk2(y.x, y.y);
;                 if (st < T - 1) { r4 = nr4; d4 = nd4; k4 = nk4; kk4 = nkk4; b4 = nb4; v2 = nv2; }
;             }
	v_pk_fma_f32 v[54:55], v[38:39], v[58:59], v[44:45] op_sel_hi:[0,1,1]
	v_pk_mul_f32 v[44:45], v[46:47], v[42:43] op_sel:[1,0]
	ds_write_b32 v14, v2 offset:256
	v_pk_fma_f32 v[34:35], v[34:35], v[50:51], v[44:45] op_sel:[1,0,0] neg_lo:[0,0,1] neg_hi:[0,0,1]
	ds_read_b128 v[2:5], v15 offset:6144
	ds_read_b128 v[6:9], v15 offset:6400
	ds_read_b128 v[18:21], v15 offset:6656
	ds_read_b128 v[22:25], v15 offset:6912
	ds_read_b128 v[26:29], v15 offset:7168
	ds_read_b64 v[60:61], v16 offset:7424
	v_pk_fma_f32 v[50:51], v[38:39], v[58:59], v[34:35] op_sel:[1,0,0]
	v_pk_mul_f32 v[34:35], v[48:49], v[42:43] op_sel_hi:[0,1]
	v_pk_fma_f32 v[34:35], v[36:37], v[56:57], v[34:35] op_sel_hi:[0,1,1] neg_lo:[0,0,1] neg_hi:[0,0,1]
	v_mov_b32_e32 v36, v49
	v_pk_fma_f32 v[56:57], v[40:41], v[58:59], v[34:35] op_sel_hi:[0,1,1]
	v_mov_b32_e32 v34, v37
	v_pk_mul_f32 v[36:37], v[36:37], v[42:43] op_sel_hi:[0,1]
	v_pk_fma_f32 v[34:35], v[34:35], v[52:53], v[36:37] op_sel_hi:[0,1,1] neg_lo:[0,0,1] neg_hi:[0,0,1]
	v_mov_b32_e32 v36, v41
	s_waitcnt lgkmcnt(2)
	v_pk_mul_f32 v[62:63], v[22:23], v[50:51] op_sel:[1,0]
	v_pk_fma_f32 v[52:53], v[36:37], v[58:59], v[34:35] op_sel_hi:[0,1,1]
	v_pk_fma_f32 v[22:23], v[22:23], v[54:55], v[62:63] op_sel_hi:[0,1,1]
	v_mov_b32_e32 v62, v25
	v_pk_mul_f32 v[34:35], v[30:31], v[50:51] op_sel:[1,0]
	v_pk_mul_f32 v[62:63], v[62:63], v[52:53] op_sel_hi:[0,1]
	v_pk_fma_f32 v[30:31], v[30:31], v[54:55], v[34:35] op_sel_hi:[0,1,1]
	v_mov_b32_e32 v34, v33
	v_pk_fma_f32 v[24:25], v[24:25], v[56:57], v[62:63] op_sel_hi:[0,1,1]
	v_pk_mul_f32 v[34:35], v[34:35], v[52:53] op_sel_hi:[0,1]
	v_pk_add_f32 v[22:23], v[22:23], v[24:25]
	v_pk_fma_f32 v[32:33], v[32:33], v[56:57], v[34:35] op_sel_hi:[0,1,1]
	s_nop 1
	v_add_f32_dpp v22, v22, v22 quad_perm:[1,0,3,2] row_mask:0xf bank_mask:0xf bound_ctrl:1
	v_add_f32_dpp v23, v23, v23 quad_perm:[1,0,3,2] row_mask:0xf bank_mask:0xf bound_ctrl:1
	v_pk_add_f32 v[30:31], v[30:31], v[32:33]
	s_nop 1
	v_add_f32_dpp v22, v22, v22 quad_perm:[2,3,0,1] row_mask:0xf bank_mask:0xf bound_ctrl:1
	v_add_f32_dpp v23, v23, v23 quad_perm:[2,3,0,1] row_mask:0xf bank_mask:0xf bound_ctrl:1
	s_nop 1
	v_add_f32_dpp v30, v30, v30 quad_perm:[1,0,3,2] row_mask:0xf bank_mask:0xf bound_ctrl:1
	v_add_f32_dpp v31, v31, v31 quad_perm:[1,0,3,2] row_mask:0xf bank_mask:0xf bound_ctrl:1
	s_nop 1
	v_add_f32_dpp v22, v22, v22 row_half_mirror row_mask:0xf bank_mask:0xf bound_ctrl:1
	v_add_f32_dpp v23, v23, v23 row_half_mirror row_mask:0xf bank_mask:0xf bound_ctrl:1
	s_nop 1
	v_add_f32_dpp v30, v30, v30 quad_perm:[2,3,0,1] row_mask:0xf bank_mask:0xf bound_ctrl:1
	v_add_f32_dpp v31, v31, v31 quad_perm:[2,3,0,1] row_mask:0xf bank_mask:0xf bound_ctrl:1
	s_nop 1
	v_add_f32_dpp v22, v22, v22 row_mirror row_mask:0xf bank_mask:0xf bound_ctrl:1
	v_add_f32_dpp v23, v23, v23 row_mirror row_mask:0xf bank_mask:0xf bound_ctrl:1
	s_waitcnt lgkmcnt(1)
	v_pk_mul_f32 v[24:25], v[26:27], v[22:23] op_sel_hi:[0,1]
	s_nop 1
	v_add_f32_dpp v30, v30, v30 row_half_mirror row_mask:0xf bank_mask:0xf bound_ctrl:1
	v_add_f32_dpp v31, v31, v31 row_half_mirror row_mask:0xf bank_mask:0xf bound_ctrl:1
	v_pk_fma_f32 v[24:25], v[6:7], v[54:55], v[24:25] op_sel_hi:[0,1,1] neg_lo:[0,0,1] neg_hi:[0,0,1]
	s_nop 1
	v_add_f32_dpp v30, v30, v30 row_mirror row_mask:0xf bank_mask:0xf bound_ctrl:1
	v_add_f32_dpp v31, v31, v31 row_mirror row_mask:0xf bank_mask:0xf bound_ctrl:1
	s_waitcnt lgkmcnt(0)
	v_pk_fma_f32 v[54:55], v[18:19], v[60:61], v[24:25] op_sel_hi:[0,1,1]
	v_cvt_pk_bf16_f32 v17, v30, v31
	v_pk_mul_f32 v[24:25], v[26:27], v[22:23] op_sel:[1,0]
	ds_write_b32 v14, v17 offset:384
	v_pk_fma_f32 v[6:7], v[6:7], v[50:51], v[24:25] op_sel:[1,0,0] neg_lo:[0,0,1] neg_hi:[0,0,1]
	ds_read_b128 v[30:33], v15 offset:7680
	ds_read_b128 v[34:37], v15 offset:7936
	ds_read_b128 v[38:41], v15 offset:8192
	ds_read_b128 v[42:45], v15 offset:8448
	ds_read_b128 v[46:49], v15 offset:8704
	ds_read_b64 v[58:59], v16 offset:8960
	v_pk_fma_f32 v[50:51], v[18:19], v[60:61], v[6:7] op_sel:[1,0,0]
	v_pk_mul_f32 v[6:7], v[28:29], v[22:23] op_sel_hi:[0,1]
	v_pk_fma_f32 v[6:7], v[8:9], v[56:57], v[6:7] op_sel_hi:[0,1,1] neg_lo:[0,0,1] neg_hi:[0,0,1]
	v_mov_b32_e32 v8, v29
	v_pk_fma_f32 v[56:57], v[20:21], v[60:61], v[6:7] op_sel_hi:[0,1,1]
	v_mov_b32_e32 v6, v9
	v_pk_mul_f32 v[8:9], v[8:9], v[22:23] op_sel_hi:[0,1]
	v_pk_fma_f32 v[6:7], v[6:7], v[52:53], v[8:9] op_sel_hi:[0,1,1] neg_lo:[0,0,1] neg_hi:[0,0,1]
	v_mov_b32_e32 v8, v21
	s_waitcnt lgkmcnt(2)
	v_pk_mul_f32 v[62:63], v[42:43], v[50:51] op_sel:[1,0]
	v_pk_fma_f32 v[52:53], v[8:9], v[60:61], v[6:7] op_sel_hi:[0,1,1]
	v_pk_mul_f32 v[6:7], v[2:3], v[50:51] op_sel:[1,0]
	v_pk_fma_f32 v[42:43], v[42:43], v[54:55], v[62:63] op_sel_hi:[0,1,1]
	v_mov_b32_e32 v62, v45
	v_pk_fma_f32 v[2:3], v[2:3], v[54:55], v[6:7] op_sel_hi:[0,1,1]
	v_mov_b32_e32 v6, v5
	v_pk_mul_f32 v[62:63], v[62:63], v[52:53] op_sel_hi:[0,1]
	v_pk_mul_f32 v[6:7], v[6:7], v[52:53] op_sel_hi:[0,1]
	v_pk_fma_f32 v[44:45], v[44:45], v[56:57], v[62:63] op_sel_hi:[0,1,1]
	v_pk_fma_f32 v[4:5], v[4:5], v[56:57], v[6:7] op_sel_hi:[0,1,1]
	v_pk_add_f32 v[42:43], v[42:43], v[44:45]
	v_pk_add_f32 v[2:3], v[2:3], v[4:5]
	s_nop 1
	v_add_f32_dpp v42, v42, v42 quad_perm:[1,0,3,2] row_mask:0xf bank_mask:0xf bound_ctrl:1
	v_add_f32_dpp v43, v43, v43 quad_perm:[1,0,3,2] row_mask:0xf bank_mask:0xf bound_ctrl:1
	s_nop 1
	v_add_f32_dpp v2, v2, v2 quad_perm:[1,0,3,2] row_mask:0xf bank_mask:0xf bound_ctrl:1
	v_add_f32_dpp v3, v3, v3 quad_perm:[1,0,3,2] row_mask:0xf bank_mask:0xf bound_ctrl:1
	s_nop 1
	v_add_f32_dpp v42, v42, v42 quad_perm:[2,3,0,1] row_mask:0xf bank_mask:0xf bound_ctrl:1
	v_add_f32_dpp v43, v43, v43 quad_perm:[2,3,0,1] row_mask:0xf bank_mask:0xf bound_ctrl:1
	s_nop 1
	v_add_f32_dpp v2, v2, v2 quad_perm:[2,3,0,1] row_mask:0xf bank_mask:0xf bound_ctrl:1
	v_add_f32_dpp v3, v3, v3 quad_perm:[2,3,0,1] row_mask:0xf bank_mask:0xf bound_ctrl:1
	s_nop 1
	v_add_f32_dpp v42, v42, v42 row_half_mirror row_mask:0xf bank_mask:0xf bound_ctrl:1
	v_add_f32_dpp v43, v43, v43 row_half_mirror row_mask:0xf bank_mask:0xf bound_ctrl:1
	s_nop 1
	v_add_f32_dpp v2, v2, v2 row_half_mirror row_mask:0xf bank_mask:0xf bound_ctrl:1
	v_add_f32_dpp v3, v3, v3 row_half_mirror row_mask:0xf bank_mask:0xf bound_ctrl:1
	s_nop 1
	v_add_f32_dpp v42, v42, v42 row_mirror row_mask:0xf bank_mask:0xf bound_ctrl:1
	v_add_f32_dpp v43, v43, v43 row_mirror row_mask:0xf bank_mask:0xf bound_ctrl:1
	s_waitcnt lgkmcnt(1)
; #define LAS __attribute__((address_space(3)))
; DI unsigned pk2(float a, float b) { f32x2 v = {a, b}; bf2_t r = __builtin_convertvector(v, bf2_t); return __builtin_bit_cast(unsigned, r); }
; #define DPP_ADD2(a, b, ctrl) asm("s_nop 1\n\tv_add_f32_dpp %0, %0, %0 " ctrl " row_mask:0xf bank_mask:0xf bound_ctrl:1\n\tv_add_f32_dpp %1, %1, %1 " ctrl " row_mask:0xf bank_mask:0xf bound_ctrl:1" : "+v"(a), "+v"(b))
; DI f32x2 red16p(f32x2 x) { float a = x.x, b = x.y; red16x2(a, b); return (f32x2){a, b}; }
; DI void red16x2(float& a, float& b) { DPP_ADD2(a, b, "quad_perm:[1,0,3,2]"); DPP_ADD2(a, b, "quad_perm:[2,3,0,1]"); DPP_ADD2(a, b, "row_half_mirror"); DPP_ADD2(a, b, "row_mirror"); }
; DI void scan_bh2(const Args& a, int l, int bh, int halfsel, LAS unsigned char* lds) {
;     ...
;             for (int st = 0; st < T; ++st) {
;                 f32x4 nr4, nd4, nk4, nkk4, nb4; f32x2 nv2;
;                 if (st < T - 1) {
;                     const LAS float* o = cur + (st + 1) * 384;
;                     nr4 = *(const LAS f32x4*)(o + kq * 4); nd4 = *(const LAS f32x4*)(o + 64 + kq * 4); nk4 = *(const LAS f32x4*)(o + 128 + kq * 4);
;                     nkk4 = *(const LAS f32x4*)(o + 192 + kq * 4); nb4 = *(const LAS f32x4*)(o + 256 + kq * 4); nv2 = *(const LAS f32x2*)(o + 320 + row0);
;                 }
;                 f32x2 sa = S[0] * kk4[0]; sa += S[1] * kk4[1]; f32x2 sb = S[2] * kk4[2]; sb += S[3] * kk4[3]; sa += sb;
;                 sa = red16p(sa); sa = -sa;
; #pragma unroll
;                 for (int j = 0; j < 4; ++j) S[j] = S[j] * d4[j] + sa * b4[j] + v2 * k4[j];
;                 f32x2 y = S[0] * r4[0]; y += S[1] * r4[1]; f32x2 yc = S[2] * r4[2]; yc += S[3] * r4[3]; y += yc;
;                 y = red16p(y);
;                 *(LAS unsigned*)(yb + st * 128 + row0 * 2) = pk2(y.x, y.y);
;                 if (st < T - 1) { r4 = nr4; d4 = nd4; k4 = nk4; kk4 = nkk4; b4 = nb4; v2 = nv2; }
;             }
	v_pk_mul_f32 v[44:45], v[46:47], v[42:43] op_sel_hi:[0,1]
	s_nop 1
	v_add_f32_dpp v2, v2, v2 row_mirror row_mask:0xf bank_mask:0xf bound_ctrl:1
	v_add_f32_dpp v3, v3, v3 row_mirror row_mask:0xf bank_mask:0xf bound_ctrl:1
	v_pk_fma_f32 v[44:45], v[34:35], v[54:55], v[44:45] op_sel_hi:[0,1,1] neg_lo:[0,0,1] neg_hi:[0,0,1]
	v_cvt_pk_bf16_f32 v2, v2, v3
	s_waitcnt lgkmcnt(0)
	v_pk_fma_f32 v[54:55], v[38:39], v[58:59], v[44:45] op_sel_hi:[0,1,1]
	v_pk_mul_f32 v[44:45], v[46:47], v[42:43] op_sel:[1,0]
	ds_write_b32 v14, v2 offset:512
	v_pk_fma_f32 v[34:35], v[34:35], v[50:51], v[44:45] op_sel:[1,0,0] neg_lo:[0,0,1] neg_hi:[0,0,1]
	ds_read_b128 v[2:5], v15 offset:9216
	ds_read_b128 v[6:9], v15 offset:9472
	ds_read_b128 v[18:21], v15 offset:9728
	ds_read_b128 v[22:25], v15 offset:9984
	ds_read_b128 v[26:29], v15 offset:10240
	ds_read_b64 v[60:61], v16 offset:10496
	v_pk_fma_f32 v[50:51], v[38:39], v[58:59], v[34:35] op_sel:[1,0,0]
	v_pk_mul_f32 v[34:35], v[48:49], v[42:43] op_sel_hi:[0,1]
	v_pk_fma_f32 v[34:35], v[36:37], v[56:57], v[34:35] op_sel_hi:[0,1,1] neg_lo:[0,0,1] neg_hi:[0,0,1]
	v_mov_b32_e32 v36, v49
	v_pk_fma_f32 v[56:57], v[40:41], v[58:59], v[34:35] op_sel_hi:[0,1,1]
	v_mov_b32_e32 v34, v37
	v_pk_mul_f32 v[36:37], v[36:37], v[42:43] op_sel_hi:[0,1]
	v_pk_fma_f32 v[34:35], v[34:35], v[52:53], v[36:37] op_sel_hi:[0,1,1] neg_lo:[0,0,1] neg_hi:[0,0,1]
	v_mov_b32_e32 v36, v41
	s_waitcnt lgkmcnt(2)
	v_pk_mul_f32 v[62:63], v[22:23], v[50:51] op_sel:[1,0]
	v_pk_fma_f32 v[52:53], v[36:37], v[58:59], v[34:35] op_sel_hi:[0,1,1]
	v_pk_fma_f32 v[22:23], v[22:23], v[54:55], v[62:63] op_sel_hi:[0,1,1]
	v_mov_b32_e32 v62, v25
	v_pk_mul_f32 v[34:35], v[30:31], v[50:51] op_sel:[1,0]
	v_pk_mul_f32 v[62:63], v[62:63], v[52:53] op_sel_hi:[0,1]
	v_pk_fma_f32 v[30:31], v[30:31], v[54:55], v[34:35] op_sel_hi:[0,1,1]
	v_mov_b32_e32 v34, v33
	v_pk_fma_f32 v[24:25], v[24:25], v[56:57], v[62:63] op_sel_hi:[0,1,1]
	v_pk_mul_f32 v[34:35], v[34:35], v[52:53] op_sel_hi:[0,1]
	v_pk_add_f32 v[22:23], v[22:23], v[24:25]
	v_pk_fma_f32 v[32:33], v[32:33], v[56:57], v[34:35] op_sel_hi:[0,1,1]
	s_nop 1
	v_add_f32_dpp v22, v22, v22 quad_perm:[1,0,3,2] row_mask:0xf bank_mask:0xf bound_ctrl:1
	v_add_f32_dpp v23, v23, v23 quad_perm:[1,0,3,2] row_mask:0xf bank_mask:0xf bound_ctrl:1
	v_pk_add_f32 v[30:31], v[30:31], v[32:33]
	s_nop 1
	v_add_f32_dpp v22, v22, v22 quad_perm:[2,3,0,1] row_mask:0xf bank_mask:0xf bound_ctrl:1
	v_add_f32_dpp v23, v23, v23 quad_perm:[2,3,0,1] row_mask:0xf bank_mask:0xf bound_ctrl:1
	s_nop 1
	v_add_f32_dpp v30, v30, v30 quad_perm:[1,0,3,2] row_mask:0xf bank_mask:0xf bound_ctrl:1
	v_add_f32_dpp v31, v31, v31 quad_perm:[1,0,3,2] row_mask:0xf bank_mask:0xf bound_ctrl:1
	s_nop 1
	v_add_f32_dpp v22, v22, v22 row_half_mirror row_mask:0xf bank_mask:0xf bound_ctrl:1
	v_add_f32_dpp v23, v23, v23 row_half_mirror row_mask:0xf bank_mask:0xf bound_ctrl:1
	s_nop 1
	v_add_f32_dpp v30, v30, v30 quad_perm:[2,3,0,1] row_mask:0xf bank_mask:0xf bound_ctrl:1
	v_add_f32_dpp v31, v31, v31 quad_perm:[2,3,0,1] row_mask:0xf bank_mask:0xf bound_ctrl:1
	s_nop 1
	v_add_f32_dpp v22, v22, v22 row_mirror row_mask:0xf bank_mask:0xf bound_ctrl:1
	v_add_f32_dpp v23, v23, v23 row_mirror row_mask:0xf bank_mask:0xf bound_ctrl:1
	s_waitcnt lgkmcnt(1)
	v_pk_mul_f32 v[24:25], v[26:27], v[22:23] op_sel_hi:[0,1]
	s_nop 1
	v_add_f32_dpp v30, v30, v30 row_half_mirror row_mask:0xf bank_mask:0xf bound_ctrl:1
	v_add_f32_dpp v31, v31, v31 row_half_mirror row_mask:0xf bank_mask:0xf bound_ctrl:1
	v_pk_fma_f32 v[24:25], v[6:7], v[54:55], v[24:25] op_sel_hi:[0,1,1] neg_lo:[0,0,1] neg_hi:[0,0,1]
	s_nop 1
	v_add_f32_dpp v30, v30, v30 row_mirror row_mask:0xf bank_mask:0xf bound_ctrl:1
	v_add_f32_dpp v31, v31, v31 row_mirror row_mask:0xf bank_mask:0xf bound_ctrl:1
	s_waitcnt lgkmcnt(0)
	v_pk_fma_f32 v[54:55], v[18:19], v[60:61], v[24:25] op_sel_hi:[0,1,1]
	v_cvt_pk_bf16_f32 v17, v30, v31
	v_pk_mul_f32 v[24:25], v[26:27], v[22:23] op_sel:[1,0]
	ds_write_b32 v14, v17 offset:640
	v_pk_fma_f32 v[6:7], v[6:7], v[50:51], v[24:25] op_sel:[1,0,0] neg_lo:[0,0,1] neg_hi:[0,0,1]
	ds_read_b128 v[30:33], v15 offset:10752
	ds_read_b128 v[34:37], v15 offset:11008
	ds_read_b128 v[38:41], v15 offset:11264
	ds_read_b128 v[42:45], v15 offset:11520
	ds_read_b128 v[46:49], v15 offset:11776
	ds_read_b64 v[58:59], v16 offset:12032
	v_pk_fma_f32 v[50:51], v[18:19], v[60:61], v[6:7] op_sel:[1,0,0]
	v_pk_mul_f32 v[6:7], v[28:29], v[22:23] op_sel_hi:[0,1]
	v_pk_fma_f32 v[6:7], v[8:9], v[56:57], v[6:7] op_sel_hi:[0,1,1] neg_lo:[0,0,1] neg_hi:[0,0,1]
	v_mov_b32_e32 v8, v29
	v_pk_fma_f32 v[56:57], v[20:21], v[60:61], v[6:7] op_sel_hi:[0,1,1]
	v_mov_b32_e32 v6, v9
	v_pk_mul_f32 v[8:9], v[8:9], v[22:23] op_sel_hi:[0,1]
	v_pk_fma_f32 v[6:7], v[6:7], v[52:53], v[8:9] op_sel_hi:[0,1,1] neg_lo:[0,0,1] neg_hi:[0,0,1]
	v_mov_b32_e32 v8, v21
	s_waitcnt lgkmcnt(2)
; #define LAS __attribute__((address_space(3)))
; DI unsigned pk2(float a, float b) { f32x2 v = {a, b}; bf2_t r = __builtin_convertvector(v, bf2_t); return __builtin_bit_cast(unsigned, r); }
; #define DPP_ADD2(a, b, ctrl) asm("s_nop 1\n\tv_add_f32_dpp %0, %0, %0 " ctrl " row_mask:0xf bank_mask:0xf bound_ctrl:1\n\tv_add_f32_dpp %1, %1, %1 " ctrl " row_mask:0xf bank_mask:0xf bound_ctrl:1" : "+v"(a), "+v"(b))
; DI f32x2 red16p(f32x2 x) { float a = x.x, b = x.y; red16x2(a, b); return (f32x2){a, b}; }
; DI void red16x2(float& a, float& b) { DPP_ADD2(a, b, "quad_perm:[1,0,3,2]"); DPP_ADD2(a, b, "quad_perm:[2,3,0,1]"); DPP_ADD2(a, b, "row_half_mirror"); DPP_ADD2(a, b, "row_mirror"); }
; DI void scan_bh2(const Args& a, int l, int bh, int halfsel, LAS unsigned char* lds) {
;     ...
;             for (int st = 0; st < T; ++st) {
;                 f32x4 nr4, nd4, nk4, nkk4, nb4; f32x2 nv2;
;                 if (st < T - 1) {
;                     const LAS float* o = cur + (st + 1) * 384;
;                     nr4 = *(const LAS f32x4*)(o + kq * 4); nd4 = *(const LAS f32x4*)(o + 64 + kq * 4); nk4 = *(const LAS f32x4*)(o + 128 + kq * 4);
;                     nkk4 = *(const LAS f32x4*)(o + 192 + kq * 4); nb4 = *(const LAS f32x4*)(o + 256 + kq * 4); nv2 = *(const LAS f32x2*)(o + 320 + row0);
;                 }
;                 f32x2 sa = S[0] * kk4[0]; sa += S[1] * kk4[1]; f32x2 sb = S[2] * kk4[2]; sb += S[3] * kk4[3]; sa += sb;
;                 sa = red16p(sa); sa = -sa;
; #pragma unroll
;                 for (int j = 0; j < 4; ++j) S[j] = S[j] * d4[j] + sa * b4[j] + v2 * k4[j];
;                 f32x2 y = S[0] * r4[0]; y += S[1] * r4[1]; f32x2 yc = S[2] * r4[2]; yc += S[3] * r4[3]; y += yc;
;                 y = red16p(y);
;                 *(LAS unsigned*)(yb + st * 128 + row0 * 2) = pk2(y.x, y.y);
;                 if (st < T - 1) { r4 = nr4; d4 = nd4; k4 = nk4; kk4 = nkk4; b4 = nb4; v2 = nv2; }
;             }
	v_pk_mul_f32 v[62:63], v[42:43], v[50:51] op_sel:[1,0]
	v_pk_fma_f32 v[52:53], v[8:9], v[60:61], v[6:7] op_sel_hi:[0,1,1]
	v_pk_mul_f32 v[6:7], v[2:3], v[50:51] op_sel:[1,0]
	v_pk_fma_f32 v[42:43], v[42:43], v[54:55], v[62:63] op_sel_hi:[0,1,1]
	v_mov_b32_e32 v62, v45
	v_pk_fma_f32 v[2:3], v[2:3], v[54:55], v[6:7] op_sel_hi:[0,1,1]
	v_mov_b32_e32 v6, v5
	v_pk_mul_f32 v[62:63], v[62:63], v[52:53] op_sel_hi:[0,1]
	v_pk_mul_f32 v[6:7], v[6:7], v[52:53] op_sel_hi:[0,1]
	v_pk_fma_f32 v[44:45], v[44:45], v[56:57], v[62:63] op_sel_hi:[0,1,1]
	v_pk_fma_f32 v[4:5], v[4:5], v[56:57], v[6:7] op_sel_hi:[0,1,1]
	v_pk_add_f32 v[42:43], v[42:43], v[44:45]
	v_pk_add_f32 v[2:3], v[2:3], v[4:5]
	s_nop 1
	v_add_f32_dpp v42, v42, v42 quad_perm:[1,0,3,2] row_mask:0xf bank_mask:0xf bound_ctrl:1
	v_add_f32_dpp v43, v43, v43 quad_perm:[1,0,3,2] row_mask:0xf bank_mask:0xf bound_ctrl:1
	s_nop 1
	v_add_f32_dpp v2, v2, v2 quad_perm:[1,0,3,2] row_mask:0xf bank_mask:0xf bound_ctrl:1
	v_add_f32_dpp v3, v3, v3 quad_perm:[1,0,3,2] row_mask:0xf bank_mask:0xf bound_ctrl:1
	s_nop 1
	v_add_f32_dpp v42, v42, v42 quad_perm:[2,3,0,1] row_mask:0xf bank_mask:0xf bound_ctrl:1
	v_add_f32_dpp v43, v43, v43 quad_perm:[2,3,0,1] row_mask:0xf bank_mask:0xf bound_ctrl:1
	s_nop 1
	v_add_f32_dpp v2, v2, v2 quad_perm:[2,3,0,1] row_mask:0xf bank_mask:0xf bound_ctrl:1
	v_add_f32_dpp v3, v3, v3 quad_perm:[2,3,0,1] row_mask:0xf bank_mask:0xf bound_ctrl:1
	s_nop 1
	v_add_f32_dpp v42, v42, v42 row_half_mirror row_mask:0xf bank_mask:0xf bound_ctrl:1
	v_add_f32_dpp v43, v43, v43 row_half_mirror row_mask:0xf bank_mask:0xf bound_ctrl:1
	s_nop 1
	v_add_f32_dpp v2, v2, v2 row_half_mirror row_mask:0xf bank_mask:0xf bound_ctrl:1
	v_add_f32_dpp v3, v3, v3 row_half_mirror row_mask:0xf bank_mask:0xf bound_ctrl:1
	s_nop 1
	v_add_f32_dpp v42, v42, v42 row_mirror row_mask:0xf bank_mask:0xf bound_ctrl:1
	v_add_f32_dpp v43, v43, v43 row_mirror row_mask:0xf bank_mask:0xf bound_ctrl:1
	s_waitcnt lgkmcnt(1)
	v_pk_mul_f32 v[44:45], v[46:47], v[42:43] op_sel_hi:[0,1]
	s_nop 1
	v_add_f32_dpp v2, v2, v2 row_mirror row_mask:0xf bank_mask:0xf bound_ctrl:1
	v_add_f32_dpp v3, v3, v3 row_mirror row_mask:0xf bank_mask:0xf bound_ctrl:1
	v_pk_fma_f32 v[44:45], v[34:35], v[54:55], v[44:45] op_sel_hi:[0,1,1] neg_lo:[0,0,1] neg_hi:[0,0,1]
	v_cvt_pk_bf16_f32 v2, v2, v3
	s_waitcnt lgkmcnt(0)
	v_pk_fma_f32 v[54:55], v[38:39], v[58:59], v[44:45] op_sel_hi:[0,1,1]
	v_pk_mul_f32 v[44:45], v[46:47], v[42:43] op_sel:[1,0]
	ds_write_b32 v14, v2 offset:768
	v_pk_fma_f32 v[34:35], v[34:35], v[50:51], v[44:45] op_sel:[1,0,0] neg_lo:[0,0,1] neg_hi:[0,0,1]
	ds_read_b128 v[2:5], v15 offset:12288
	ds_read_b128 v[6:9], v15 offset:12544
	ds_read_b128 v[18:21], v15 offset:12800
	ds_read_b128 v[22:25], v15 offset:13056
	ds_read_b128 v[26:29], v15 offset:13312
	ds_read_b64 v[60:61], v16 offset:13568
	v_pk_fma_f32 v[50:51], v[38:39], v[58:59], v[34:35] op_sel:[1,0,0]
	v_pk_mul_f32 v[34:35], v[48:49], v[42:43] op_sel_hi:[0,1]
	v_pk_fma_f32 v[34:35], v[36:37], v[56:57], v[34:35] op_sel_hi:[0,1,1] neg_lo:[0,0,1] neg_hi:[0,0,1]
	v_mov_b32_e32 v36, v49
	v_pk_fma_f32 v[56:57], v[40:41], v[58:59], v[34:35] op_sel_hi:[0,1,1]
	v_mov_b32_e32 v34, v37
	v_pk_mul_f32 v[36:37], v[36:37], v[42:43] op_sel_hi:[0,1]
	v_pk_fma_f32 v[34:35], v[34:35], v[52:53], v[36:37] op_sel_hi:[0,1,1] neg_lo:[0,0,1] neg_hi:[0,0,1]
	v_mov_b32_e32 v36, v41
	s_waitcnt lgkmcnt(2)
	v_pk_mul_f32 v[62:63], v[22:23], v[50:51] op_sel:[1,0]
	v_pk_fma_f32 v[52:53], v[36:37], v[58:59], v[34:35] op_sel_hi:[0,1,1]
	v_pk_fma_f32 v[22:23], v[22:23], v[54:55], v[62:63] op_sel_hi:[0,1,1]
	v_mov_b32_e32 v62, v25
	v_pk_mul_f32 v[34:35], v[30:31], v[50:51] op_sel:[1,0]
	v_pk_mul_f32 v[62:63], v[62:63], v[52:53] op_sel_hi:[0,1]
	v_pk_fma_f32 v[30:31], v[30:31], v[54:55], v[34:35] op_sel_hi:[0,1,1]
	v_mov_b32_e32 v34, v33
	v_pk_fma_f32 v[24:25], v[24:25], v[56:57], v[62:63] op_sel_hi:[0,1,1]
	v_pk_mul_f32 v[34:35], v[34:35], v[52:53] op_sel_hi:[0,1]
	v_pk_add_f32 v[22:23], v[22:23], v[24:25]
	v_pk_fma_f32 v[32:33], v[32:33], v[56:57], v[34:35] op_sel_hi:[0,1,1]
	s_nop 1
	v_add_f32_dpp v22, v22, v22 quad_perm:[1,0,3,2] row_mask:0xf bank_mask:0xf bound_ctrl:1
	v_add_f32_dpp v23, v23, v23 quad_perm:[1,0,3,2] row_mask:0xf bank_mask:0xf bound_ctrl:1
	v_pk_add_f32 v[30:31], v[30:31], v[32:33]
	s_nop 1
	v_add_f32_dpp v22, v22, v22 quad_perm:[2,3,0,1] row_mask:0xf bank_mask:0xf bound_ctrl:1
	v_add_f32_dpp v23, v23, v23 quad_perm:[2,3,0,1] row_mask:0xf bank_mask:0xf bound_ctrl:1
	s_nop 1
	v_add_f32_dpp v30, v30, v30 quad_perm:[1,0,3,2] row_mask:0xf bank_mask:0xf bound_ctrl:1
	v_add_f32_dpp v31, v31, v31 quad_perm:[1,0,3,2] row_mask:0xf bank_mask:0xf bound_ctrl:1
	s_nop 1
	v_add_f32_dpp v22, v22, v22 row_half_mirror row_mask:0xf bank_mask:0xf bound_ctrl:1
	v_add_f32_dpp v23, v23, v23 row_half_mirror row_mask:0xf bank_mask:0xf bound_ctrl:1
	s_nop 1
	v_add_f32_dpp v30, v30, v30 quad_perm:[2,3,0,1] row_mask:0xf bank_mask:0xf bound_ctrl:1
	v_add_f32_dpp v31, v31, v31 quad_perm:[2,3,0,1] row_mask:0xf bank_mask:0xf bound_ctrl:1
	s_nop 1
	v_add_f32_dpp v22, v22, v22 row_mirror row_mask:0xf bank_mask:0xf bound_ctrl:1
	v_add_f32_dpp v23, v23, v23 row_mirror row_mask:0xf bank_mask:0xf bound_ctrl:1
	s_waitcnt lgkmcnt(1)
	v_pk_mul_f32 v[24:25], v[26:27], v[22:23] op_sel_hi:[0,1]
	s_nop 1
	v_add_f32_dpp v30, v30, v30 row_half_mirror row_mask:0xf bank_mask:0xf bound_ctrl:1
	v_add_f32_dpp v31, v31, v31 row_half_mirror row_mask:0xf bank_mask:0xf bound_ctrl:1
	v_pk_fma_f32 v[24:25], v[6:7], v[54:55], v[24:25] op_sel_hi:[0,1,1] neg_lo:[0,0,1] neg_hi:[0,0,1]
	s_nop 1
	v_add_f32_dpp v30, v30, v30 row_mirror row_mask:0xf bank_mask:0xf bound_ctrl:1
	v_add_f32_dpp v31, v31, v31 row_mirror row_mask:0xf bank_mask:0xf bound_ctrl:1
	s_waitcnt lgkmcnt(0)
; #define LAS __attribute__((address_space(3)))
; DI unsigned pk2(float a, float b) { f32x2 v = {a, b}; bf2_t r = __builtin_convertvector(v, bf2_t); return __builtin_bit_cast(unsigned, r); }
; #define DPP_ADD2(a, b, ctrl) asm("s_nop 1\n\tv_add_f32_dpp %0, %0, %0 " ctrl " row_mask:0xf bank_mask:0xf bound_ctrl:1\n\tv_add_f32_dpp %1, %1, %1 " ctrl " row_mask:0xf bank_mask:0xf bound_ctrl:1" : "+v"(a), "+v"(b))
; DI f32x2 red16p(f32x2 x) { float a = x.x, b = x.y; red16x2(a, b); return (f32x2){a, b}; }
; DI void red16x2(float& a, float& b) { DPP_ADD2(a, b, "quad_perm:[1,0,3,2]"); DPP_ADD2(a, b, "quad_perm:[2,3,0,1]"); DPP_ADD2(a, b, "row_half_mirror"); DPP_ADD2(a, b, "row_mirror"); }
; DI void scan_bh2(const Args& a, int l, int bh, int halfsel, LAS unsigned char* lds) {
;     ...
;             for (int st = 0; st < T; ++st) {
;                 f32x4 nr4, nd4, nk4, nkk4, nb4; f32x2 nv2;
;                 if (st < T - 1) {
;                     const LAS float* o = cur + (st + 1) * 384;
;                     nr4 = *(const LAS f32x4*)(o + kq * 4); nd4 = *(const LAS f32x4*)(o + 64 + kq * 4); nk4 = *(const LAS f32x4*)(o + 128 + kq * 4);
;                     nkk4 = *(const LAS f32x4*)(o + 192 + kq * 4); nb4 = *(const LAS f32x4*)(o + 256 + kq * 4); nv2 = *(const LAS f32x2*)(o + 320 + row0);
;                 }
;                 f32x2 sa = S[0] * kk4[0]; sa += S[1] * kk4[1]; f32x2 sb = S[2] * kk4[2]; sb += S[3] * kk4[3]; sa += sb;
;                 sa = red16p(sa); sa = -sa;
; #pragma unroll
;                 for (int j = 0; j < 4; ++j) S[j] = S[j] * d4[j] + sa * b4[j] + v2 * k4[j];
;                 f32x2 y = S[0] * r4[0]; y += S[1] * r4[1]; f32x2 yc = S[2] * r4[2]; yc += S[3] * r4[3]; y += yc;
;                 y = red16p(y);
;                 *(LAS unsigned*)(yb + st * 128 + row0 * 2) = pk2(y.x, y.y);
;                 if (st < T - 1) { r4 = nr4; d4 = nd4; k4 = nk4; kk4 = nkk4; b4 = nb4; v2 = nv2; }
;             }
	v_pk_fma_f32 v[54:55], v[18:19], v[60:61], v[24:25] op_sel_hi:[0,1,1]
	v_cvt_pk_bf16_f32 v17, v30, v31
	v_pk_mul_f32 v[24:25], v[26:27], v[22:23] op_sel:[1,0]
	ds_write_b32 v14, v17 offset:896
	v_pk_fma_f32 v[6:7], v[6:7], v[50:51], v[24:25] op_sel:[1,0,0] neg_lo:[0,0,1] neg_hi:[0,0,1]
	ds_read_b128 v[30:33], v15 offset:13824
	ds_read_b128 v[34:37], v15 offset:14080
	ds_read_b128 v[38:41], v15 offset:14336
	ds_read_b128 v[42:45], v15 offset:14592
	ds_read_b128 v[46:49], v15 offset:14848
	ds_read_b64 v[58:59], v16 offset:15104
	v_pk_fma_f32 v[50:51], v[18:19], v[60:61], v[6:7] op_sel:[1,0,0]
	v_pk_mul_f32 v[6:7], v[28:29], v[22:23] op_sel_hi:[0,1]
	v_pk_fma_f32 v[6:7], v[8:9], v[56:57], v[6:7] op_sel_hi:[0,1,1] neg_lo:[0,0,1] neg_hi:[0,0,1]
	v_mov_b32_e32 v8, v29
	v_pk_fma_f32 v[56:57], v[20:21], v[60:61], v[6:7] op_sel_hi:[0,1,1]
	v_mov_b32_e32 v6, v9
	v_pk_mul_f32 v[8:9], v[8:9], v[22:23] op_sel_hi:[0,1]
	v_pk_fma_f32 v[6:7], v[6:7], v[52:53], v[8:9] op_sel_hi:[0,1,1] neg_lo:[0,0,1] neg_hi:[0,0,1]
	v_mov_b32_e32 v8, v21
	s_waitcnt lgkmcnt(2)
	v_pk_mul_f32 v[62:63], v[42:43], v[50:51] op_sel:[1,0]
	v_pk_fma_f32 v[52:53], v[8:9], v[60:61], v[6:7] op_sel_hi:[0,1,1]
	v_pk_mul_f32 v[6:7], v[2:3], v[50:51] op_sel:[1,0]
	v_pk_fma_f32 v[42:43], v[42:43], v[54:55], v[62:63] op_sel_hi:[0,1,1]
	v_mov_b32_e32 v62, v45
	v_pk_fma_f32 v[2:3], v[2:3], v[54:55], v[6:7] op_sel_hi:[0,1,1]
	v_mov_b32_e32 v6, v5
	v_pk_mul_f32 v[62:63], v[62:63], v[52:53] op_sel_hi:[0,1]
	v_pk_mul_f32 v[6:7], v[6:7], v[52:53] op_sel_hi:[0,1]
	v_pk_fma_f32 v[44:45], v[44:45], v[56:57], v[62:63] op_sel_hi:[0,1,1]
	v_pk_fma_f32 v[4:5], v[4:5], v[56:57], v[6:7] op_sel_hi:[0,1,1]
	v_pk_add_f32 v[42:43], v[42:43], v[44:45]
	v_pk_add_f32 v[2:3], v[2:3], v[4:5]
	s_nop 1
	v_add_f32_dpp v42, v42, v42 quad_perm:[1,0,3,2] row_mask:0xf bank_mask:0xf bound_ctrl:1
	v_add_f32_dpp v43, v43, v43 quad_perm:[1,0,3,2] row_mask:0xf bank_mask:0xf bound_ctrl:1
	s_nop 1
	v_add_f32_dpp v2, v2, v2 quad_perm:[1,0,3,2] row_mask:0xf bank_mask:0xf bound_ctrl:1
	v_add_f32_dpp v3, v3, v3 quad_perm:[1,0,3,2] row_mask:0xf bank_mask:0xf bound_ctrl:1
	s_nop 1
	v_add_f32_dpp v42, v42, v42 quad_perm:[2,3,0,1] row_mask:0xf bank_mask:0xf bound_ctrl:1
	v_add_f32_dpp v43, v43, v43 quad_perm:[2,3,0,1] row_mask:0xf bank_mask:0xf bound_ctrl:1
	s_nop 1
	v_add_f32_dpp v2, v2, v2 quad_perm:[2,3,0,1] row_mask:0xf bank_mask:0xf bound_ctrl:1
	v_add_f32_dpp v3, v3, v3 quad_perm:[2,3,0,1] row_mask:0xf bank_mask:0xf bound_ctrl:1
	s_nop 1
	v_add_f32_dpp v42, v42, v42 row_half_mirror row_mask:0xf bank_mask:0xf bound_ctrl:1
	v_add_f32_dpp v43, v43, v43 row_half_mirror row_mask:0xf bank_mask:0xf bound_ctrl:1
	s_nop 1
	v_add_f32_dpp v2, v2, v2 row_half_mirror row_mask:0xf bank_mask:0xf bound_ctrl:1
	v_add_f32_dpp v3, v3, v3 row_half_mirror row_mask:0xf bank_mask:0xf bound_ctrl:1
	s_nop 1
	v_add_f32_dpp v42, v42, v42 row_mirror row_mask:0xf bank_mask:0xf bound_ctrl:1
	v_add_f32_dpp v43, v43, v43 row_mirror row_mask:0xf bank_mask:0xf bound_ctrl:1
	s_waitcnt lgkmcnt(1)
	v_pk_mul_f32 v[44:45], v[46:47], v[42:43] op_sel_hi:[0,1]
	s_nop 1
	v_add_f32_dpp v2, v2, v2 row_mirror row_mask:0xf bank_mask:0xf bound_ctrl:1
	v_add_f32_dpp v3, v3, v3 row_mirror row_mask:0xf bank_mask:0xf bound_ctrl:1
	v_pk_fma_f32 v[44:45], v[34:35], v[54:55], v[44:45] op_sel_hi:[0,1,1] neg_lo:[0,0,1] neg_hi:[0,0,1]
	v_cvt_pk_bf16_f32 v2, v2, v3
	s_waitcnt lgkmcnt(0)
	v_pk_fma_f32 v[54:55], v[38:39], v[58:59], v[44:45] op_sel_hi:[0,1,1]
	v_pk_mul_f32 v[44:45], v[46:47], v[42:43] op_sel:[1,0]
	ds_write_b32 v14, v2 offset:1024
	v_pk_fma_f32 v[34:35], v[34:35], v[50:51], v[44:45] op_sel:[1,0,0] neg_lo:[0,0,1] neg_hi:[0,0,1]
	ds_read_b128 v[2:5], v15 offset:15360
	ds_read_b128 v[6:9], v15 offset:15616
	ds_read_b128 v[18:21], v15 offset:15872
	ds_read_b128 v[22:25], v15 offset:16128
	ds_read_b128 v[26:29], v15 offset:16384
	ds_read_b64 v[60:61], v16 offset:16640
	v_pk_fma_f32 v[50:51], v[38:39], v[58:59], v[34:35] op_sel:[1,0,0]
	v_pk_mul_f32 v[34:35], v[48:49], v[42:43] op_sel_hi:[0,1]
	v_pk_fma_f32 v[34:35], v[36:37], v[56:57], v[34:35] op_sel_hi:[0,1,1] neg_lo:[0,0,1] neg_hi:[0,0,1]
	v_mov_b32_e32 v36, v49
	v_pk_fma_f32 v[56:57], v[40:41], v[58:59], v[34:35] op_sel_hi:[0,1,1]
	v_mov_b32_e32 v34, v37
	v_pk_mul_f32 v[36:37], v[36:37], v[42:43] op_sel_hi:[0,1]
	v_pk_fma_f32 v[34:35], v[34:35], v[52:53], v[36:37] op_sel_hi:[0,1,1] neg_lo:[0,0,1] neg_hi:[0,0,1]
	v_mov_b32_e32 v36, v41
	s_waitcnt lgkmcnt(2)
	v_pk_mul_f32 v[62:63], v[22:23], v[50:51] op_sel:[1,0]
	v_pk_fma_f32 v[52:53], v[36:37], v[58:59], v[34:35] op_sel_hi:[0,1,1]
	v_pk_fma_f32 v[22:23], v[22:23], v[54:55], v[62:63] op_sel_hi:[0,1,1]
	v_mov_b32_e32 v62, v25
	v_pk_mul_f32 v[34:35], v[30:31], v[50:51] op_sel:[1,0]
	v_pk_mul_f32 v[62:63], v[62:63], v[52:53] op_sel_hi:[0,1]
	v_pk_fma_f32 v[30:31], v[30:31], v[54:55], v[34:35] op_sel_hi:[0,1,1]
	v_mov_b32_e32 v34, v33
	v_pk_fma_f32 v[24:25], v[24:25], v[56:57], v[62:63] op_sel_hi:[0,1,1]
	v_pk_mul_f32 v[34:35], v[34:35], v[52:53] op_sel_hi:[0,1]
	v_pk_add_f32 v[22:23], v[22:23], v[24:25]
	v_pk_fma_f32 v[32:33], v[32:33], v[56:57], v[34:35] op_sel_hi:[0,1,1]
	s_nop 1
	v_add_f32_dpp v22, v22, v22 quad_perm:[1,0,3,2] row_mask:0xf bank_mask:0xf bound_ctrl:1
	v_add_f32_dpp v23, v23, v23 quad_perm:[1,0,3,2] row_mask:0xf bank_mask:0xf bound_ctrl:1
	v_pk_add_f32 v[30:31], v[30:31], v[32:33]
	s_nop 1
	v_add_f32_dpp v22, v22, v22 quad_perm:[2,3,0,1] row_mask:0xf bank_mask:0xf bound_ctrl:1
	v_add_f32_dpp v23, v23, v23 quad_perm:[2,3,0,1] row_mask:0xf bank_mask:0xf bound_ctrl:1
	s_nop 1
	v_add_f32_dpp v30, v30, v30 quad_perm:[1,0,3,2] row_mask:0xf bank_mask:0xf bound_ctrl:1
	v_add_f32_dpp v31, v31, v31 quad_perm:[1,0,3,2] row_mask:0xf bank_mask:0xf bound_ctrl:1
	s_nop 1
	v_add_f32_dpp v22, v22, v22 row_half_mirror row_mask:0xf bank_mask:0xf bound_ctrl:1
	v_add_f32_dpp v23, v23, v23 row_half_mirror row_mask:0xf bank_mask:0xf bound_ctrl:1
	s_nop 1
	v_add_f32_dpp v30, v30, v30 quad_perm:[2,3,0,1] row_mask:0xf bank_mask:0xf bound_ctrl:1
	v_add_f32_dpp v31, v31, v31 quad_perm:[2,3,0,1] row_mask:0xf bank_mask:0xf bound_ctrl:1
	s_nop 1
	v_add_f32_dpp v22, v22, v22 row_mirror row_mask:0xf bank_mask:0xf bound_ctrl:1
	v_add_f32_dpp v23, v23, v23 row_mirror row_mask:0xf bank_mask:0xf bound_ctrl:1
	s_waitcnt lgkmcnt(1)
; #define LAS __attribute__((address_space(3)))
; DI unsigned pk2(float a, float b) { f32x2 v = {a, b}; bf2_t r = __builtin_convertvector(v, bf2_t); return __builtin_bit_cast(unsigned, r); }
; #define DPP_ADD2(a, b, ctrl) asm("s_nop 1\n\tv_add_f32_dpp %0, %0, %0 " ctrl " row_mask:0xf bank_mask:0xf bound_ctrl:1\n\tv_add_f32_dpp %1, %1, %1 " ctrl " row_mask:0xf bank_mask:0xf bound_ctrl:1" : "+v"(a), "+v"(b))
; DI f32x2 red16p(f32x2 x) { float a = x.x, b = x.y; red16x2(a, b); return (f32x2){a, b}; }
; DI void red16x2(float& a, float& b) { DPP_ADD2(a, b, "quad_perm:[1,0,3,2]"); DPP_ADD2(a, b, "quad_perm:[2,3,0,1]"); DPP_ADD2(a, b, "row_half_mirror"); DPP_ADD2(a, b, "row_mirror"); }
; DI void scan_bh2(const Args& a, int l, int bh, int halfsel, LAS unsigned char* lds) {
;     ...
;             for (int st = 0; st < T; ++st) {
;                 f32x4 nr4, nd4, nk4, nkk4, nb4; f32x2 nv2;
;                 if (st < T - 1) {
;                     const LAS float* o = cur + (st + 1) * 384;
;                     nr4 = *(const LAS f32x4*)(o + kq * 4); nd4 = *(const LAS f32x4*)(o + 64 + kq * 4); nk4 = *(const LAS f32x4*)(o + 128 + kq * 4);
;                     nkk4 = *(const LAS f32x4*)(o + 192 + kq * 4); nb4 = *(const LAS f32x4*)(o + 256 + kq * 4); nv2 = *(const LAS f32x2*)(o + 320 + row0);
;                 }
;                 f32x2 sa = S[0] * kk4[0]; sa += S[1] * kk4[1]; f32x2 sb = S[2] * kk4[2]; sb += S[3] * kk4[3]; sa += sb;
;                 sa = red16p(sa); sa = -sa;
; #pragma unroll
;                 for (int j = 0; j < 4; ++j) S[j] = S[j] * d4[j] + sa * b4[j] + v2 * k4[j];
;                 f32x2 y = S[0] * r4[0]; y += S[1] * r4[1]; f32x2 yc = S[2] * r4[2]; yc += S[3] * r4[3]; y += yc;
;                 y = red16p(y);
;                 *(LAS unsigned*)(yb + st * 128 + row0 * 2) = pk2(y.x, y.y);
;                 if (st < T - 1) { r4 = nr4; d4 = nd4; k4 = nk4; kk4 = nkk4; b4 = nb4; v2 = nv2; }
;             }
	v_pk_mul_f32 v[24:25], v[26:27], v[22:23] op_sel_hi:[0,1]
	s_nop 1
	v_add_f32_dpp v30, v30, v30 row_half_mirror row_mask:0xf bank_mask:0xf bound_ctrl:1
	v_add_f32_dpp v31, v31, v31 row_half_mirror row_mask:0xf bank_mask:0xf bound_ctrl:1
	v_pk_fma_f32 v[24:25], v[6:7], v[54:55], v[24:25] op_sel_hi:[0,1,1] neg_lo:[0,0,1] neg_hi:[0,0,1]
	s_nop 1
	v_add_f32_dpp v30, v30, v30 row_mirror row_mask:0xf bank_mask:0xf bound_ctrl:1
	v_add_f32_dpp v31, v31, v31 row_mirror row_mask:0xf bank_mask:0xf bound_ctrl:1
	s_waitcnt lgkmcnt(0)
	v_pk_fma_f32 v[54:55], v[18:19], v[60:61], v[24:25] op_sel_hi:[0,1,1]
	v_cvt_pk_bf16_f32 v17, v30, v31
	v_pk_mul_f32 v[24:25], v[26:27], v[22:23] op_sel:[1,0]
	ds_write_b32 v14, v17 offset:1152
	v_pk_fma_f32 v[6:7], v[6:7], v[50:51], v[24:25] op_sel:[1,0,0] neg_lo:[0,0,1] neg_hi:[0,0,1]
	ds_read_b128 v[30:33], v15 offset:16896
	ds_read_b128 v[34:37], v15 offset:17152
	ds_read_b128 v[38:41], v15 offset:17408
	ds_read_b128 v[42:45], v15 offset:17664
	ds_read_b128 v[46:49], v15 offset:17920
	ds_read_b64 v[58:59], v16 offset:18176
	v_pk_fma_f32 v[50:51], v[18:19], v[60:61], v[6:7] op_sel:[1,0,0]
	v_pk_mul_f32 v[6:7], v[28:29], v[22:23] op_sel_hi:[0,1]
	v_pk_fma_f32 v[6:7], v[8:9], v[56:57], v[6:7] op_sel_hi:[0,1,1] neg_lo:[0,0,1] neg_hi:[0,0,1]
	v_mov_b32_e32 v8, v29
	v_pk_fma_f32 v[56:57], v[20:21], v[60:61], v[6:7] op_sel_hi:[0,1,1]
	v_mov_b32_e32 v6, v9
	v_pk_mul_f32 v[8:9], v[8:9], v[22:23] op_sel_hi:[0,1]
	v_pk_fma_f32 v[6:7], v[6:7], v[52:53], v[8:9] op_sel_hi:[0,1,1] neg_lo:[0,0,1] neg_hi:[0,0,1]
	v_mov_b32_e32 v8, v21
	s_waitcnt lgkmcnt(2)
	v_pk_mul_f32 v[62:63], v[42:43], v[50:51] op_sel:[1,0]
	v_pk_fma_f32 v[52:53], v[8:9], v[60:61], v[6:7] op_sel_hi:[0,1,1]
	v_pk_mul_f32 v[6:7], v[2:3], v[50:51] op_sel:[1,0]
	v_pk_fma_f32 v[42:43], v[42:43], v[54:55], v[62:63] op_sel_hi:[0,1,1]
	v_mov_b32_e32 v62, v45
	v_pk_fma_f32 v[2:3], v[2:3], v[54:55], v[6:7] op_sel_hi:[0,1,1]
	v_mov_b32_e32 v6, v5
	v_pk_mul_f32 v[62:63], v[62:63], v[52:53] op_sel_hi:[0,1]
	v_pk_mul_f32 v[6:7], v[6:7], v[52:53] op_sel_hi:[0,1]
	v_pk_fma_f32 v[44:45], v[44:45], v[56:57], v[62:63] op_sel_hi:[0,1,1]
	v_pk_fma_f32 v[4:5], v[4:5], v[56:57], v[6:7] op_sel_hi:[0,1,1]
	v_pk_add_f32 v[42:43], v[42:43], v[44:45]
	v_pk_add_f32 v[2:3], v[2:3], v[4:5]
	s_nop 1
	v_add_f32_dpp v42, v42, v42 quad_perm:[1,0,3,2] row_mask:0xf bank_mask:0xf bound_ctrl:1
	v_add_f32_dpp v43, v43, v43 quad_perm:[1,0,3,2] row_mask:0xf bank_mask:0xf bound_ctrl:1
	s_nop 1
	v_add_f32_dpp v2, v2, v2 quad_perm:[1,0,3,2] row_mask:0xf bank_mask:0xf bound_ctrl:1
	v_add_f32_dpp v3, v3, v3 quad_perm:[1,0,3,2] row_mask:0xf bank_mask:0xf bound_ctrl:1
	s_nop 1
	v_add_f32_dpp v42, v42, v42 quad_perm:[2,3,0,1] row_mask:0xf bank_mask:0xf bound_ctrl:1
	v_add_f32_dpp v43, v43, v43 quad_perm:[2,3,0,1] row_mask:0xf bank_mask:0xf bound_ctrl:1
	s_nop 1
	v_add_f32_dpp v2, v2, v2 quad_perm:[2,3,0,1] row_mask:0xf bank_mask:0xf bound_ctrl:1
	v_add_f32_dpp v3, v3, v3 quad_perm:[2,3,0,1] row_mask:0xf bank_mask:0xf bound_ctrl:1
	s_nop 1
	v_add_f32_dpp v42, v42, v42 row_half_mirror row_mask:0xf bank_mask:0xf bound_ctrl:1
	v_add_f32_dpp v43, v43, v43 row_half_mirror row_mask:0xf bank_mask:0xf bound_ctrl:1
	s_nop 1
	v_add_f32_dpp v2, v2, v2 row_half_mirror row_mask:0xf bank_mask:0xf bound_ctrl:1
	v_add_f32_dpp v3, v3, v3 row_half_mirror row_mask:0xf bank_mask:0xf bound_ctrl:1
	s_nop 1
	v_add_f32_dpp v42, v42, v42 row_mirror row_mask:0xf bank_mask:0xf bound_ctrl:1
	v_add_f32_dpp v43, v43, v43 row_mirror row_mask:0xf bank_mask:0xf bound_ctrl:1
	s_waitcnt lgkmcnt(1)
	v_pk_mul_f32 v[44:45], v[46:47], v[42:43] op_sel_hi:[0,1]
	s_nop 1
	v_add_f32_dpp v2, v2, v2 row_mirror row_mask:0xf bank_mask:0xf bound_ctrl:1
	v_add_f32_dpp v3, v3, v3 row_mirror row_mask:0xf bank_mask:0xf bound_ctrl:1
	v_pk_fma_f32 v[44:45], v[34:35], v[54:55], v[44:45] op_sel_hi:[0,1,1] neg_lo:[0,0,1] neg_hi:[0,0,1]
	v_cvt_pk_bf16_f32 v2, v2, v3
	s_waitcnt lgkmcnt(0)
	v_pk_fma_f32 v[54:55], v[38:39], v[58:59], v[44:45] op_sel_hi:[0,1,1]
	v_pk_mul_f32 v[44:45], v[46:47], v[42:43] op_sel:[1,0]
	ds_write_b32 v14, v2 offset:1280
	v_pk_fma_f32 v[34:35], v[34:35], v[50:51], v[44:45] op_sel:[1,0,0] neg_lo:[0,0,1] neg_hi:[0,0,1]
	ds_read_b128 v[2:5], v15 offset:18432
	ds_read_b128 v[6:9], v15 offset:18688
	ds_read_b128 v[18:21], v15 offset:18944
	ds_read_b128 v[22:25], v15 offset:19200
	ds_read_b128 v[26:29], v15 offset:19456
	ds_read_b64 v[60:61], v16 offset:19712
	v_pk_fma_f32 v[50:51], v[38:39], v[58:59], v[34:35] op_sel:[1,0,0]
	v_pk_mul_f32 v[34:35], v[48:49], v[42:43] op_sel_hi:[0,1]
	v_pk_fma_f32 v[34:35], v[36:37], v[56:57], v[34:35] op_sel_hi:[0,1,1] neg_lo:[0,0,1] neg_hi:[0,0,1]
	v_mov_b32_e32 v36, v49
	v_pk_fma_f32 v[56:57], v[40:41], v[58:59], v[34:35] op_sel_hi:[0,1,1]
	v_mov_b32_e32 v34, v37
	v_pk_mul_f32 v[36:37], v[36:37], v[42:43] op_sel_hi:[0,1]
	v_pk_fma_f32 v[34:35], v[34:35], v[52:53], v[36:37] op_sel_hi:[0,1,1] neg_lo:[0,0,1] neg_hi:[0,0,1]
	v_mov_b32_e32 v36, v41
	s_waitcnt lgkmcnt(2)
; #define LAS __attribute__((address_space(3)))
; DI unsigned pk2(float a, float b) { f32x2 v = {a, b}; bf2_t r = __builtin_convertvector(v, bf2_t); return __builtin_bit_cast(unsigned, r); }
; #define DPP_ADD2(a, b, ctrl) asm("s_nop 1\n\tv_add_f32_dpp %0, %0, %0 " ctrl " row_mask:0xf bank_mask:0xf bound_ctrl:1\n\tv_add_f32_dpp %1, %1, %1 " ctrl " row_mask:0xf bank_mask:0xf bound_ctrl:1" : "+v"(a), "+v"(b))
; DI f32x2 red16p(f32x2 x) { float a = x.x, b = x.y; red16x2(a, b); return (f32x2){a, b}; }
; DI void red16x2(float& a, float& b) { DPP_ADD2(a, b, "quad_perm:[1,0,3,2]"); DPP_ADD2(a, b, "quad_perm:[2,3,0,1]"); DPP_ADD2(a, b, "row_half_mirror"); DPP_ADD2(a, b, "row_mirror"); }
; DI void scan_bh2(const Args& a, int l, int bh, int halfsel, LAS unsigned char* lds) {
;     ...
;             for (int st = 0; st < T; ++st) {
;                 f32x4 nr4, nd4, nk4, nkk4, nb4; f32x2 nv2;
;                 if (st < T - 1) {
;                     const LAS float* o = cur + (st + 1) * 384;
;                     nr4 = *(const LAS f32x4*)(o + kq * 4); nd4 = *(const LAS f32x4*)(o + 64 + kq * 4); nk4 = *(const LAS f32x4*)(o + 128 + kq * 4);
;                     nkk4 = *(const LAS f32x4*)(o + 192 + kq * 4); nb4 = *(const LAS f32x4*)(o + 256 + kq * 4); nv2 = *(const LAS f32x2*)(o + 320 + row0);
;                 }
;                 f32x2 sa = S[0] * kk4[0]; sa += S[1] * kk4[1]; f32x2 sb = S[2] * kk4[2]; sb += S[3] * kk4[3]; sa += sb;
;                 sa = red16p(sa); sa = -sa;
; #pragma unroll
;                 for (int j = 0; j < 4; ++j) S[j] = S[j] * d4[j] + sa * b4[j] + v2 * k4[j];
;                 f32x2 y = S[0] * r4[0]; y += S[1] * r4[1]; f32x2 yc = S[2] * r4[2]; yc += S[3] * r4[3]; y += yc;
;                 y = red16p(y);
;                 *(LAS unsigned*)(yb + st * 128 + row0 * 2) = pk2(y.x, y.y);
;                 if (st < T - 1) { r4 = nr4; d4 = nd4; k4 = nk4; kk4 = nkk4; b4 = nb4; v2 = nv2; }
;             }
	v_pk_mul_f32 v[62:63], v[22:23], v[50:51] op_sel:[1,0]
	v_pk_fma_f32 v[52:53], v[36:37], v[58:59], v[34:35] op_sel_hi:[0,1,1]
	v_pk_fma_f32 v[22:23], v[22:23], v[54:55], v[62:63] op_sel_hi:[0,1,1]
	v_mov_b32_e32 v62, v25
	v_pk_mul_f32 v[34:35], v[30:31], v[50:51] op_sel:[1,0]
	v_pk_mul_f32 v[62:63], v[62:63], v[52:53] op_sel_hi:[0,1]
	v_pk_fma_f32 v[30:31], v[30:31], v[54:55], v[34:35] op_sel_hi:[0,1,1]
	v_mov_b32_e32 v34, v33
	v_pk_fma_f32 v[24:25], v[24:25], v[56:57], v[62:63] op_sel_hi:[0,1,1]
	v_pk_mul_f32 v[34:35], v[34:35], v[52:53] op_sel_hi:[0,1]
	v_pk_add_f32 v[22:23], v[22:23], v[24:25]
	v_pk_fma_f32 v[32:33], v[32:33], v[56:57], v[34:35] op_sel_hi:[0,1,1]
	s_nop 1
	v_add_f32_dpp v22, v22, v22 quad_perm:[1,0,3,2] row_mask:0xf bank_mask:0xf bound_ctrl:1
	v_add_f32_dpp v23, v23, v23 quad_perm:[1,0,3,2] row_mask:0xf bank_mask:0xf bound_ctrl:1
	v_pk_add_f32 v[30:31], v[30:31], v[32:33]
	s_nop 1
	v_add_f32_dpp v22, v22, v22 quad_perm:[2,3,0,1] row_mask:0xf bank_mask:0xf bound_ctrl:1
	v_add_f32_dpp v23, v23, v23 quad_perm:[2,3,0,1] row_mask:0xf bank_mask:0xf bound_ctrl:1
	s_nop 1
	v_add_f32_dpp v30, v30, v30 quad_perm:[1,0,3,2] row_mask:0xf bank_mask:0xf bound_ctrl:1
	v_add_f32_dpp v31, v31, v31 quad_perm:[1,0,3,2] row_mask:0xf bank_mask:0xf bound_ctrl:1
	s_nop 1
	v_add_f32_dpp v22, v22, v22 row_half_mirror row_mask:0xf bank_mask:0xf bound_ctrl:1
	v_add_f32_dpp v23, v23, v23 row_half_mirror row_mask:0xf bank_mask:0xf bound_ctrl:1
	s_nop 1
	v_add_f32_dpp v30, v30, v30 quad_perm:[2,3,0,1] row_mask:0xf bank_mask:0xf bound_ctrl:1
	v_add_f32_dpp v31, v31, v31 quad_perm:[2,3,0,1] row_mask:0xf bank_mask:0xf bound_ctrl:1
	s_nop 1
	v_add_f32_dpp v22, v22, v22 row_mirror row_mask:0xf bank_mask:0xf bound_ctrl:1
	v_add_f32_dpp v23, v23, v23 row_mirror row_mask:0xf bank_mask:0xf bound_ctrl:1
	s_waitcnt lgkmcnt(1)
	v_pk_mul_f32 v[24:25], v[26:27], v[22:23] op_sel_hi:[0,1]
	s_nop 1
	v_add_f32_dpp v30, v30, v30 row_half_mirror row_mask:0xf bank_mask:0xf bound_ctrl:1
	v_add_f32_dpp v31, v31, v31 row_half_mirror row_mask:0xf bank_mask:0xf bound_ctrl:1
	v_pk_fma_f32 v[24:25], v[6:7], v[54:55], v[24:25] op_sel_hi:[0,1,1] neg_lo:[0,0,1] neg_hi:[0,0,1]
	s_nop 1
	v_add_f32_dpp v30, v30, v30 row_mirror row_mask:0xf bank_mask:0xf bound_ctrl:1
	v_add_f32_dpp v31, v31, v31 row_mirror row_mask:0xf bank_mask:0xf bound_ctrl:1
	s_waitcnt lgkmcnt(0)
	v_pk_fma_f32 v[54:55], v[18:19], v[60:61], v[24:25] op_sel_hi:[0,1,1]
	v_cvt_pk_bf16_f32 v17, v30, v31
	v_pk_mul_f32 v[24:25], v[26:27], v[22:23] op_sel:[1,0]
	ds_write_b32 v14, v17 offset:1408
	v_pk_fma_f32 v[6:7], v[6:7], v[50:51], v[24:25] op_sel:[1,0,0] neg_lo:[0,0,1] neg_hi:[0,0,1]
	ds_read_b128 v[30:33], v15 offset:19968
	ds_read_b128 v[34:37], v15 offset:20224
	ds_read_b128 v[38:41], v15 offset:20480
	ds_read_b128 v[42:45], v15 offset:20736
	ds_read_b128 v[46:49], v15 offset:20992
	ds_read_b64 v[58:59], v16 offset:21248
	v_pk_fma_f32 v[50:51], v[18:19], v[60:61], v[6:7] op_sel:[1,0,0]
	v_pk_mul_f32 v[6:7], v[28:29], v[22:23] op_sel_hi:[0,1]
	v_pk_fma_f32 v[6:7], v[8:9], v[56:57], v[6:7] op_sel_hi:[0,1,1] neg_lo:[0,0,1] neg_hi:[0,0,1]
	v_mov_b32_e32 v8, v29
	v_pk_fma_f32 v[56:57], v[20:21], v[60:61], v[6:7] op_sel_hi:[0,1,1]
	v_mov_b32_e32 v6, v9
	v_pk_mul_f32 v[8:9], v[8:9], v[22:23] op_sel_hi:[0,1]
	v_pk_fma_f32 v[6:7], v[6:7], v[52:53], v[8:9] op_sel_hi:[0,1,1] neg_lo:[0,0,1] neg_hi:[0,0,1]
	v_mov_b32_e32 v8, v21
	s_waitcnt lgkmcnt(2)
	v_pk_mul_f32 v[62:63], v[42:43], v[50:51] op_sel:[1,0]
	v_pk_fma_f32 v[52:53], v[8:9], v[60:61], v[6:7] op_sel_hi:[0,1,1]
	v_pk_mul_f32 v[6:7], v[2:3], v[50:51] op_sel:[1,0]
	v_pk_fma_f32 v[42:43], v[42:43], v[54:55], v[62:63] op_sel_hi:[0,1,1]
	v_mov_b32_e32 v62, v45
	v_pk_fma_f32 v[2:3], v[2:3], v[54:55], v[6:7] op_sel_hi:[0,1,1]
	v_mov_b32_e32 v6, v5
	v_pk_mul_f32 v[62:63], v[62:63], v[52:53] op_sel_hi:[0,1]
	v_pk_mul_f32 v[6:7], v[6:7], v[52:53] op_sel_hi:[0,1]
	v_pk_fma_f32 v[44:45], v[44:45], v[56:57], v[62:63] op_sel_hi:[0,1,1]
	v_pk_fma_f32 v[4:5], v[4:5], v[56:57], v[6:7] op_sel_hi:[0,1,1]
	v_pk_add_f32 v[42:43], v[42:43], v[44:45]
	v_pk_add_f32 v[2:3], v[2:3], v[4:5]
	s_nop 1
	v_add_f32_dpp v42, v42, v42 quad_perm:[1,0,3,2] row_mask:0xf bank_mask:0xf bound_ctrl:1
	v_add_f32_dpp v43, v43, v43 quad_perm:[1,0,3,2] row_mask:0xf bank_mask:0xf bound_ctrl:1
	s_nop 1
	v_add_f32_dpp v2, v2, v2 quad_perm:[1,0,3,2] row_mask:0xf bank_mask:0xf bound_ctrl:1
	v_add_f32_dpp v3, v3, v3 quad_perm:[1,0,3,2] row_mask:0xf bank_mask:0xf bound_ctrl:1
	s_nop 1
	v_add_f32_dpp v42, v42, v42 quad_perm:[2,3,0,1] row_mask:0xf bank_mask:0xf bound_ctrl:1
	v_add_f32_dpp v43, v43, v43 quad_perm:[2,3,0,1] row_mask:0xf bank_mask:0xf bound_ctrl:1
	s_nop 1
	v_add_f32_dpp v2, v2, v2 quad_perm:[2,3,0,1] row_mask:0xf bank_mask:0xf bound_ctrl:1
	v_add_f32_dpp v3, v3, v3 quad_perm:[2,3,0,1] row_mask:0xf bank_mask:0xf bound_ctrl:1
	s_nop 1
	v_add_f32_dpp v42, v42, v42 row_half_mirror row_mask:0xf bank_mask:0xf bound_ctrl:1
	v_add_f32_dpp v43, v43, v43 row_half_mirror row_mask:0xf bank_mask:0xf bound_ctrl:1
	s_nop 1
	v_add_f32_dpp v2, v2, v2 row_half_mirror row_mask:0xf bank_mask:0xf bound_ctrl:1
	v_add_f32_dpp v3, v3, v3 row_half_mirror row_mask:0xf bank_mask:0xf bound_ctrl:1
	s_nop 1
	v_add_f32_dpp v42, v42, v42 row_mirror row_mask:0xf bank_mask:0xf bound_ctrl:1
	v_add_f32_dpp v43, v43, v43 row_mirror row_mask:0xf bank_mask:0xf bound_ctrl:1
	s_waitcnt lgkmcnt(1)
	v_pk_mul_f32 v[44:45], v[46:47], v[42:43] op_sel_hi:[0,1]
	s_nop 1
	v_add_f32_dpp v2, v2, v2 row_mirror row_mask:0xf bank_mask:0xf bound_ctrl:1
	v_add_f32_dpp v3, v3, v3 row_mirror row_mask:0xf bank_mask:0xf bound_ctrl:1
	v_pk_fma_f32 v[44:45], v[34:35], v[54:55], v[44:45] op_sel_hi:[0,1,1] neg_lo:[0,0,1] neg_hi:[0,0,1]
	v_cvt_pk_bf16_f32 v2, v2, v3
	s_waitcnt lgkmcnt(0)
; #define LAS __attribute__((address_space(3)))
; DI unsigned pk2(float a, float b) { f32x2 v = {a, b}; bf2_t r = __builtin_convertvector(v, bf2_t); return __builtin_bit_cast(unsigned, r); }
; #define DPP_ADD2(a, b, ctrl) asm("s_nop 1\n\tv_add_f32_dpp %0, %0, %0 " ctrl " row_mask:0xf bank_mask:0xf bound_ctrl:1\n\tv_add_f32_dpp %1, %1, %1 " ctrl " row_mask:0xf bank_mask:0xf bound_ctrl:1" : "+v"(a), "+v"(b))
; DI f32x2 red16p(f32x2 x) { float a = x.x, b = x.y; red16x2(a, b); return (f32x2){a, b}; }
; DI void red16x2(float& a, float& b) { DPP_ADD2(a, b, "quad_perm:[1,0,3,2]"); DPP_ADD2(a, b, "quad_perm:[2,3,0,1]"); DPP_ADD2(a, b, "row_half_mirror"); DPP_ADD2(a, b, "row_mirror"); }
; DI void scan_bh2(const Args& a, int l, int bh, int halfsel, LAS unsigned char* lds) {
;     ...
;             for (int st = 0; st < T; ++st) {
;                 f32x4 nr4, nd4, nk4, nkk4, nb4; f32x2 nv2;
;                 if (st < T - 1) {
;                     const LAS float* o = cur + (st + 1) * 384;
;                     nr4 = *(const LAS f32x4*)(o + kq * 4); nd4 = *(const LAS f32x4*)(o + 64 + kq * 4); nk4 = *(const LAS f32x4*)(o + 128 + kq * 4);
;                     nkk4 = *(const LAS f32x4*)(o + 192 + kq * 4); nb4 = *(const LAS f32x4*)(o + 256 + kq * 4); nv2 = *(const LAS f32x2*)(o + 320 + row0);
;                 }
;                 f32x2 sa = S[0] * kk4[0]; sa += S[1] * kk4[1]; f32x2 sb = S[2] * kk4[2]; sb += S[3] * kk4[3]; sa += sb;
;                 sa = red16p(sa); sa = -sa;
; #pragma unroll
;                 for (int j = 0; j < 4; ++j) S[j] = S[j] * d4[j] + sa * b4[j] + v2 * k4[j];
;                 f32x2 y = S[0] * r4[0]; y += S[1] * r4[1]; f32x2 yc = S[2] * r4[2]; yc += S[3] * r4[3]; y += yc;
;                 y = red16p(y);
;                 *(LAS unsigned*)(yb + st * 128 + row0 * 2) = pk2(y.x, y.y);
;                 if (st < T - 1) { r4 = nr4; d4 = nd4; k4 = nk4; kk4 = nkk4; b4 = nb4; v2 = nv2; }
;             }
	v_pk_fma_f32 v[54:55], v[38:39], v[58:59], v[44:45] op_sel_hi:[0,1,1]
	v_pk_mul_f32 v[44:45], v[46:47], v[42:43] op_sel:[1,0]
	ds_write_b32 v14, v2 offset:1536
	v_pk_fma_f32 v[34:35], v[34:35], v[50:51], v[44:45] op_sel:[1,0,0] neg_lo:[0,0,1] neg_hi:[0,0,1]
	ds_read_b128 v[2:5], v15 offset:21504
	ds_read_b128 v[6:9], v15 offset:21760
	ds_read_b128 v[18:21], v15 offset:22016
	ds_read_b128 v[22:25], v15 offset:22272
	ds_read_b128 v[26:29], v15 offset:22528
	ds_read_b64 v[60:61], v16 offset:22784
	v_pk_fma_f32 v[50:51], v[38:39], v[58:59], v[34:35] op_sel:[1,0,0]
	v_pk_mul_f32 v[34:35], v[48:49], v[42:43] op_sel_hi:[0,1]
	v_pk_fma_f32 v[34:35], v[36:37], v[56:57], v[34:35] op_sel_hi:[0,1,1] neg_lo:[0,0,1] neg_hi:[0,0,1]
	v_mov_b32_e32 v36, v49
	v_pk_fma_f32 v[56:57], v[40:41], v[58:59], v[34:35] op_sel_hi:[0,1,1]
	v_mov_b32_e32 v34, v37
	v_pk_mul_f32 v[36:37], v[36:37], v[42:43] op_sel_hi:[0,1]
	v_pk_fma_f32 v[34:35], v[34:35], v[52:53], v[36:37] op_sel_hi:[0,1,1] neg_lo:[0,0,1] neg_hi:[0,0,1]
	v_mov_b32_e32 v36, v41
	s_waitcnt lgkmcnt(2)
	v_pk_mul_f32 v[62:63], v[22:23], v[50:51] op_sel:[1,0]
	v_pk_fma_f32 v[52:53], v[36:37], v[58:59], v[34:35] op_sel_hi:[0,1,1]
	v_pk_fma_f32 v[22:23], v[22:23], v[54:55], v[62:63] op_sel_hi:[0,1,1]
	v_mov_b32_e32 v62, v25
	v_pk_mul_f32 v[34:35], v[30:31], v[50:51] op_sel:[1,0]
	v_pk_mul_f32 v[62:63], v[62:63], v[52:53] op_sel_hi:[0,1]
	v_pk_fma_f32 v[30:31], v[30:31], v[54:55], v[34:35] op_sel_hi:[0,1,1]
	v_mov_b32_e32 v34, v33
	v_pk_fma_f32 v[24:25], v[24:25], v[56:57], v[62:63] op_sel_hi:[0,1,1]
	v_pk_mul_f32 v[34:35], v[34:35], v[52:53] op_sel_hi:[0,1]
	v_pk_add_f32 v[22:23], v[22:23], v[24:25]
	v_pk_fma_f32 v[32:33], v[32:33], v[56:57], v[34:35] op_sel_hi:[0,1,1]
	s_nop 1
	v_add_f32_dpp v22, v22, v22 quad_perm:[1,0,3,2] row_mask:0xf bank_mask:0xf bound_ctrl:1
	v_add_f32_dpp v23, v23, v23 quad_perm:[1,0,3,2] row_mask:0xf bank_mask:0xf bound_ctrl:1
	v_pk_add_f32 v[30:31], v[30:31], v[32:33]
	s_nop 1
	v_add_f32_dpp v22, v22, v22 quad_perm:[2,3,0,1] row_mask:0xf bank_mask:0xf bound_ctrl:1
	v_add_f32_dpp v23, v23, v23 quad_perm:[2,3,0,1] row_mask:0xf bank_mask:0xf bound_ctrl:1
	s_nop 1
	v_add_f32_dpp v30, v30, v30 quad_perm:[1,0,3,2] row_mask:0xf bank_mask:0xf bound_ctrl:1
	v_add_f32_dpp v31, v31, v31 quad_perm:[1,0,3,2] row_mask:0xf bank_mask:0xf bound_ctrl:1
	s_nop 1
	v_add_f32_dpp v22, v22, v22 row_half_mirror row_mask:0xf bank_mask:0xf bound_ctrl:1
	v_add_f32_dpp v23, v23, v23 row_half_mirror row_mask:0xf bank_mask:0xf bound_ctrl:1
	s_nop 1
	v_add_f32_dpp v30, v30, v30 quad_perm:[2,3,0,1] row_mask:0xf bank_mask:0xf bound_ctrl:1
	v_add_f32_dpp v31, v31, v31 quad_perm:[2,3,0,1] row_mask:0xf bank_mask:0xf bound_ctrl:1
	s_nop 1
	v_add_f32_dpp v22, v22, v22 row_mirror row_mask:0xf bank_mask:0xf bound_ctrl:1
	v_add_f32_dpp v23, v23, v23 row_mirror row_mask:0xf bank_mask:0xf bound_ctrl:1
	s_waitcnt lgkmcnt(1)
	v_pk_mul_f32 v[24:25], v[26:27], v[22:23] op_sel_hi:[0,1]
	s_nop 1
	v_add_f32_dpp v30, v30, v30 row_half_mirror row_mask:0xf bank_mask:0xf bound_ctrl:1
	v_add_f32_dpp v31, v31, v31 row_half_mirror row_mask:0xf bank_mask:0xf bound_ctrl:1
	v_pk_fma_f32 v[24:25], v[6:7], v[54:55], v[24:25] op_sel_hi:[0,1,1] neg_lo:[0,0,1] neg_hi:[0,0,1]
	s_nop 1
	v_add_f32_dpp v30, v30, v30 row_mirror row_mask:0xf bank_mask:0xf bound_ctrl:1
	v_add_f32_dpp v31, v31, v31 row_mirror row_mask:0xf bank_mask:0xf bound_ctrl:1
	s_waitcnt lgkmcnt(0)
	v_pk_fma_f32 v[54:55], v[18:19], v[60:61], v[24:25] op_sel_hi:[0,1,1]
	v_cvt_pk_bf16_f32 v17, v30, v31
	v_pk_mul_f32 v[24:25], v[26:27], v[22:23] op_sel:[1,0]
	ds_write_b32 v14, v17 offset:1664
	v_pk_fma_f32 v[6:7], v[6:7], v[50:51], v[24:25] op_sel:[1,0,0] neg_lo:[0,0,1] neg_hi:[0,0,1]
	ds_read_b128 v[30:33], v15 offset:23040
	ds_read_b128 v[34:37], v15 offset:23296
	ds_read_b128 v[38:41], v15 offset:23552
	ds_read_b128 v[42:45], v15 offset:23808
	ds_read_b128 v[46:49], v15 offset:24064
	ds_read_b64 v[58:59], v16 offset:24320
	v_pk_fma_f32 v[50:51], v[18:19], v[60:61], v[6:7] op_sel:[1,0,0]
	v_pk_mul_f32 v[6:7], v[28:29], v[22:23] op_sel_hi:[0,1]
	v_pk_fma_f32 v[6:7], v[8:9], v[56:57], v[6:7] op_sel_hi:[0,1,1] neg_lo:[0,0,1] neg_hi:[0,0,1]
	v_mov_b32_e32 v8, v29
	v_pk_fma_f32 v[56:57], v[20:21], v[60:61], v[6:7] op_sel_hi:[0,1,1]
	v_mov_b32_e32 v6, v9
	v_pk_mul_f32 v[8:9], v[8:9], v[22:23] op_sel_hi:[0,1]
	v_pk_fma_f32 v[6:7], v[6:7], v[52:53], v[8:9] op_sel_hi:[0,1,1] neg_lo:[0,0,1] neg_hi:[0,0,1]
	v_mov_b32_e32 v8, v21
	s_waitcnt lgkmcnt(2)
	v_pk_mul_f32 v[62:63], v[42:43], v[50:51] op_sel:[1,0]
	v_pk_fma_f32 v[52:53], v[8:9], v[60:61], v[6:7] op_sel_hi:[0,1,1]
	v_pk_mul_f32 v[6:7], v[2:3], v[50:51] op_sel:[1,0]
	v_pk_fma_f32 v[42:43], v[42:43], v[54:55], v[62:63] op_sel_hi:[0,1,1]
	v_mov_b32_e32 v62, v45
	v_pk_fma_f32 v[2:3], v[2:3], v[54:55], v[6:7] op_sel_hi:[0,1,1]
	v_mov_b32_e32 v6, v5
	v_pk_mul_f32 v[62:63], v[62:63], v[52:53] op_sel_hi:[0,1]
	v_pk_mul_f32 v[6:7], v[6:7], v[52:53] op_sel_hi:[0,1]
	v_pk_fma_f32 v[44:45], v[44:45], v[56:57], v[62:63] op_sel_hi:[0,1,1]
	v_pk_fma_f32 v[4:5], v[4:5], v[56:57], v[6:7] op_sel_hi:[0,1,1]
	v_pk_add_f32 v[42:43], v[42:43], v[44:45]
	v_pk_add_f32 v[2:3], v[2:3], v[4:5]
	s_nop 1
	v_add_f32_dpp v42, v42, v42 quad_perm:[1,0,3,2] row_mask:0xf bank_mask:0xf bound_ctrl:1
	v_add_f32_dpp v43, v43, v43 quad_perm:[1,0,3,2] row_mask:0xf bank_mask:0xf bound_ctrl:1
	s_nop 1
	v_add_f32_dpp v2, v2, v2 quad_perm:[1,0,3,2] row_mask:0xf bank_mask:0xf bound_ctrl:1
	v_add_f32_dpp v3, v3, v3 quad_perm:[1,0,3,2] row_mask:0xf bank_mask:0xf bound_ctrl:1
	s_nop 1
	v_add_f32_dpp v42, v42, v42 quad_perm:[2,3,0,1] row_mask:0xf bank_mask:0xf bound_ctrl:1
	v_add_f32_dpp v43, v43, v43 quad_perm:[2,3,0,1] row_mask:0xf bank_mask:0xf bound_ctrl:1
	s_nop 1
	v_add_f32_dpp v2, v2, v2 quad_perm:[2,3,0,1] row_mask:0xf bank_mask:0xf bound_ctrl:1
	v_add_f32_dpp v3, v3, v3 quad_perm:[2,3,0,1] row_mask:0xf bank_mask:0xf bound_ctrl:1
	s_nop 1
	v_add_f32_dpp v42, v42, v42 row_half_mirror row_mask:0xf bank_mask:0xf bound_ctrl:1
	v_add_f32_dpp v43, v43, v43 row_half_mirror row_mask:0xf bank_mask:0xf bound_ctrl:1
	s_nop 1
	v_add_f32_dpp v2, v2, v2 row_half_mirror row_mask:0xf bank_mask:0xf bound_ctrl:1
	v_add_f32_dpp v3, v3, v3 row_half_mirror row_mask:0xf bank_mask:0xf bound_ctrl:1
	s_nop 1
	v_add_f32_dpp v42, v42, v42 row_mirror row_mask:0xf bank_mask:0xf bound_ctrl:1
	v_add_f32_dpp v43, v43, v43 row_mirror row_mask:0xf bank_mask:0xf bound_ctrl:1
	s_waitcnt lgkmcnt(1)
; #define LAS __attribute__((address_space(3)))
; DI unsigned pk2(float a, float b) { f32x2 v = {a, b}; bf2_t r = __builtin_convertvector(v, bf2_t); return __builtin_bit_cast(unsigned, r); }
; #define DPP_ADD2(a, b, ctrl) asm("s_nop 1\n\tv_add_f32_dpp %0, %0, %0 " ctrl " row_mask:0xf bank_mask:0xf bound_ctrl:1\n\tv_add_f32_dpp %1, %1, %1 " ctrl " row_mask:0xf bank_mask:0xf bound_ctrl:1" : "+v"(a), "+v"(b))
; DI f32x2 red16p(f32x2 x) { float a = x.x, b = x.y; red16x2(a, b); return (f32x2){a, b}; }
; DI void red16x2(float& a, float& b) { DPP_ADD2(a, b, "quad_perm:[1,0,3,2]"); DPP_ADD2(a, b, "quad_perm:[2,3,0,1]"); DPP_ADD2(a, b, "row_half_mirror"); DPP_ADD2(a, b, "row_mirror"); }
; DI void scan_bh2(const Args& a, int l, int bh, int halfsel, LAS unsigned char* lds) {
;     ...
;             for (int st = 0; st < T; ++st) {
;                 f32x4 nr4, nd4, nk4, nkk4, nb4; f32x2 nv2;
;                 if (st < T - 1) {
;                     const LAS float* o = cur + (st + 1) * 384;
;                     nr4 = *(const LAS f32x4*)(o + kq * 4); nd4 = *(const LAS f32x4*)(o + 64 + kq * 4); nk4 = *(const LAS f32x4*)(o + 128 + kq * 4);
;                     nkk4 = *(const LAS f32x4*)(o + 192 + kq * 4); nb4 = *(const LAS f32x4*)(o + 256 + kq * 4); nv2 = *(const LAS f32x2*)(o + 320 + row0);
;                 }
;                 f32x2 sa = S[0] * kk4[0]; sa += S[1] * kk4[1]; f32x2 sb = S[2] * kk4[2]; sb += S[3] * kk4[3]; sa += sb;
;                 sa = red16p(sa); sa = -sa;
; #pragma unroll
;                 for (int j = 0; j < 4; ++j) S[j] = S[j] * d4[j] + sa * b4[j] + v2 * k4[j];
;                 f32x2 y = S[0] * r4[0]; y += S[1] * r4[1]; f32x2 yc = S[2] * r4[2]; yc += S[3] * r4[3]; y += yc;
;                 y = red16p(y);
;                 *(LAS unsigned*)(yb + st * 128 + row0 * 2) = pk2(y.x, y.y);
;                 if (st < T - 1) { r4 = nr4; d4 = nd4; k4 = nk4; kk4 = nkk4; b4 = nb4; v2 = nv2; }
;             }
	v_pk_mul_f32 v[44:45], v[46:47], v[42:43] op_sel_hi:[0,1]
	s_nop 1
	v_add_f32_dpp v2, v2, v2 row_mirror row_mask:0xf bank_mask:0xf bound_ctrl:1
	v_add_f32_dpp v3, v3, v3 row_mirror row_mask:0xf bank_mask:0xf bound_ctrl:1
	v_pk_fma_f32 v[44:45], v[34:35], v[54:55], v[44:45] op_sel_hi:[0,1,1] neg_lo:[0,0,1] neg_hi:[0,0,1]
	v_cvt_pk_bf16_f32 v2, v2, v3
	s_waitcnt lgkmcnt(0)
	v_pk_fma_f32 v[54:55], v[38:39], v[58:59], v[44:45] op_sel_hi:[0,1,1]
	v_pk_mul_f32 v[44:45], v[46:47], v[42:43] op_sel:[1,0]
	ds_write_b32 v14, v2 offset:1792
	v_pk_fma_f32 v[34:35], v[34:35], v[50:51], v[44:45] op_sel:[1,0,0] neg_lo:[0,0,1] neg_hi:[0,0,1]
	ds_read_b128 v[2:5], v15 offset:24576
	ds_read_b128 v[6:9], v15 offset:24832
	ds_read_b128 v[18:21], v15 offset:25088
	ds_read_b128 v[22:25], v15 offset:25344
	ds_read_b128 v[26:29], v15 offset:25600
	ds_read_b64 v[60:61], v16 offset:25856
	v_pk_fma_f32 v[50:51], v[38:39], v[58:59], v[34:35] op_sel:[1,0,0]
	v_pk_mul_f32 v[34:35], v[48:49], v[42:43] op_sel_hi:[0,1]
	v_pk_fma_f32 v[34:35], v[36:37], v[56:57], v[34:35] op_sel_hi:[0,1,1] neg_lo:[0,0,1] neg_hi:[0,0,1]
	v_mov_b32_e32 v36, v49
	v_pk_fma_f32 v[56:57], v[40:41], v[58:59], v[34:35] op_sel_hi:[0,1,1]
	v_mov_b32_e32 v34, v37
	v_pk_mul_f32 v[36:37], v[36:37], v[42:43] op_sel_hi:[0,1]
	v_pk_fma_f32 v[34:35], v[34:35], v[52:53], v[36:37] op_sel_hi:[0,1,1] neg_lo:[0,0,1] neg_hi:[0,0,1]
	v_mov_b32_e32 v36, v41
	s_waitcnt lgkmcnt(2)
	v_pk_mul_f32 v[62:63], v[22:23], v[50:51] op_sel:[1,0]
	v_pk_fma_f32 v[52:53], v[36:37], v[58:59], v[34:35] op_sel_hi:[0,1,1]
	v_pk_fma_f32 v[22:23], v[22:23], v[54:55], v[62:63] op_sel_hi:[0,1,1]
	v_mov_b32_e32 v62, v25
	v_pk_mul_f32 v[34:35], v[30:31], v[50:51] op_sel:[1,0]
	v_pk_mul_f32 v[62:63], v[62:63], v[52:53] op_sel_hi:[0,1]
	v_pk_fma_f32 v[30:31], v[30:31], v[54:55], v[34:35] op_sel_hi:[0,1,1]
	v_mov_b32_e32 v34, v33
	v_pk_fma_f32 v[24:25], v[24:25], v[56:57], v[62:63] op_sel_hi:[0,1,1]
	v_pk_mul_f32 v[34:35], v[34:35], v[52:53] op_sel_hi:[0,1]
	v_pk_add_f32 v[22:23], v[22:23], v[24:25]
	v_pk_fma_f32 v[32:33], v[32:33], v[56:57], v[34:35] op_sel_hi:[0,1,1]
	s_nop 1
	v_add_f32_dpp v22, v22, v22 quad_perm:[1,0,3,2] row_mask:0xf bank_mask:0xf bound_ctrl:1
	v_add_f32_dpp v23, v23, v23 quad_perm:[1,0,3,2] row_mask:0xf bank_mask:0xf bound_ctrl:1
	v_pk_add_f32 v[30:31], v[30:31], v[32:33]
	s_nop 1
	v_add_f32_dpp v22, v22, v22 quad_perm:[2,3,0,1] row_mask:0xf bank_mask:0xf bound_ctrl:1
	v_add_f32_dpp v23, v23, v23 quad_perm:[2,3,0,1] row_mask:0xf bank_mask:0xf bound_ctrl:1
	s_nop 1
	v_add_f32_dpp v30, v30, v30 quad_perm:[1,0,3,2] row_mask:0xf bank_mask:0xf bound_ctrl:1
	v_add_f32_dpp v31, v31, v31 quad_perm:[1,0,3,2] row_mask:0xf bank_mask:0xf bound_ctrl:1
	s_nop 1
	v_add_f32_dpp v22, v22, v22 row_half_mirror row_mask:0xf bank_mask:0xf bound_ctrl:1
	v_add_f32_dpp v23, v23, v23 row_half_mirror row_mask:0xf bank_mask:0xf bound_ctrl:1
	s_nop 1
	v_add_f32_dpp v30, v30, v30 quad_perm:[2,3,0,1] row_mask:0xf bank_mask:0xf bound_ctrl:1
	v_add_f32_dpp v31, v31, v31 quad_perm:[2,3,0,1] row_mask:0xf bank_mask:0xf bound_ctrl:1
	s_nop 1
	v_add_f32_dpp v22, v22, v22 row_mirror row_mask:0xf bank_mask:0xf bound_ctrl:1
	v_add_f32_dpp v23, v23, v23 row_mirror row_mask:0xf bank_mask:0xf bound_ctrl:1
	s_waitcnt lgkmcnt(1)
	v_pk_mul_f32 v[24:25], v[26:27], v[22:23] op_sel_hi:[0,1]
	s_nop 1
	v_add_f32_dpp v30, v30, v30 row_half_mirror row_mask:0xf bank_mask:0xf bound_ctrl:1
	v_add_f32_dpp v31, v31, v31 row_half_mirror row_mask:0xf bank_mask:0xf bound_ctrl:1
	v_pk_fma_f32 v[24:25], v[6:7], v[54:55], v[24:25] op_sel_hi:[0,1,1] neg_lo:[0,0,1] neg_hi:[0,0,1]
	s_nop 1
	v_add_f32_dpp v30, v30, v30 row_mirror row_mask:0xf bank_mask:0xf bound_ctrl:1
	v_add_f32_dpp v31, v31, v31 row_mirror row_mask:0xf bank_mask:0xf bound_ctrl:1
	s_waitcnt lgkmcnt(0)
	v_pk_fma_f32 v[54:55], v[18:19], v[60:61], v[24:25] op_sel_hi:[0,1,1]
	v_cvt_pk_bf16_f32 v17, v30, v31
	v_pk_mul_f32 v[24:25], v[26:27], v[22:23] op_sel:[1,0]
	ds_write_b32 v14, v17 offset:1920
	v_pk_fma_f32 v[6:7], v[6:7], v[50:51], v[24:25] op_sel:[1,0,0] neg_lo:[0,0,1] neg_hi:[0,0,1]
	ds_read_b128 v[30:33], v15 offset:26112
	ds_read_b128 v[34:37], v15 offset:26368
	ds_read_b128 v[38:41], v15 offset:26624
	ds_read_b128 v[42:45], v15 offset:26880
	ds_read_b128 v[46:49], v15 offset:27136
	ds_read_b64 v[58:59], v16 offset:27392
	v_pk_fma_f32 v[50:51], v[18:19], v[60:61], v[6:7] op_sel:[1,0,0]
	v_pk_mul_f32 v[6:7], v[28:29], v[22:23] op_sel_hi:[0,1]
	v_pk_fma_f32 v[6:7], v[8:9], v[56:57], v[6:7] op_sel_hi:[0,1,1] neg_lo:[0,0,1] neg_hi:[0,0,1]
	v_mov_b32_e32 v8, v29
	v_pk_fma_f32 v[56:57], v[20:21], v[60:61], v[6:7] op_sel_hi:[0,1,1]
	v_mov_b32_e32 v6, v9
	v_pk_mul_f32 v[8:9], v[8:9], v[22:23] op_sel_hi:[0,1]
	v_pk_fma_f32 v[6:7], v[6:7], v[52:53], v[8:9] op_sel_hi:[0,1,1] neg_lo:[0,0,1] neg_hi:[0,0,1]
	v_mov_b32_e32 v8, v21
	s_waitcnt lgkmcnt(2)
; #define LAS __attribute__((address_space(3)))
; DI unsigned pk2(float a, float b) { f32x2 v = {a, b}; bf2_t r = __builtin_convertvector(v, bf2_t); return __builtin_bit_cast(unsigned, r); }
; #define DPP_ADD2(a, b, ctrl) asm("s_nop 1\n\tv_add_f32_dpp %0, %0, %0 " ctrl " row_mask:0xf bank_mask:0xf bound_ctrl:1\n\tv_add_f32_dpp %1, %1, %1 " ctrl " row_mask:0xf bank_mask:0xf bound_ctrl:1" : "+v"(a), "+v"(b))
; DI f32x2 red16p(f32x2 x) { float a = x.x, b = x.y; red16x2(a, b); return (f32x2){a, b}; }
; DI void red16x2(float& a, float& b) { DPP_ADD2(a, b, "quad_perm:[1,0,3,2]"); DPP_ADD2(a, b, "quad_perm:[2,3,0,1]"); DPP_ADD2(a, b, "row_half_mirror"); DPP_ADD2(a, b, "row_mirror"); }
; DI void scan_bh2(const Args& a, int l, int bh, int halfsel, LAS unsigned char* lds) {
;     ...
;             for (int st = 0; st < T; ++st) {
;                 f32x4 nr4, nd4, nk4, nkk4, nb4; f32x2 nv2;
;                 if (st < T - 1) {
;                     const LAS float* o = cur + (st + 1) * 384;
;                     nr4 = *(const LAS f32x4*)(o + kq * 4); nd4 = *(const LAS f32x4*)(o + 64 + kq * 4); nk4 = *(const LAS f32x4*)(o + 128 + kq * 4);
;                     nkk4 = *(const LAS f32x4*)(o + 192 + kq * 4); nb4 = *(const LAS f32x4*)(o + 256 + kq * 4); nv2 = *(const LAS f32x2*)(o + 320 + row0);
;                 }
;                 f32x2 sa = S[0] * kk4[0]; sa += S[1] * kk4[1]; f32x2 sb = S[2] * kk4[2]; sb += S[3] * kk4[3]; sa += sb;
;                 sa = red16p(sa); sa = -sa;
; #pragma unroll
;                 for (int j = 0; j < 4; ++j) S[j] = S[j] * d4[j] + sa * b4[j] + v2 * k4[j];
;                 f32x2 y = S[0] * r4[0]; y += S[1] * r4[1]; f32x2 yc = S[2] * r4[2]; yc += S[3] * r4[3]; y += yc;
;                 y = red16p(y);
;                 *(LAS unsigned*)(yb + st * 128 + row0 * 2) = pk2(y.x, y.y);
;                 if (st < T - 1) { r4 = nr4; d4 = nd4; k4 = nk4; kk4 = nkk4; b4 = nb4; v2 = nv2; }
;             }
	v_pk_mul_f32 v[62:63], v[42:43], v[50:51] op_sel:[1,0]
	v_pk_fma_f32 v[52:53], v[8:9], v[60:61], v[6:7] op_sel_hi:[0,1,1]
	v_pk_mul_f32 v[6:7], v[2:3], v[50:51] op_sel:[1,0]
	v_pk_fma_f32 v[42:43], v[42:43], v[54:55], v[62:63] op_sel_hi:[0,1,1]
	v_mov_b32_e32 v62, v45
	v_pk_fma_f32 v[2:3], v[2:3], v[54:55], v[6:7] op_sel_hi:[0,1,1]
	v_mov_b32_e32 v6, v5
	v_pk_mul_f32 v[62:63], v[62:63], v[52:53] op_sel_hi:[0,1]
	v_pk_mul_f32 v[6:7], v[6:7], v[52:53] op_sel_hi:[0,1]
	v_pk_fma_f32 v[44:45], v[44:45], v[56:57], v[62:63] op_sel_hi:[0,1,1]
	v_pk_fma_f32 v[4:5], v[4:5], v[56:57], v[6:7] op_sel_hi:[0,1,1]
	v_pk_add_f32 v[42:43], v[42:43], v[44:45]
	v_pk_add_f32 v[2:3], v[2:3], v[4:5]
	s_nop 1
	v_add_f32_dpp v42, v42, v42 quad_perm:[1,0,3,2] row_mask:0xf bank_mask:0xf bound_ctrl:1
	v_add_f32_dpp v43, v43, v43 quad_perm:[1,0,3,2] row_mask:0xf bank_mask:0xf bound_ctrl:1
	s_nop 1
	v_add_f32_dpp v2, v2, v2 quad_perm:[1,0,3,2] row_mask:0xf bank_mask:0xf bound_ctrl:1
	v_add_f32_dpp v3, v3, v3 quad_perm:[1,0,3,2] row_mask:0xf bank_mask:0xf bound_ctrl:1
	s_nop 1
	v_add_f32_dpp v42, v42, v42 quad_perm:[2,3,0,1] row_mask:0xf bank_mask:0xf bound_ctrl:1
	v_add_f32_dpp v43, v43, v43 quad_perm:[2,3,0,1] row_mask:0xf bank_mask:0xf bound_ctrl:1
	s_nop 1
	v_add_f32_dpp v2, v2, v2 quad_perm:[2,3,0,1] row_mask:0xf bank_mask:0xf bound_ctrl:1
	v_add_f32_dpp v3, v3, v3 quad_perm:[2,3,0,1] row_mask:0xf bank_mask:0xf bound_ctrl:1
	s_nop 1
	v_add_f32_dpp v42, v42, v42 row_half_mirror row_mask:0xf bank_mask:0xf bound_ctrl:1
	v_add_f32_dpp v43, v43, v43 row_half_mirror row_mask:0xf bank_mask:0xf bound_ctrl:1
	s_nop 1
	v_add_f32_dpp v2, v2, v2 row_half_mirror row_mask:0xf bank_mask:0xf bound_ctrl:1
	v_add_f32_dpp v3, v3, v3 row_half_mirror row_mask:0xf bank_mask:0xf bound_ctrl:1
	s_nop 1
	v_add_f32_dpp v42, v42, v42 row_mirror row_mask:0xf bank_mask:0xf bound_ctrl:1
	v_add_f32_dpp v43, v43, v43 row_mirror row_mask:0xf bank_mask:0xf bound_ctrl:1
	s_waitcnt lgkmcnt(1)
	v_pk_mul_f32 v[44:45], v[46:47], v[42:43] op_sel_hi:[0,1]
	s_nop 1
	v_add_f32_dpp v2, v2, v2 row_mirror row_mask:0xf bank_mask:0xf bound_ctrl:1
	v_add_f32_dpp v3, v3, v3 row_mirror row_mask:0xf bank_mask:0xf bound_ctrl:1
	v_pk_fma_f32 v[44:45], v[34:35], v[54:55], v[44:45] op_sel_hi:[0,1,1] neg_lo:[0,0,1] neg_hi:[0,0,1]
	v_cvt_pk_bf16_f32 v2, v2, v3
	s_waitcnt lgkmcnt(0)
	v_pk_fma_f32 v[54:55], v[38:39], v[58:59], v[44:45] op_sel_hi:[0,1,1]
	v_pk_mul_f32 v[44:45], v[46:47], v[42:43] op_sel:[1,0]
	ds_write_b32 v14, v2 offset:2048
	v_pk_fma_f32 v[34:35], v[34:35], v[50:51], v[44:45] op_sel:[1,0,0] neg_lo:[0,0,1] neg_hi:[0,0,1]
	ds_read_b128 v[2:5], v15 offset:27648
	ds_read_b128 v[6:9], v15 offset:27904
	ds_read_b128 v[18:21], v15 offset:28160
	ds_read_b128 v[22:25], v15 offset:28416
	ds_read_b128 v[26:29], v15 offset:28672
	ds_read_b64 v[60:61], v16 offset:28928
	v_pk_fma_f32 v[50:51], v[38:39], v[58:59], v[34:35] op_sel:[1,0,0]
	v_pk_mul_f32 v[34:35], v[48:49], v[42:43] op_sel_hi:[0,1]
	v_pk_fma_f32 v[34:35], v[36:37], v[56:57], v[34:35] op_sel_hi:[0,1,1] neg_lo:[0,0,1] neg_hi:[0,0,1]
	v_mov_b32_e32 v36, v49
	v_pk_fma_f32 v[56:57], v[40:41], v[58:59], v[34:35] op_sel_hi:[0,1,1]
	v_mov_b32_e32 v34, v37
	v_pk_mul_f32 v[36:37], v[36:37], v[42:43] op_sel_hi:[0,1]
	v_pk_fma_f32 v[34:35], v[34:35], v[52:53], v[36:37] op_sel_hi:[0,1,1] neg_lo:[0,0,1] neg_hi:[0,0,1]
	v_mov_b32_e32 v36, v41
	s_waitcnt lgkmcnt(2)
	v_pk_mul_f32 v[62:63], v[22:23], v[50:51] op_sel:[1,0]
	v_pk_fma_f32 v[52:53], v[36:37], v[58:59], v[34:35] op_sel_hi:[0,1,1]
	v_pk_fma_f32 v[22:23], v[22:23], v[54:55], v[62:63] op_sel_hi:[0,1,1]
	v_mov_b32_e32 v62, v25
	v_pk_mul_f32 v[34:35], v[30:31], v[50:51] op_sel:[1,0]
	v_pk_mul_f32 v[62:63], v[62:63], v[52:53] op_sel_hi:[0,1]
	v_pk_fma_f32 v[30:31], v[30:31], v[54:55], v[34:35] op_sel_hi:[0,1,1]
	v_mov_b32_e32 v34, v33
	v_pk_fma_f32 v[24:25], v[24:25], v[56:57], v[62:63] op_sel_hi:[0,1,1]
	v_pk_mul_f32 v[34:35], v[34:35], v[52:53] op_sel_hi:[0,1]
	v_pk_add_f32 v[22:23], v[22:23], v[24:25]
	v_pk_fma_f32 v[32:33], v[32:33], v[56:57], v[34:35] op_sel_hi:[0,1,1]
	s_nop 1
	v_add_f32_dpp v22, v22, v22 quad_perm:[1,0,3,2] row_mask:0xf bank_mask:0xf bound_ctrl:1
	v_add_f32_dpp v23, v23, v23 quad_perm:[1,0,3,2] row_mask:0xf bank_mask:0xf bound_ctrl:1
	v_pk_add_f32 v[30:31], v[30:31], v[32:33]
	s_nop 1
	v_add_f32_dpp v22, v22, v22 quad_perm:[2,3,0,1] row_mask:0xf bank_mask:0xf bound_ctrl:1
	v_add_f32_dpp v23, v23, v23 quad_perm:[2,3,0,1] row_mask:0xf bank_mask:0xf bound_ctrl:1
	s_nop 1
	v_add_f32_dpp v30, v30, v30 quad_perm:[1,0,3,2] row_mask:0xf bank_mask:0xf bound_ctrl:1
	v_add_f32_dpp v31, v31, v31 quad_perm:[1,0,3,2] row_mask:0xf bank_mask:0xf bound_ctrl:1
	s_nop 1
	v_add_f32_dpp v22, v22, v22 row_half_mirror row_mask:0xf bank_mask:0xf bound_ctrl:1
	v_add_f32_dpp v23, v23, v23 row_half_mirror row_mask:0xf bank_mask:0xf bound_ctrl:1
	s_nop 1
	v_add_f32_dpp v30, v30, v30 quad_perm:[2,3,0,1] row_mask:0xf bank_mask:0xf bound_ctrl:1
	v_add_f32_dpp v31, v31, v31 quad_perm:[2,3,0,1] row_mask:0xf bank_mask:0xf bound_ctrl:1
	s_nop 1
	v_add_f32_dpp v22, v22, v22 row_mirror row_mask:0xf bank_mask:0xf bound_ctrl:1
	v_add_f32_dpp v23, v23, v23 row_mirror row_mask:0xf bank_mask:0xf bound_ctrl:1
	s_waitcnt lgkmcnt(1)
	v_pk_mul_f32 v[24:25], v[26:27], v[22:23] op_sel_hi:[0,1]
	s_nop 1
	v_add_f32_dpp v30, v30, v30 row_half_mirror row_mask:0xf bank_mask:0xf bound_ctrl:1
	v_add_f32_dpp v31, v31, v31 row_half_mirror row_mask:0xf bank_mask:0xf bound_ctrl:1
	v_pk_fma_f32 v[24:25], v[6:7], v[54:55], v[24:25] op_sel_hi:[0,1,1] neg_lo:[0,0,1] neg_hi:[0,0,1]
	s_nop 1
	v_add_f32_dpp v30, v30, v30 row_mirror row_mask:0xf bank_mask:0xf bound_ctrl:1
	v_add_f32_dpp v31, v31, v31 row_mirror row_mask:0xf bank_mask:0xf bound_ctrl:1
	s_waitcnt lgkmcnt(0)
; #define LAS __attribute__((address_space(3)))
; DI unsigned pk2(float a, float b) { f32x2 v = {a, b}; bf2_t r = __builtin_convertvector(v, bf2_t); return __builtin_bit_cast(unsigned, r); }
; #define DPP_ADD2(a, b, ctrl) asm("s_nop 1\n\tv_add_f32_dpp %0, %0, %0 " ctrl " row_mask:0xf bank_mask:0xf bound_ctrl:1\n\tv_add_f32_dpp %1, %1, %1 " ctrl " row_mask:0xf bank_mask:0xf bound_ctrl:1" : "+v"(a), "+v"(b))
; DI f32x2 red16p(f32x2 x) { float a = x.x, b = x.y; red16x2(a, b); return (f32x2){a, b}; }
; DI void red16x2(float& a, float& b) { DPP_ADD2(a, b, "quad_perm:[1,0,3,2]"); DPP_ADD2(a, b, "quad_perm:[2,3,0,1]"); DPP_ADD2(a, b, "row_half_mirror"); DPP_ADD2(a, b, "row_mirror"); }
; DI void scan_bh2(const Args& a, int l, int bh, int halfsel, LAS unsigned char* lds) {
;     ...
;             for (int st = 0; st < T; ++st) {
;                 f32x4 nr4, nd4, nk4, nkk4, nb4; f32x2 nv2;
;                 if (st < T - 1) {
;                     const LAS float* o = cur + (st + 1) * 384;
;                     nr4 = *(const LAS f32x4*)(o + kq * 4); nd4 = *(const LAS f32x4*)(o + 64 + kq * 4); nk4 = *(const LAS f32x4*)(o + 128 + kq * 4);
;                     nkk4 = *(const LAS f32x4*)(o + 192 + kq * 4); nb4 = *(const LAS f32x4*)(o + 256 + kq * 4); nv2 = *(const LAS f32x2*)(o + 320 + row0);
;                 }
;                 f32x2 sa = S[0] * kk4[0]; sa += S[1] * kk4[1]; f32x2 sb = S[2] * kk4[2]; sb += S[3] * kk4[3]; sa += sb;
;                 sa = red16p(sa); sa = -sa;
; #pragma unroll
;                 for (int j = 0; j < 4; ++j) S[j] = S[j] * d4[j] + sa * b4[j] + v2 * k4[j];
;                 f32x2 y = S[0] * r4[0]; y += S[1] * r4[1]; f32x2 yc = S[2] * r4[2]; yc += S[3] * r4[3]; y += yc;
;                 y = red16p(y);
;                 *(LAS unsigned*)(yb + st * 128 + row0 * 2) = pk2(y.x, y.y);
;                 if (st < T - 1) { r4 = nr4; d4 = nd4; k4 = nk4; kk4 = nkk4; b4 = nb4; v2 = nv2; }
;             }
	v_pk_fma_f32 v[54:55], v[18:19], v[60:61], v[24:25] op_sel_hi:[0,1,1]
	v_cvt_pk_bf16_f32 v17, v30, v31
	v_pk_mul_f32 v[24:25], v[26:27], v[22:23] op_sel:[1,0]
	ds_write_b32 v14, v17 offset:2176
	v_pk_fma_f32 v[6:7], v[6:7], v[50:51], v[24:25] op_sel:[1,0,0] neg_lo:[0,0,1] neg_hi:[0,0,1]
	ds_read_b128 v[30:33], v15 offset:29184
	ds_read_b128 v[34:37], v15 offset:29440
	ds_read_b128 v[38:41], v15 offset:29696
	ds_read_b128 v[42:45], v15 offset:29952
	ds_read_b128 v[46:49], v15 offset:30208
	ds_read_b64 v[58:59], v16 offset:30464
	v_pk_fma_f32 v[50:51], v[18:19], v[60:61], v[6:7] op_sel:[1,0,0]
	v_pk_mul_f32 v[6:7], v[28:29], v[22:23] op_sel_hi:[0,1]
	v_pk_fma_f32 v[6:7], v[8:9], v[56:57], v[6:7] op_sel_hi:[0,1,1] neg_lo:[0,0,1] neg_hi:[0,0,1]
	v_mov_b32_e32 v8, v29
	v_pk_fma_f32 v[56:57], v[20:21], v[60:61], v[6:7] op_sel_hi:[0,1,1]
	v_mov_b32_e32 v6, v9
	v_pk_mul_f32 v[8:9], v[8:9], v[22:23] op_sel_hi:[0,1]
	v_pk_fma_f32 v[6:7], v[6:7], v[52:53], v[8:9] op_sel_hi:[0,1,1] neg_lo:[0,0,1] neg_hi:[0,0,1]
	v_mov_b32_e32 v8, v21
	s_waitcnt lgkmcnt(2)
	v_pk_mul_f32 v[62:63], v[42:43], v[50:51] op_sel:[1,0]
	v_pk_fma_f32 v[52:53], v[8:9], v[60:61], v[6:7] op_sel_hi:[0,1,1]
	v_pk_mul_f32 v[6:7], v[2:3], v[50:51] op_sel:[1,0]
	v_pk_fma_f32 v[42:43], v[42:43], v[54:55], v[62:63] op_sel_hi:[0,1,1]
	v_mov_b32_e32 v62, v45
	v_pk_fma_f32 v[2:3], v[2:3], v[54:55], v[6:7] op_sel_hi:[0,1,1]
	v_mov_b32_e32 v6, v5
	v_pk_mul_f32 v[62:63], v[62:63], v[52:53] op_sel_hi:[0,1]
	v_pk_mul_f32 v[6:7], v[6:7], v[52:53] op_sel_hi:[0,1]
	v_pk_fma_f32 v[44:45], v[44:45], v[56:57], v[62:63] op_sel_hi:[0,1,1]
	v_pk_fma_f32 v[4:5], v[4:5], v[56:57], v[6:7] op_sel_hi:[0,1,1]
	v_pk_add_f32 v[42:43], v[42:43], v[44:45]
	v_pk_add_f32 v[2:3], v[2:3], v[4:5]
	s_nop 1
	v_add_f32_dpp v42, v42, v42 quad_perm:[1,0,3,2] row_mask:0xf bank_mask:0xf bound_ctrl:1
	v_add_f32_dpp v43, v43, v43 quad_perm:[1,0,3,2] row_mask:0xf bank_mask:0xf bound_ctrl:1
	s_nop 1
	v_add_f32_dpp v2, v2, v2 quad_perm:[1,0,3,2] row_mask:0xf bank_mask:0xf bound_ctrl:1
	v_add_f32_dpp v3, v3, v3 quad_perm:[1,0,3,2] row_mask:0xf bank_mask:0xf bound_ctrl:1
	s_nop 1
	v_add_f32_dpp v42, v42, v42 quad_perm:[2,3,0,1] row_mask:0xf bank_mask:0xf bound_ctrl:1
	v_add_f32_dpp v43, v43, v43 quad_perm:[2,3,0,1] row_mask:0xf bank_mask:0xf bound_ctrl:1
	s_nop 1
	v_add_f32_dpp v2, v2, v2 quad_perm:[2,3,0,1] row_mask:0xf bank_mask:0xf bound_ctrl:1
	v_add_f32_dpp v3, v3, v3 quad_perm:[2,3,0,1] row_mask:0xf bank_mask:0xf bound_ctrl:1
	s_nop 1
	v_add_f32_dpp v42, v42, v42 row_half_mirror row_mask:0xf bank_mask:0xf bound_ctrl:1
	v_add_f32_dpp v43, v43, v43 row_half_mirror row_mask:0xf bank_mask:0xf bound_ctrl:1
	s_nop 1
	v_add_f32_dpp v2, v2, v2 row_half_mirror row_mask:0xf bank_mask:0xf bound_ctrl:1
	v_add_f32_dpp v3, v3, v3 row_half_mirror row_mask:0xf bank_mask:0xf bound_ctrl:1
	s_nop 1
	v_add_f32_dpp v42, v42, v42 row_mirror row_mask:0xf bank_mask:0xf bound_ctrl:1
	v_add_f32_dpp v43, v43, v43 row_mirror row_mask:0xf bank_mask:0xf bound_ctrl:1
	s_waitcnt lgkmcnt(1)
	v_pk_mul_f32 v[44:45], v[46:47], v[42:43] op_sel_hi:[0,1]
	s_nop 1
	v_add_f32_dpp v2, v2, v2 row_mirror row_mask:0xf bank_mask:0xf bound_ctrl:1
	v_add_f32_dpp v3, v3, v3 row_mirror row_mask:0xf bank_mask:0xf bound_ctrl:1
	v_pk_fma_f32 v[44:45], v[34:35], v[54:55], v[44:45] op_sel_hi:[0,1,1] neg_lo:[0,0,1] neg_hi:[0,0,1]
	v_cvt_pk_bf16_f32 v2, v2, v3
	s_waitcnt lgkmcnt(0)
	v_pk_fma_f32 v[54:55], v[38:39], v[58:59], v[44:45] op_sel_hi:[0,1,1]
	v_pk_mul_f32 v[44:45], v[46:47], v[42:43] op_sel:[1,0]
	ds_write_b32 v14, v2 offset:2304
	v_pk_fma_f32 v[34:35], v[34:35], v[50:51], v[44:45] op_sel:[1,0,0] neg_lo:[0,0,1] neg_hi:[0,0,1]
	ds_read_b128 v[2:5], v15 offset:30720
	ds_read_b128 v[6:9], v15 offset:30976
	ds_read_b128 v[18:21], v15 offset:31232
	ds_read_b128 v[22:25], v15 offset:31488
	ds_read_b128 v[26:29], v15 offset:31744
	ds_read_b64 v[60:61], v16 offset:32000
	v_pk_fma_f32 v[50:51], v[38:39], v[58:59], v[34:35] op_sel:[1,0,0]
	v_pk_mul_f32 v[34:35], v[48:49], v[42:43] op_sel_hi:[0,1]
	v_pk_fma_f32 v[34:35], v[36:37], v[56:57], v[34:35] op_sel_hi:[0,1,1] neg_lo:[0,0,1] neg_hi:[0,0,1]
	v_mov_b32_e32 v36, v49
	v_pk_fma_f32 v[56:57], v[40:41], v[58:59], v[34:35] op_sel_hi:[0,1,1]
	v_mov_b32_e32 v34, v37
	v_pk_mul_f32 v[36:37], v[36:37], v[42:43] op_sel_hi:[0,1]
	v_pk_fma_f32 v[34:35], v[34:35], v[52:53], v[36:37] op_sel_hi:[0,1,1] neg_lo:[0,0,1] neg_hi:[0,0,1]
	v_mov_b32_e32 v36, v41
	s_waitcnt lgkmcnt(2)
	v_pk_mul_f32 v[62:63], v[22:23], v[50:51] op_sel:[1,0]
	v_pk_fma_f32 v[52:53], v[36:37], v[58:59], v[34:35] op_sel_hi:[0,1,1]
	v_pk_fma_f32 v[22:23], v[22:23], v[54:55], v[62:63] op_sel_hi:[0,1,1]
	v_mov_b32_e32 v62, v25
	v_pk_mul_f32 v[62:63], v[62:63], v[52:53] op_sel_hi:[0,1]
	v_pk_fma_f32 v[24:25], v[24:25], v[56:57], v[62:63] op_sel_hi:[0,1,1]
	v_pk_mul_f32 v[34:35], v[30:31], v[50:51] op_sel:[1,0]
	v_pk_add_f32 v[22:23], v[22:23], v[24:25]
	v_pk_fma_f32 v[30:31], v[30:31], v[54:55], v[34:35] op_sel_hi:[0,1,1]
	v_mov_b32_e32 v34, v33
	s_nop 1
	v_add_f32_dpp v22, v22, v22 quad_perm:[1,0,3,2] row_mask:0xf bank_mask:0xf bound_ctrl:1
	v_add_f32_dpp v23, v23, v23 quad_perm:[1,0,3,2] row_mask:0xf bank_mask:0xf bound_ctrl:1
	v_pk_mul_f32 v[34:35], v[34:35], v[52:53] op_sel_hi:[0,1]
	s_nop 1
	v_add_f32_dpp v22, v22, v22 quad_perm:[2,3,0,1] row_mask:0xf bank_mask:0xf bound_ctrl:1
	v_add_f32_dpp v23, v23, v23 quad_perm:[2,3,0,1] row_mask:0xf bank_mask:0xf bound_ctrl:1
	v_pk_fma_f32 v[32:33], v[32:33], v[56:57], v[34:35] op_sel_hi:[0,1,1]
	s_nop 1
	v_add_f32_dpp v22, v22, v22 row_half_mirror row_mask:0xf bank_mask:0xf bound_ctrl:1
	v_add_f32_dpp v23, v23, v23 row_half_mirror row_mask:0xf bank_mask:0xf bound_ctrl:1
	v_pk_add_f32 v[30:31], v[30:31], v[32:33]
	s_nop 1
	v_add_f32_dpp v22, v22, v22 row_mirror row_mask:0xf bank_mask:0xf bound_ctrl:1
	v_add_f32_dpp v23, v23, v23 row_mirror row_mask:0xf bank_mask:0xf bound_ctrl:1
	s_waitcnt lgkmcnt(1)
; #define LAS __attribute__((address_space(3)))
; DI unsigned pk2(float a, float b) { f32x2 v = {a, b}; bf2_t r = __builtin_convertvector(v, bf2_t); return __builtin_bit_cast(unsigned, r); }
; #define DPP_ADD2(a, b, ctrl) asm("s_nop 1\n\tv_add_f32_dpp %0, %0, %0 " ctrl " row_mask:0xf bank_mask:0xf bound_ctrl:1\n\tv_add_f32_dpp %1, %1, %1 " ctrl " row_mask:0xf bank_mask:0xf bound_ctrl:1" : "+v"(a), "+v"(b))
; DI f32x2 red16p(f32x2 x) { float a = x.x, b = x.y; red16x2(a, b); return (f32x2){a, b}; }
; DI void red16x2(float& a, float& b) { DPP_ADD2(a, b, "quad_perm:[1,0,3,2]"); DPP_ADD2(a, b, "quad_perm:[2,3,0,1]"); DPP_ADD2(a, b, "row_half_mirror"); DPP_ADD2(a, b, "row_mirror"); }
; DI void scan_bh2(const Args& a, int l, int bh, int halfsel, LAS unsigned char* lds) {
;     ...
;             for (int st = 0; st < T; ++st) {
;                 f32x4 nr4, nd4, nk4, nkk4, nb4; f32x2 nv2;
;                 if (st < T - 1) {
;                     const LAS float* o = cur + (st + 1) * 384;
;                     nr4 = *(const LAS f32x4*)(o + kq * 4); nd4 = *(const LAS f32x4*)(o + 64 + kq * 4); nk4 = *(const LAS f32x4*)(o + 128 + kq * 4);
;                     nkk4 = *(const LAS f32x4*)(o + 192 + kq * 4); nb4 = *(const LAS f32x4*)(o + 256 + kq * 4); nv2 = *(const LAS f32x2*)(o + 320 + row0);
;                 }
;                 f32x2 sa = S[0] * kk4[0]; sa += S[1] * kk4[1]; f32x2 sb = S[2] * kk4[2]; sb += S[3] * kk4[3]; sa += sb;
;                 sa = red16p(sa); sa = -sa;
; #pragma unroll
;                 for (int j = 0; j < 4; ++j) S[j] = S[j] * d4[j] + sa * b4[j] + v2 * k4[j];
;                 f32x2 y = S[0] * r4[0]; y += S[1] * r4[1]; f32x2 yc = S[2] * r4[2]; yc += S[3] * r4[3]; y += yc;
;                 y = red16p(y);
;                 *(LAS unsigned*)(yb + st * 128 + row0 * 2) = pk2(y.x, y.y);
;                 if (st < T - 1) { r4 = nr4; d4 = nd4; k4 = nk4; kk4 = nkk4; b4 = nb4; v2 = nv2; }
;             }
	v_pk_mul_f32 v[24:25], v[26:27], v[22:23] op_sel_hi:[0,1]
	s_nop 1
	v_add_f32_dpp v30, v30, v30 quad_perm:[1,0,3,2] row_mask:0xf bank_mask:0xf bound_ctrl:1
	v_add_f32_dpp v31, v31, v31 quad_perm:[1,0,3,2] row_mask:0xf bank_mask:0xf bound_ctrl:1
	v_pk_fma_f32 v[24:25], v[6:7], v[54:55], v[24:25] op_sel_hi:[0,1,1] neg_lo:[0,0,1] neg_hi:[0,0,1]
	s_nop 1
	v_add_f32_dpp v30, v30, v30 quad_perm:[2,3,0,1] row_mask:0xf bank_mask:0xf bound_ctrl:1
	v_add_f32_dpp v31, v31, v31 quad_perm:[2,3,0,1] row_mask:0xf bank_mask:0xf bound_ctrl:1
	s_waitcnt lgkmcnt(0)
	v_pk_fma_f32 v[54:55], v[18:19], v[60:61], v[24:25] op_sel_hi:[0,1,1]
	v_pk_mul_f32 v[24:25], v[26:27], v[22:23] op_sel:[1,0]
	s_nop 1
	v_add_f32_dpp v30, v30, v30 row_half_mirror row_mask:0xf bank_mask:0xf bound_ctrl:1
	v_add_f32_dpp v31, v31, v31 row_half_mirror row_mask:0xf bank_mask:0xf bound_ctrl:1
	s_nop 0
	v_pk_fma_f32 v[6:7], v[6:7], v[50:51], v[24:25] op_sel:[1,0,0] neg_lo:[0,0,1] neg_hi:[0,0,1]
	s_nop 1
	v_add_f32_dpp v30, v30, v30 row_mirror row_mask:0xf bank_mask:0xf bound_ctrl:1
	v_add_f32_dpp v31, v31, v31 row_mirror row_mask:0xf bank_mask:0xf bound_ctrl:1
	s_nop 0
	v_cvt_pk_bf16_f32 v17, v30, v31
	v_pk_fma_f32 v[50:51], v[18:19], v[60:61], v[6:7] op_sel:[1,0,0]
	v_pk_mul_f32 v[6:7], v[28:29], v[22:23] op_sel_hi:[0,1]
	ds_write_b32 v14, v17 offset:2432
	v_pk_fma_f32 v[6:7], v[8:9], v[56:57], v[6:7] op_sel_hi:[0,1,1] neg_lo:[0,0,1] neg_hi:[0,0,1]
	v_mov_b32_e32 v8, v29
	ds_read_b128 v[30:33], v15 offset:32768
	ds_read_b128 v[34:37], v15 offset:33024
	ds_read_b128 v[38:41], v15 offset:32256
	ds_read_b128 v[42:45], v15 offset:33280
	ds_read_b128 v[46:49], v15 offset:32512
	ds_read_b64 v[58:59], v16 offset:33536
	v_pk_fma_f32 v[56:57], v[20:21], v[60:61], v[6:7] op_sel_hi:[0,1,1]
	v_mov_b32_e32 v6, v9
	v_pk_mul_f32 v[8:9], v[8:9], v[22:23] op_sel_hi:[0,1]
	v_pk_fma_f32 v[6:7], v[6:7], v[52:53], v[8:9] op_sel_hi:[0,1,1] neg_lo:[0,0,1] neg_hi:[0,0,1]
	v_mov_b32_e32 v8, v21
	s_waitcnt lgkmcnt(4)
	v_pk_mul_f32 v[62:63], v[34:35], v[50:51] op_sel:[1,0]
	v_pk_fma_f32 v[52:53], v[8:9], v[60:61], v[6:7] op_sel_hi:[0,1,1]
	v_pk_fma_f32 v[34:35], v[34:35], v[54:55], v[62:63] op_sel_hi:[0,1,1]
	v_mov_b32_e32 v62, v37
	v_pk_mul_f32 v[6:7], v[2:3], v[50:51] op_sel:[1,0]
	v_pk_mul_f32 v[62:63], v[62:63], v[52:53] op_sel_hi:[0,1]
	v_pk_fma_f32 v[2:3], v[2:3], v[54:55], v[6:7] op_sel_hi:[0,1,1]
	v_mov_b32_e32 v6, v5
	v_pk_fma_f32 v[36:37], v[36:37], v[56:57], v[62:63] op_sel_hi:[0,1,1]
	v_pk_mul_f32 v[6:7], v[6:7], v[52:53] op_sel_hi:[0,1]
	v_pk_add_f32 v[34:35], v[34:35], v[36:37]
	v_pk_fma_f32 v[4:5], v[4:5], v[56:57], v[6:7] op_sel_hi:[0,1,1]
	s_nop 1
	v_add_f32_dpp v34, v34, v34 quad_perm:[1,0,3,2] row_mask:0xf bank_mask:0xf bound_ctrl:1
	v_add_f32_dpp v35, v35, v35 quad_perm:[1,0,3,2] row_mask:0xf bank_mask:0xf bound_ctrl:1
	v_pk_add_f32 v[2:3], v[2:3], v[4:5]
	s_nop 1
	v_add_f32_dpp v34, v34, v34 quad_perm:[2,3,0,1] row_mask:0xf bank_mask:0xf bound_ctrl:1
	v_add_f32_dpp v35, v35, v35 quad_perm:[2,3,0,1] row_mask:0xf bank_mask:0xf bound_ctrl:1
	s_nop 1
	v_add_f32_dpp v2, v2, v2 quad_perm:[1,0,3,2] row_mask:0xf bank_mask:0xf bound_ctrl:1
	v_add_f32_dpp v3, v3, v3 quad_perm:[1,0,3,2] row_mask:0xf bank_mask:0xf bound_ctrl:1
	s_nop 1
	v_add_f32_dpp v34, v34, v34 row_half_mirror row_mask:0xf bank_mask:0xf bound_ctrl:1
	v_add_f32_dpp v35, v35, v35 row_half_mirror row_mask:0xf bank_mask:0xf bound_ctrl:1
	s_nop 1
	v_add_f32_dpp v2, v2, v2 quad_perm:[2,3,0,1] row_mask:0xf bank_mask:0xf bound_ctrl:1
	v_add_f32_dpp v3, v3, v3 quad_perm:[2,3,0,1] row_mask:0xf bank_mask:0xf bound_ctrl:1
	s_nop 1
	v_add_f32_dpp v34, v34, v34 row_mirror row_mask:0xf bank_mask:0xf bound_ctrl:1
	v_add_f32_dpp v35, v35, v35 row_mirror row_mask:0xf bank_mask:0xf bound_ctrl:1
	s_waitcnt lgkmcnt(2)
	v_pk_mul_f32 v[36:37], v[42:43], v[34:35] op_sel_hi:[0,1]
	s_nop 1
	v_add_f32_dpp v2, v2, v2 row_half_mirror row_mask:0xf bank_mask:0xf bound_ctrl:1
	v_add_f32_dpp v3, v3, v3 row_half_mirror row_mask:0xf bank_mask:0xf bound_ctrl:1
	s_waitcnt lgkmcnt(1)
	v_pk_fma_f32 v[36:37], v[46:47], v[54:55], v[36:37] op_sel_hi:[0,1,1] neg_lo:[0,0,1] neg_hi:[0,0,1]
	s_nop 1
	v_add_f32_dpp v2, v2, v2 row_mirror row_mask:0xf bank_mask:0xf bound_ctrl:1
	v_add_f32_dpp v3, v3, v3 row_mirror row_mask:0xf bank_mask:0xf bound_ctrl:1
	s_waitcnt lgkmcnt(0)
	v_pk_fma_f32 v[54:55], v[30:31], v[58:59], v[36:37] op_sel_hi:[0,1,1]
	v_pk_mul_f32 v[36:37], v[42:43], v[34:35] op_sel:[1,0]
	v_cvt_pk_bf16_f32 v2, v2, v3
	v_pk_fma_f32 v[36:37], v[46:47], v[50:51], v[36:37] op_sel:[1,0,0] neg_lo:[0,0,1] neg_hi:[0,0,1]
	ds_write_b32 v14, v2 offset:2560
	v_pk_fma_f32 v[50:51], v[30:31], v[58:59], v[36:37] op_sel:[1,0,0]
	v_pk_mul_f32 v[30:31], v[44:45], v[34:35] op_sel_hi:[0,1]
	ds_read_b128 v[2:5], v15 offset:33792
	ds_read_b128 v[6:9], v15 offset:34048
	ds_read_b128 v[18:21], v15 offset:34304
	ds_read_b128 v[22:25], v15 offset:34560
	ds_read_b128 v[26:29], v15 offset:34816
	ds_read_b64 v[60:61], v16 offset:35072
	v_pk_fma_f32 v[30:31], v[48:49], v[56:57], v[30:31] op_sel_hi:[0,1,1] neg_lo:[0,0,1] neg_hi:[0,0,1]
	v_pk_fma_f32 v[56:57], v[32:33], v[58:59], v[30:31] op_sel_hi:[0,1,1]
	v_mov_b32_e32 v32, v45
	v_mov_b32_e32 v30, v49
	v_pk_mul_f32 v[34:35], v[32:33], v[34:35] op_sel_hi:[0,1]
	v_pk_fma_f32 v[30:31], v[30:31], v[52:53], v[34:35] op_sel_hi:[0,1,1] neg_lo:[0,0,1] neg_hi:[0,0,1]
	v_mov_b32_e32 v32, v33
	s_waitcnt lgkmcnt(2)
; #define LAS __attribute__((address_space(3)))
; DI unsigned pk2(float a, float b) { f32x2 v = {a, b}; bf2_t r = __builtin_convertvector(v, bf2_t); return __builtin_bit_cast(unsigned, r); }
; #define DPP_ADD2(a, b, ctrl) asm("s_nop 1\n\tv_add_f32_dpp %0, %0, %0 " ctrl " row_mask:0xf bank_mask:0xf bound_ctrl:1\n\tv_add_f32_dpp %1, %1, %1 " ctrl " row_mask:0xf bank_mask:0xf bound_ctrl:1" : "+v"(a), "+v"(b))
; DI f32x2 red16p(f32x2 x) { float a = x.x, b = x.y; red16x2(a, b); return (f32x2){a, b}; }
; DI void red16x2(float& a, float& b) { DPP_ADD2(a, b, "quad_perm:[1,0,3,2]"); DPP_ADD2(a, b, "quad_perm:[2,3,0,1]"); DPP_ADD2(a, b, "row_half_mirror"); DPP_ADD2(a, b, "row_mirror"); }
; DI void scan_bh2(const Args& a, int l, int bh, int halfsel, LAS unsigned char* lds) {
;     ...
;             for (int st = 0; st < T; ++st) {
;                 f32x4 nr4, nd4, nk4, nkk4, nb4; f32x2 nv2;
;                 if (st < T - 1) {
;                     const LAS float* o = cur + (st + 1) * 384;
;                     nr4 = *(const LAS f32x4*)(o + kq * 4); nd4 = *(const LAS f32x4*)(o + 64 + kq * 4); nk4 = *(const LAS f32x4*)(o + 128 + kq * 4);
;                     nkk4 = *(const LAS f32x4*)(o + 192 + kq * 4); nb4 = *(const LAS f32x4*)(o + 256 + kq * 4); nv2 = *(const LAS f32x2*)(o + 320 + row0);
;                 }
;                 f32x2 sa = S[0] * kk4[0]; sa += S[1] * kk4[1]; f32x2 sb = S[2] * kk4[2]; sb += S[3] * kk4[3]; sa += sb;
;                 sa = red16p(sa); sa = -sa;
; #pragma unroll
;                 for (int j = 0; j < 4; ++j) S[j] = S[j] * d4[j] + sa * b4[j] + v2 * k4[j];
;                 f32x2 y = S[0] * r4[0]; y += S[1] * r4[1]; f32x2 yc = S[2] * r4[2]; yc += S[3] * r4[3]; y += yc;
;                 y = red16p(y);
;                 *(LAS unsigned*)(yb + st * 128 + row0 * 2) = pk2(y.x, y.y);
;                 if (st < T - 1) { r4 = nr4; d4 = nd4; k4 = nk4; kk4 = nkk4; b4 = nb4; v2 = nv2; }
;             }
	v_pk_mul_f32 v[62:63], v[22:23], v[50:51] op_sel:[1,0]
	v_pk_fma_f32 v[52:53], v[32:33], v[58:59], v[30:31] op_sel_hi:[0,1,1]
	v_pk_fma_f32 v[22:23], v[22:23], v[54:55], v[62:63] op_sel_hi:[0,1,1]
	v_mov_b32_e32 v62, v25
	v_pk_mul_f32 v[62:63], v[62:63], v[52:53] op_sel_hi:[0,1]
	v_mov_b32_e32 v32, v41
	v_pk_fma_f32 v[24:25], v[24:25], v[56:57], v[62:63] op_sel_hi:[0,1,1]
	v_pk_mul_f32 v[30:31], v[38:39], v[50:51] op_sel:[1,0]
	v_pk_mul_f32 v[32:33], v[32:33], v[52:53] op_sel_hi:[0,1]
	v_pk_add_f32 v[22:23], v[22:23], v[24:25]
	v_pk_fma_f32 v[30:31], v[38:39], v[54:55], v[30:31] op_sel_hi:[0,1,1]
	v_pk_fma_f32 v[32:33], v[40:41], v[56:57], v[32:33] op_sel_hi:[0,1,1]
	s_nop 1
	v_add_f32_dpp v22, v22, v22 quad_perm:[1,0,3,2] row_mask:0xf bank_mask:0xf bound_ctrl:1
	v_add_f32_dpp v23, v23, v23 quad_perm:[1,0,3,2] row_mask:0xf bank_mask:0xf bound_ctrl:1
	v_pk_add_f32 v[30:31], v[30:31], v[32:33]
	s_nop 1
	v_add_f32_dpp v22, v22, v22 quad_perm:[2,3,0,1] row_mask:0xf bank_mask:0xf bound_ctrl:1
	v_add_f32_dpp v23, v23, v23 quad_perm:[2,3,0,1] row_mask:0xf bank_mask:0xf bound_ctrl:1
	s_nop 1
	v_add_f32_dpp v30, v30, v30 quad_perm:[1,0,3,2] row_mask:0xf bank_mask:0xf bound_ctrl:1
	v_add_f32_dpp v31, v31, v31 quad_perm:[1,0,3,2] row_mask:0xf bank_mask:0xf bound_ctrl:1
	s_nop 1
	v_add_f32_dpp v22, v22, v22 row_half_mirror row_mask:0xf bank_mask:0xf bound_ctrl:1
	v_add_f32_dpp v23, v23, v23 row_half_mirror row_mask:0xf bank_mask:0xf bound_ctrl:1
	s_nop 1
	v_add_f32_dpp v30, v30, v30 quad_perm:[2,3,0,1] row_mask:0xf bank_mask:0xf bound_ctrl:1
	v_add_f32_dpp v31, v31, v31 quad_perm:[2,3,0,1] row_mask:0xf bank_mask:0xf bound_ctrl:1
	s_nop 1
	v_add_f32_dpp v22, v22, v22 row_mirror row_mask:0xf bank_mask:0xf bound_ctrl:1
	v_add_f32_dpp v23, v23, v23 row_mirror row_mask:0xf bank_mask:0xf bound_ctrl:1
	s_waitcnt lgkmcnt(1)
	v_pk_mul_f32 v[24:25], v[26:27], v[22:23] op_sel_hi:[0,1]
	s_nop 1
	v_add_f32_dpp v30, v30, v30 row_half_mirror row_mask:0xf bank_mask:0xf bound_ctrl:1
	v_add_f32_dpp v31, v31, v31 row_half_mirror row_mask:0xf bank_mask:0xf bound_ctrl:1
	v_pk_fma_f32 v[24:25], v[6:7], v[54:55], v[24:25] op_sel_hi:[0,1,1] neg_lo:[0,0,1] neg_hi:[0,0,1]
	s_nop 1
	v_add_f32_dpp v30, v30, v30 row_mirror row_mask:0xf bank_mask:0xf bound_ctrl:1
	v_add_f32_dpp v31, v31, v31 row_mirror row_mask:0xf bank_mask:0xf bound_ctrl:1
	s_waitcnt lgkmcnt(0)
	v_pk_fma_f32 v[54:55], v[18:19], v[60:61], v[24:25] op_sel_hi:[0,1,1]
	v_cvt_pk_bf16_f32 v17, v30, v31
	v_pk_mul_f32 v[24:25], v[26:27], v[22:23] op_sel:[1,0]
	ds_write_b32 v14, v17 offset:2688
	v_pk_fma_f32 v[6:7], v[6:7], v[50:51], v[24:25] op_sel:[1,0,0] neg_lo:[0,0,1] neg_hi:[0,0,1]
	ds_read_b128 v[30:33], v15 offset:35328
	ds_read_b128 v[34:37], v15 offset:35584
	ds_read_b128 v[38:41], v15 offset:35840
	ds_read_b128 v[42:45], v15 offset:36096
	ds_read_b128 v[46:49], v15 offset:36352
	ds_read_b64 v[58:59], v16 offset:36608
	v_pk_fma_f32 v[50:51], v[18:19], v[60:61], v[6:7] op_sel:[1,0,0]
	v_pk_mul_f32 v[6:7], v[28:29], v[22:23] op_sel_hi:[0,1]
	v_pk_fma_f32 v[6:7], v[8:9], v[56:57], v[6:7] op_sel_hi:[0,1,1] neg_lo:[0,0,1] neg_hi:[0,0,1]
	v_mov_b32_e32 v8, v29
	v_pk_fma_f32 v[56:57], v[20:21], v[60:61], v[6:7] op_sel_hi:[0,1,1]
	v_mov_b32_e32 v6, v9
	v_pk_mul_f32 v[8:9], v[8:9], v[22:23] op_sel_hi:[0,1]
	v_pk_fma_f32 v[6:7], v[6:7], v[52:53], v[8:9] op_sel_hi:[0,1,1] neg_lo:[0,0,1] neg_hi:[0,0,1]
	v_mov_b32_e32 v8, v21
	s_waitcnt lgkmcnt(2)
	v_pk_mul_f32 v[62:63], v[42:43], v[50:51] op_sel:[1,0]
	v_pk_fma_f32 v[52:53], v[8:9], v[60:61], v[6:7] op_sel_hi:[0,1,1]
	v_pk_mul_f32 v[6:7], v[2:3], v[50:51] op_sel:[1,0]
	v_pk_fma_f32 v[42:43], v[42:43], v[54:55], v[62:63] op_sel_hi:[0,1,1]
	v_mov_b32_e32 v62, v45
	v_pk_fma_f32 v[2:3], v[2:3], v[54:55], v[6:7] op_sel_hi:[0,1,1]
	v_mov_b32_e32 v6, v5
	v_pk_mul_f32 v[62:63], v[62:63], v[52:53] op_sel_hi:[0,1]
	v_pk_mul_f32 v[6:7], v[6:7], v[52:53] op_sel_hi:[0,1]
	v_pk_fma_f32 v[44:45], v[44:45], v[56:57], v[62:63] op_sel_hi:[0,1,1]
	v_pk_fma_f32 v[4:5], v[4:5], v[56:57], v[6:7] op_sel_hi:[0,1,1]
	v_pk_add_f32 v[42:43], v[42:43], v[44:45]
	v_pk_add_f32 v[2:3], v[2:3], v[4:5]
	s_nop 1
	v_add_f32_dpp v42, v42, v42 quad_perm:[1,0,3,2] row_mask:0xf bank_mask:0xf bound_ctrl:1
	v_add_f32_dpp v43, v43, v43 quad_perm:[1,0,3,2] row_mask:0xf bank_mask:0xf bound_ctrl:1
	s_nop 1
	v_add_f32_dpp v2, v2, v2 quad_perm:[1,0,3,2] row_mask:0xf bank_mask:0xf bound_ctrl:1
	v_add_f32_dpp v3, v3, v3 quad_perm:[1,0,3,2] row_mask:0xf bank_mask:0xf bound_ctrl:1
	s_nop 1
	v_add_f32_dpp v42, v42, v42 quad_perm:[2,3,0,1] row_mask:0xf bank_mask:0xf bound_ctrl:1
	v_add_f32_dpp v43, v43, v43 quad_perm:[2,3,0,1] row_mask:0xf bank_mask:0xf bound_ctrl:1
	s_nop 1
	v_add_f32_dpp v2, v2, v2 quad_perm:[2,3,0,1] row_mask:0xf bank_mask:0xf bound_ctrl:1
	v_add_f32_dpp v3, v3, v3 quad_perm:[2,3,0,1] row_mask:0xf bank_mask:0xf bound_ctrl:1
	s_nop 1
	v_add_f32_dpp v42, v42, v42 row_half_mirror row_mask:0xf bank_mask:0xf bound_ctrl:1
	v_add_f32_dpp v43, v43, v43 row_half_mirror row_mask:0xf bank_mask:0xf bound_ctrl:1
	s_nop 1
	v_add_f32_dpp v2, v2, v2 row_half_mirror row_mask:0xf bank_mask:0xf bound_ctrl:1
	v_add_f32_dpp v3, v3, v3 row_half_mirror row_mask:0xf bank_mask:0xf bound_ctrl:1
	s_nop 1
	v_add_f32_dpp v42, v42, v42 row_mirror row_mask:0xf bank_mask:0xf bound_ctrl:1
	v_add_f32_dpp v43, v43, v43 row_mirror row_mask:0xf bank_mask:0xf bound_ctrl:1
	s_waitcnt lgkmcnt(1)
	v_pk_mul_f32 v[44:45], v[46:47], v[42:43] op_sel_hi:[0,1]
	s_nop 1
	v_add_f32_dpp v2, v2, v2 row_mirror row_mask:0xf bank_mask:0xf bound_ctrl:1
	v_add_f32_dpp v3, v3, v3 row_mirror row_mask:0xf bank_mask:0xf bound_ctrl:1
	v_pk_fma_f32 v[44:45], v[34:35], v[54:55], v[44:45] op_sel_hi:[0,1,1] neg_lo:[0,0,1] neg_hi:[0,0,1]
	v_cvt_pk_bf16_f32 v2, v2, v3
	s_waitcnt lgkmcnt(0)
; #define LAS __attribute__((address_space(3)))
; DI unsigned pk2(float a, float b) { f32x2 v = {a, b}; bf2_t r = __builtin_convertvector(v, bf2_t); return __builtin_bit_cast(unsigned, r); }
; #define DPP_ADD2(a, b, ctrl) asm("s_nop 1\n\tv_add_f32_dpp %0, %0, %0 " ctrl " row_mask:0xf bank_mask:0xf bound_ctrl:1\n\tv_add_f32_dpp %1, %1, %1 " ctrl " row_mask:0xf bank_mask:0xf bound_ctrl:1" : "+v"(a), "+v"(b))
; DI f32x2 red16p(f32x2 x) { float a = x.x, b = x.y; red16x2(a, b); return (f32x2){a, b}; }
; DI void red16x2(float& a, float& b) { DPP_ADD2(a, b, "quad_perm:[1,0,3,2]"); DPP_ADD2(a, b, "quad_perm:[2,3,0,1]"); DPP_ADD2(a, b, "row_half_mirror"); DPP_ADD2(a, b, "row_mirror"); }
; DI void scan_bh2(const Args& a, int l, int bh, int halfsel, LAS unsigned char* lds) {
;     ...
;             for (int st = 0; st < T; ++st) {
;                 f32x4 nr4, nd4, nk4, nkk4, nb4; f32x2 nv2;
;                 if (st < T - 1) {
;                     const LAS float* o = cur + (st + 1) * 384;
;                     nr4 = *(const LAS f32x4*)(o + kq * 4); nd4 = *(const LAS f32x4*)(o + 64 + kq * 4); nk4 = *(const LAS f32x4*)(o + 128 + kq * 4);
;                     nkk4 = *(const LAS f32x4*)(o + 192 + kq * 4); nb4 = *(const LAS f32x4*)(o + 256 + kq * 4); nv2 = *(const LAS f32x2*)(o + 320 + row0);
;                 }
;                 f32x2 sa = S[0] * kk4[0]; sa += S[1] * kk4[1]; f32x2 sb = S[2] * kk4[2]; sb += S[3] * kk4[3]; sa += sb;
;                 sa = red16p(sa); sa = -sa;
; #pragma unroll
;                 for (int j = 0; j < 4; ++j) S[j] = S[j] * d4[j] + sa * b4[j] + v2 * k4[j];
;                 f32x2 y = S[0] * r4[0]; y += S[1] * r4[1]; f32x2 yc = S[2] * r4[2]; yc += S[3] * r4[3]; y += yc;
;                 y = red16p(y);
;                 *(LAS unsigned*)(yb + st * 128 + row0 * 2) = pk2(y.x, y.y);
;                 if (st < T - 1) { r4 = nr4; d4 = nd4; k4 = nk4; kk4 = nkk4; b4 = nb4; v2 = nv2; }
;             }
	v_pk_fma_f32 v[54:55], v[38:39], v[58:59], v[44:45] op_sel_hi:[0,1,1]
	v_pk_mul_f32 v[44:45], v[46:47], v[42:43] op_sel:[1,0]
	ds_write_b32 v14, v2 offset:2816
	v_pk_fma_f32 v[34:35], v[34:35], v[50:51], v[44:45] op_sel:[1,0,0] neg_lo:[0,0,1] neg_hi:[0,0,1]
	ds_read_b128 v[2:5], v15 offset:36864
	ds_read_b128 v[6:9], v15 offset:37120
	ds_read_b128 v[18:21], v15 offset:37376
	ds_read_b128 v[22:25], v15 offset:37632
	ds_read_b128 v[26:29], v15 offset:37888
	ds_read_b64 v[60:61], v16 offset:38144
	v_pk_fma_f32 v[50:51], v[38:39], v[58:59], v[34:35] op_sel:[1,0,0]
	v_pk_mul_f32 v[34:35], v[48:49], v[42:43] op_sel_hi:[0,1]
	v_pk_fma_f32 v[34:35], v[36:37], v[56:57], v[34:35] op_sel_hi:[0,1,1] neg_lo:[0,0,1] neg_hi:[0,0,1]
	v_mov_b32_e32 v36, v49
	v_pk_fma_f32 v[56:57], v[40:41], v[58:59], v[34:35] op_sel_hi:[0,1,1]
	v_mov_b32_e32 v34, v37
	v_pk_mul_f32 v[36:37], v[36:37], v[42:43] op_sel_hi:[0,1]
	v_pk_fma_f32 v[34:35], v[34:35], v[52:53], v[36:37] op_sel_hi:[0,1,1] neg_lo:[0,0,1] neg_hi:[0,0,1]
	v_mov_b32_e32 v36, v41
	s_waitcnt lgkmcnt(2)
	v_pk_mul_f32 v[62:63], v[22:23], v[50:51] op_sel:[1,0]
	v_pk_fma_f32 v[52:53], v[36:37], v[58:59], v[34:35] op_sel_hi:[0,1,1]
	v_pk_fma_f32 v[22:23], v[22:23], v[54:55], v[62:63] op_sel_hi:[0,1,1]
	v_mov_b32_e32 v62, v25
	v_pk_mul_f32 v[34:35], v[30:31], v[50:51] op_sel:[1,0]
	v_pk_mul_f32 v[62:63], v[62:63], v[52:53] op_sel_hi:[0,1]
	v_pk_fma_f32 v[30:31], v[30:31], v[54:55], v[34:35] op_sel_hi:[0,1,1]
	v_mov_b32_e32 v34, v33
	v_pk_fma_f32 v[24:25], v[24:25], v[56:57], v[62:63] op_sel_hi:[0,1,1]
	v_pk_mul_f32 v[34:35], v[34:35], v[52:53] op_sel_hi:[0,1]
	v_pk_add_f32 v[22:23], v[22:23], v[24:25]
	v_pk_fma_f32 v[32:33], v[32:33], v[56:57], v[34:35] op_sel_hi:[0,1,1]
	s_nop 1
	v_add_f32_dpp v22, v22, v22 quad_perm:[1,0,3,2] row_mask:0xf bank_mask:0xf bound_ctrl:1
	v_add_f32_dpp v23, v23, v23 quad_perm:[1,0,3,2] row_mask:0xf bank_mask:0xf bound_ctrl:1
	v_pk_add_f32 v[30:31], v[30:31], v[32:33]
	s_nop 1
	v_add_f32_dpp v22, v22, v22 quad_perm:[2,3,0,1] row_mask:0xf bank_mask:0xf bound_ctrl:1
	v_add_f32_dpp v23, v23, v23 quad_perm:[2,3,0,1] row_mask:0xf bank_mask:0xf bound_ctrl:1
	s_nop 1
	v_add_f32_dpp v30, v30, v30 quad_perm:[1,0,3,2] row_mask:0xf bank_mask:0xf bound_ctrl:1
	v_add_f32_dpp v31, v31, v31 quad_perm:[1,0,3,2] row_mask:0xf bank_mask:0xf bound_ctrl:1
	s_nop 1
	v_add_f32_dpp v22, v22, v22 row_half_mirror row_mask:0xf bank_mask:0xf bound_ctrl:1
	v_add_f32_dpp v23, v23, v23 row_half_mirror row_mask:0xf bank_mask:0xf bound_ctrl:1
	s_nop 1
	v_add_f32_dpp v30, v30, v30 quad_perm:[2,3,0,1] row_mask:0xf bank_mask:0xf bound_ctrl:1
	v_add_f32_dpp v31, v31, v31 quad_perm:[2,3,0,1] row_mask:0xf bank_mask:0xf bound_ctrl:1
	s_nop 1
	v_add_f32_dpp v22, v22, v22 row_mirror row_mask:0xf bank_mask:0xf bound_ctrl:1
	v_add_f32_dpp v23, v23, v23 row_mirror row_mask:0xf bank_mask:0xf bound_ctrl:1
	s_waitcnt lgkmcnt(1)
	v_pk_mul_f32 v[24:25], v[26:27], v[22:23] op_sel_hi:[0,1]
	s_nop 1
	v_add_f32_dpp v30, v30, v30 row_half_mirror row_mask:0xf bank_mask:0xf bound_ctrl:1
	v_add_f32_dpp v31, v31, v31 row_half_mirror row_mask:0xf bank_mask:0xf bound_ctrl:1
	v_pk_fma_f32 v[24:25], v[6:7], v[54:55], v[24:25] op_sel_hi:[0,1,1] neg_lo:[0,0,1] neg_hi:[0,0,1]
	s_nop 1
	v_add_f32_dpp v30, v30, v30 row_mirror row_mask:0xf bank_mask:0xf bound_ctrl:1
	v_add_f32_dpp v31, v31, v31 row_mirror row_mask:0xf bank_mask:0xf bound_ctrl:1
	s_waitcnt lgkmcnt(0)
	v_pk_fma_f32 v[54:55], v[18:19], v[60:61], v[24:25] op_sel_hi:[0,1,1]
	v_cvt_pk_bf16_f32 v17, v30, v31
	v_pk_mul_f32 v[24:25], v[26:27], v[22:23] op_sel:[1,0]
	ds_write_b32 v14, v17 offset:2944
	v_pk_fma_f32 v[6:7], v[6:7], v[50:51], v[24:25] op_sel:[1,0,0] neg_lo:[0,0,1] neg_hi:[0,0,1]
	ds_read_b128 v[30:33], v15 offset:38400
	ds_read_b128 v[34:37], v15 offset:38656
	ds_read_b128 v[38:41], v15 offset:38912
	ds_read_b128 v[42:45], v15 offset:39168
	ds_read_b128 v[46:49], v15 offset:39424
	ds_read_b64 v[58:59], v16 offset:39680
	v_pk_fma_f32 v[50:51], v[18:19], v[60:61], v[6:7] op_sel:[1,0,0]
	v_pk_mul_f32 v[6:7], v[28:29], v[22:23] op_sel_hi:[0,1]
	v_pk_fma_f32 v[6:7], v[8:9], v[56:57], v[6:7] op_sel_hi:[0,1,1] neg_lo:[0,0,1] neg_hi:[0,0,1]
	v_mov_b32_e32 v8, v29
	v_pk_fma_f32 v[56:57], v[20:21], v[60:61], v[6:7] op_sel_hi:[0,1,1]
	v_mov_b32_e32 v6, v9
	v_pk_mul_f32 v[8:9], v[8:9], v[22:23] op_sel_hi:[0,1]
	v_pk_fma_f32 v[6:7], v[6:7], v[52:53], v[8:9] op_sel_hi:[0,1,1] neg_lo:[0,0,1] neg_hi:[0,0,1]
	v_mov_b32_e32 v8, v21
	s_waitcnt lgkmcnt(2)
	v_pk_mul_f32 v[62:63], v[42:43], v[50:51] op_sel:[1,0]
	v_pk_fma_f32 v[52:53], v[8:9], v[60:61], v[6:7] op_sel_hi:[0,1,1]
	v_pk_mul_f32 v[6:7], v[2:3], v[50:51] op_sel:[1,0]
	v_pk_fma_f32 v[42:43], v[42:43], v[54:55], v[62:63] op_sel_hi:[0,1,1]
	v_mov_b32_e32 v62, v45
	v_pk_fma_f32 v[2:3], v[2:3], v[54:55], v[6:7] op_sel_hi:[0,1,1]
	v_mov_b32_e32 v6, v5
	v_pk_mul_f32 v[62:63], v[62:63], v[52:53] op_sel_hi:[0,1]
	v_pk_mul_f32 v[6:7], v[6:7], v[52:53] op_sel_hi:[0,1]
	v_pk_fma_f32 v[44:45], v[44:45], v[56:57], v[62:63] op_sel_hi:[0,1,1]
	v_pk_fma_f32 v[4:5], v[4:5], v[56:57], v[6:7] op_sel_hi:[0,1,1]
	v_pk_add_f32 v[42:43], v[42:43], v[44:45]
	v_pk_add_f32 v[2:3], v[2:3], v[4:5]
	s_nop 1
	v_add_f32_dpp v42, v42, v42 quad_perm:[1,0,3,2] row_mask:0xf bank_mask:0xf bound_ctrl:1
	v_add_f32_dpp v43, v43, v43 quad_perm:[1,0,3,2] row_mask:0xf bank_mask:0xf bound_ctrl:1
	s_nop 1
	v_add_f32_dpp v2, v2, v2 quad_perm:[1,0,3,2] row_mask:0xf bank_mask:0xf bound_ctrl:1
	v_add_f32_dpp v3, v3, v3 quad_perm:[1,0,3,2] row_mask:0xf bank_mask:0xf bound_ctrl:1
	s_nop 1
	v_add_f32_dpp v42, v42, v42 quad_perm:[2,3,0,1] row_mask:0xf bank_mask:0xf bound_ctrl:1
	v_add_f32_dpp v43, v43, v43 quad_perm:[2,3,0,1] row_mask:0xf bank_mask:0xf bound_ctrl:1
	s_nop 1
	v_add_f32_dpp v2, v2, v2 quad_perm:[2,3,0,1] row_mask:0xf bank_mask:0xf bound_ctrl:1
	v_add_f32_dpp v3, v3, v3 quad_perm:[2,3,0,1] row_mask:0xf bank_mask:0xf bound_ctrl:1
	s_nop 1
	v_add_f32_dpp v42, v42, v42 row_half_mirror row_mask:0xf bank_mask:0xf bound_ctrl:1
	v_add_f32_dpp v43, v43, v43 row_half_mirror row_mask:0xf bank_mask:0xf bound_ctrl:1
	s_nop 1
	v_add_f32_dpp v2, v2, v2 row_half_mirror row_mask:0xf bank_mask:0xf bound_ctrl:1
	v_add_f32_dpp v3, v3, v3 row_half_mirror row_mask:0xf bank_mask:0xf bound_ctrl:1
	s_nop 1
	v_add_f32_dpp v42, v42, v42 row_mirror row_mask:0xf bank_mask:0xf bound_ctrl:1
	v_add_f32_dpp v43, v43, v43 row_mirror row_mask:0xf bank_mask:0xf bound_ctrl:1
	s_waitcnt lgkmcnt(1)
; #define LAS __attribute__((address_space(3)))
; DI unsigned pk2(float a, float b) { f32x2 v = {a, b}; bf2_t r = __builtin_convertvector(v, bf2_t); return __builtin_bit_cast(unsigned, r); }
; #define DPP_ADD2(a, b, ctrl) asm("s_nop 1\n\tv_add_f32_dpp %0, %0, %0 " ctrl " row_mask:0xf bank_mask:0xf bound_ctrl:1\n\tv_add_f32_dpp %1, %1, %1 " ctrl " row_mask:0xf bank_mask:0xf bound_ctrl:1" : "+v"(a), "+v"(b))
; DI f32x2 red16p(f32x2 x) { float a = x.x, b = x.y; red16x2(a, b); return (f32x2){a, b}; }
; DI void red16x2(float& a, float& b) { DPP_ADD2(a, b, "quad_perm:[1,0,3,2]"); DPP_ADD2(a, b, "quad_perm:[2,3,0,1]"); DPP_ADD2(a, b, "row_half_mirror"); DPP_ADD2(a, b, "row_mirror"); }
; DI void scan_bh2(const Args& a, int l, int bh, int halfsel, LAS unsigned char* lds) {
;     ...
;             for (int st = 0; st < T; ++st) {
;                 f32x4 nr4, nd4, nk4, nkk4, nb4; f32x2 nv2;
;                 if (st < T - 1) {
;                     const LAS float* o = cur + (st + 1) * 384;
;                     nr4 = *(const LAS f32x4*)(o + kq * 4); nd4 = *(const LAS f32x4*)(o + 64 + kq * 4); nk4 = *(const LAS f32x4*)(o + 128 + kq * 4);
;                     nkk4 = *(const LAS f32x4*)(o + 192 + kq * 4); nb4 = *(const LAS f32x4*)(o + 256 + kq * 4); nv2 = *(const LAS f32x2*)(o + 320 + row0);
;                 }
;                 f32x2 sa = S[0] * kk4[0]; sa += S[1] * kk4[1]; f32x2 sb = S[2] * kk4[2]; sb += S[3] * kk4[3]; sa += sb;
;                 sa = red16p(sa); sa = -sa;
; #pragma unroll
;                 for (int j = 0; j < 4; ++j) S[j] = S[j] * d4[j] + sa * b4[j] + v2 * k4[j];
;                 f32x2 y = S[0] * r4[0]; y += S[1] * r4[1]; f32x2 yc = S[2] * r4[2]; yc += S[3] * r4[3]; y += yc;
;                 y = red16p(y);
;                 *(LAS unsigned*)(yb + st * 128 + row0 * 2) = pk2(y.x, y.y);
;                 if (st < T - 1) { r4 = nr4; d4 = nd4; k4 = nk4; kk4 = nkk4; b4 = nb4; v2 = nv2; }
;             }
	v_pk_mul_f32 v[44:45], v[46:47], v[42:43] op_sel_hi:[0,1]
	s_nop 1
	v_add_f32_dpp v2, v2, v2 row_mirror row_mask:0xf bank_mask:0xf bound_ctrl:1
	v_add_f32_dpp v3, v3, v3 row_mirror row_mask:0xf bank_mask:0xf bound_ctrl:1
	v_pk_fma_f32 v[44:45], v[34:35], v[54:55], v[44:45] op_sel_hi:[0,1,1] neg_lo:[0,0,1] neg_hi:[0,0,1]
	v_cvt_pk_bf16_f32 v2, v2, v3
	s_waitcnt lgkmcnt(0)
	v_pk_fma_f32 v[54:55], v[38:39], v[58:59], v[44:45] op_sel_hi:[0,1,1]
	v_pk_mul_f32 v[44:45], v[46:47], v[42:43] op_sel:[1,0]
	ds_write_b32 v14, v2 offset:3072
	v_pk_fma_f32 v[34:35], v[34:35], v[50:51], v[44:45] op_sel:[1,0,0] neg_lo:[0,0,1] neg_hi:[0,0,1]
	ds_read_b128 v[2:5], v15 offset:39936
	ds_read_b128 v[6:9], v15 offset:40192
	ds_read_b128 v[18:21], v15 offset:40448
	ds_read_b128 v[22:25], v15 offset:40704
	ds_read_b128 v[26:29], v15 offset:40960
	ds_read_b64 v[60:61], v16 offset:41216
	v_pk_fma_f32 v[50:51], v[38:39], v[58:59], v[34:35] op_sel:[1,0,0]
	v_pk_mul_f32 v[34:35], v[48:49], v[42:43] op_sel_hi:[0,1]
	v_pk_fma_f32 v[34:35], v[36:37], v[56:57], v[34:35] op_sel_hi:[0,1,1] neg_lo:[0,0,1] neg_hi:[0,0,1]
	v_mov_b32_e32 v36, v49
	v_pk_fma_f32 v[56:57], v[40:41], v[58:59], v[34:35] op_sel_hi:[0,1,1]
	v_mov_b32_e32 v34, v37
	v_pk_mul_f32 v[36:37], v[36:37], v[42:43] op_sel_hi:[0,1]
	v_pk_fma_f32 v[34:35], v[34:35], v[52:53], v[36:37] op_sel_hi:[0,1,1] neg_lo:[0,0,1] neg_hi:[0,0,1]
	v_mov_b32_e32 v36, v41
	s_waitcnt lgkmcnt(2)
	v_pk_mul_f32 v[62:63], v[22:23], v[50:51] op_sel:[1,0]
	v_pk_fma_f32 v[52:53], v[36:37], v[58:59], v[34:35] op_sel_hi:[0,1,1]
	v_pk_fma_f32 v[22:23], v[22:23], v[54:55], v[62:63] op_sel_hi:[0,1,1]
	v_mov_b32_e32 v62, v25
	v_pk_mul_f32 v[34:35], v[30:31], v[50:51] op_sel:[1,0]
	v_pk_mul_f32 v[62:63], v[62:63], v[52:53] op_sel_hi:[0,1]
	v_pk_fma_f32 v[30:31], v[30:31], v[54:55], v[34:35] op_sel_hi:[0,1,1]
	v_mov_b32_e32 v34, v33
	v_pk_fma_f32 v[24:25], v[24:25], v[56:57], v[62:63] op_sel_hi:[0,1,1]
	v_pk_mul_f32 v[34:35], v[34:35], v[52:53] op_sel_hi:[0,1]
	v_pk_add_f32 v[22:23], v[22:23], v[24:25]
	v_pk_fma_f32 v[32:33], v[32:33], v[56:57], v[34:35] op_sel_hi:[0,1,1]
	s_nop 1
	v_add_f32_dpp v22, v22, v22 quad_perm:[1,0,3,2] row_mask:0xf bank_mask:0xf bound_ctrl:1
	v_add_f32_dpp v23, v23, v23 quad_perm:[1,0,3,2] row_mask:0xf bank_mask:0xf bound_ctrl:1
	v_pk_add_f32 v[30:31], v[30:31], v[32:33]
	s_nop 1
	v_add_f32_dpp v22, v22, v22 quad_perm:[2,3,0,1] row_mask:0xf bank_mask:0xf bound_ctrl:1
	v_add_f32_dpp v23, v23, v23 quad_perm:[2,3,0,1] row_mask:0xf bank_mask:0xf bound_ctrl:1
	s_nop 1
	v_add_f32_dpp v30, v30, v30 quad_perm:[1,0,3,2] row_mask:0xf bank_mask:0xf bound_ctrl:1
	v_add_f32_dpp v31, v31, v31 quad_perm:[1,0,3,2] row_mask:0xf bank_mask:0xf bound_ctrl:1
	s_nop 1
	v_add_f32_dpp v22, v22, v22 row_half_mirror row_mask:0xf bank_mask:0xf bound_ctrl:1
	v_add_f32_dpp v23, v23, v23 row_half_mirror row_mask:0xf bank_mask:0xf bound_ctrl:1
	s_nop 1
	v_add_f32_dpp v30, v30, v30 quad_perm:[2,3,0,1] row_mask:0xf bank_mask:0xf bound_ctrl:1
	v_add_f32_dpp v31, v31, v31 quad_perm:[2,3,0,1] row_mask:0xf bank_mask:0xf bound_ctrl:1
	s_nop 1
	v_add_f32_dpp v22, v22, v22 row_mirror row_mask:0xf bank_mask:0xf bound_ctrl:1
	v_add_f32_dpp v23, v23, v23 row_mirror row_mask:0xf bank_mask:0xf bound_ctrl:1
	s_waitcnt lgkmcnt(1)
	v_pk_mul_f32 v[24:25], v[26:27], v[22:23] op_sel_hi:[0,1]
	s_nop 1
	v_add_f32_dpp v30, v30, v30 row_half_mirror row_mask:0xf bank_mask:0xf bound_ctrl:1
	v_add_f32_dpp v31, v31, v31 row_half_mirror row_mask:0xf bank_mask:0xf bound_ctrl:1
	v_pk_fma_f32 v[24:25], v[6:7], v[54:55], v[24:25] op_sel_hi:[0,1,1] neg_lo:[0,0,1] neg_hi:[0,0,1]
	s_nop 1
	v_add_f32_dpp v30, v30, v30 row_mirror row_mask:0xf bank_mask:0xf bound_ctrl:1
	v_add_f32_dpp v31, v31, v31 row_mirror row_mask:0xf bank_mask:0xf bound_ctrl:1
	s_waitcnt lgkmcnt(0)
	v_pk_fma_f32 v[54:55], v[18:19], v[60:61], v[24:25] op_sel_hi:[0,1,1]
	v_cvt_pk_bf16_f32 v17, v30, v31
	v_pk_mul_f32 v[24:25], v[26:27], v[22:23] op_sel:[1,0]
	ds_write_b32 v14, v17 offset:3200
	v_pk_fma_f32 v[6:7], v[6:7], v[50:51], v[24:25] op_sel:[1,0,0] neg_lo:[0,0,1] neg_hi:[0,0,1]
	ds_read_b128 v[30:33], v15 offset:41472
	ds_read_b128 v[34:37], v15 offset:41728
	ds_read_b128 v[38:41], v15 offset:41984
	ds_read_b128 v[42:45], v15 offset:42240
	ds_read_b128 v[46:49], v15 offset:42496
	ds_read_b64 v[58:59], v16 offset:42752
	v_pk_fma_f32 v[50:51], v[18:19], v[60:61], v[6:7] op_sel:[1,0,0]
	v_pk_mul_f32 v[6:7], v[28:29], v[22:23] op_sel_hi:[0,1]
	v_pk_fma_f32 v[6:7], v[8:9], v[56:57], v[6:7] op_sel_hi:[0,1,1] neg_lo:[0,0,1] neg_hi:[0,0,1]
	v_mov_b32_e32 v8, v29
	v_pk_fma_f32 v[56:57], v[20:21], v[60:61], v[6:7] op_sel_hi:[0,1,1]
	v_mov_b32_e32 v6, v9
	v_pk_mul_f32 v[8:9], v[8:9], v[22:23] op_sel_hi:[0,1]
	v_pk_fma_f32 v[6:7], v[6:7], v[52:53], v[8:9] op_sel_hi:[0,1,1] neg_lo:[0,0,1] neg_hi:[0,0,1]
	v_mov_b32_e32 v8, v21
	s_waitcnt lgkmcnt(2)
; #define LAS __attribute__((address_space(3)))
; DI unsigned pk2(float a, float b) { f32x2 v = {a, b}; bf2_t r = __builtin_convertvector(v, bf2_t); return __builtin_bit_cast(unsigned, r); }
; #define DPP_ADD2(a, b, ctrl) asm("s_nop 1\n\tv_add_f32_dpp %0, %0, %0 " ctrl " row_mask:0xf bank_mask:0xf bound_ctrl:1\n\tv_add_f32_dpp %1, %1, %1 " ctrl " row_mask:0xf bank_mask:0xf bound_ctrl:1" : "+v"(a), "+v"(b))
; DI f32x2 red16p(f32x2 x) { float a = x.x, b = x.y; red16x2(a, b); return (f32x2){a, b}; }
; DI void red16x2(float& a, float& b) { DPP_ADD2(a, b, "quad_perm:[1,0,3,2]"); DPP_ADD2(a, b, "quad_perm:[2,3,0,1]"); DPP_ADD2(a, b, "row_half_mirror"); DPP_ADD2(a, b, "row_mirror"); }
; DI void scan_bh2(const Args& a, int l, int bh, int halfsel, LAS unsigned char* lds) {
;     ...
;             for (int st = 0; st < T; ++st) {
;                 f32x4 nr4, nd4, nk4, nkk4, nb4; f32x2 nv2;
;                 if (st < T - 1) {
;                     const LAS float* o = cur + (st + 1) * 384;
;                     nr4 = *(const LAS f32x4*)(o + kq * 4); nd4 = *(const LAS f32x4*)(o + 64 + kq * 4); nk4 = *(const LAS f32x4*)(o + 128 + kq * 4);
;                     nkk4 = *(const LAS f32x4*)(o + 192 + kq * 4); nb4 = *(const LAS f32x4*)(o + 256 + kq * 4); nv2 = *(const LAS f32x2*)(o + 320 + row0);
;                 }
;                 f32x2 sa = S[0] * kk4[0]; sa += S[1] * kk4[1]; f32x2 sb = S[2] * kk4[2]; sb += S[3] * kk4[3]; sa += sb;
;                 sa = red16p(sa); sa = -sa;
; #pragma unroll
;                 for (int j = 0; j < 4; ++j) S[j] = S[j] * d4[j] + sa * b4[j] + v2 * k4[j];
;                 f32x2 y = S[0] * r4[0]; y += S[1] * r4[1]; f32x2 yc = S[2] * r4[2]; yc += S[3] * r4[3]; y += yc;
;                 y = red16p(y);
;                 *(LAS unsigned*)(yb + st * 128 + row0 * 2) = pk2(y.x, y.y);
;                 if (st < T - 1) { r4 = nr4; d4 = nd4; k4 = nk4; kk4 = nkk4; b4 = nb4; v2 = nv2; }
;             }
	v_pk_mul_f32 v[62:63], v[42:43], v[50:51] op_sel:[1,0]
	v_pk_fma_f32 v[52:53], v[8:9], v[60:61], v[6:7] op_sel_hi:[0,1,1]
	v_pk_mul_f32 v[6:7], v[2:3], v[50:51] op_sel:[1,0]
	v_pk_fma_f32 v[42:43], v[42:43], v[54:55], v[62:63] op_sel_hi:[0,1,1]
	v_mov_b32_e32 v62, v45
	v_pk_fma_f32 v[2:3], v[2:3], v[54:55], v[6:7] op_sel_hi:[0,1,1]
	v_mov_b32_e32 v6, v5
	v_pk_mul_f32 v[62:63], v[62:63], v[52:53] op_sel_hi:[0,1]
	v_pk_mul_f32 v[6:7], v[6:7], v[52:53] op_sel_hi:[0,1]
	v_pk_fma_f32 v[44:45], v[44:45], v[56:57], v[62:63] op_sel_hi:[0,1,1]
	v_pk_fma_f32 v[4:5], v[4:5], v[56:57], v[6:7] op_sel_hi:[0,1,1]
	v_pk_add_f32 v[42:43], v[42:43], v[44:45]
	v_pk_add_f32 v[2:3], v[2:3], v[4:5]
	s_nop 1
	v_add_f32_dpp v42, v42, v42 quad_perm:[1,0,3,2] row_mask:0xf bank_mask:0xf bound_ctrl:1
	v_add_f32_dpp v43, v43, v43 quad_perm:[1,0,3,2] row_mask:0xf bank_mask:0xf bound_ctrl:1
	s_nop 1
	v_add_f32_dpp v2, v2, v2 quad_perm:[1,0,3,2] row_mask:0xf bank_mask:0xf bound_ctrl:1
	v_add_f32_dpp v3, v3, v3 quad_perm:[1,0,3,2] row_mask:0xf bank_mask:0xf bound_ctrl:1
	s_nop 1
	v_add_f32_dpp v42, v42, v42 quad_perm:[2,3,0,1] row_mask:0xf bank_mask:0xf bound_ctrl:1
	v_add_f32_dpp v43, v43, v43 quad_perm:[2,3,0,1] row_mask:0xf bank_mask:0xf bound_ctrl:1
	s_nop 1
	v_add_f32_dpp v2, v2, v2 quad_perm:[2,3,0,1] row_mask:0xf bank_mask:0xf bound_ctrl:1
	v_add_f32_dpp v3, v3, v3 quad_perm:[2,3,0,1] row_mask:0xf bank_mask:0xf bound_ctrl:1
	s_nop 1
	v_add_f32_dpp v42, v42, v42 row_half_mirror row_mask:0xf bank_mask:0xf bound_ctrl:1
	v_add_f32_dpp v43, v43, v43 row_half_mirror row_mask:0xf bank_mask:0xf bound_ctrl:1
	s_nop 1
	v_add_f32_dpp v2, v2, v2 row_half_mirror row_mask:0xf bank_mask:0xf bound_ctrl:1
	v_add_f32_dpp v3, v3, v3 row_half_mirror row_mask:0xf bank_mask:0xf bound_ctrl:1
	s_nop 1
	v_add_f32_dpp v42, v42, v42 row_mirror row_mask:0xf bank_mask:0xf bound_ctrl:1
	v_add_f32_dpp v43, v43, v43 row_mirror row_mask:0xf bank_mask:0xf bound_ctrl:1
	s_waitcnt lgkmcnt(1)
	v_pk_mul_f32 v[44:45], v[46:47], v[42:43] op_sel_hi:[0,1]
	s_nop 1
	v_add_f32_dpp v2, v2, v2 row_mirror row_mask:0xf bank_mask:0xf bound_ctrl:1
	v_add_f32_dpp v3, v3, v3 row_mirror row_mask:0xf bank_mask:0xf bound_ctrl:1
	v_pk_fma_f32 v[44:45], v[34:35], v[54:55], v[44:45] op_sel_hi:[0,1,1] neg_lo:[0,0,1] neg_hi:[0,0,1]
	v_cvt_pk_bf16_f32 v2, v2, v3
	s_waitcnt lgkmcnt(0)
	v_pk_fma_f32 v[54:55], v[38:39], v[58:59], v[44:45] op_sel_hi:[0,1,1]
	v_pk_mul_f32 v[44:45], v[46:47], v[42:43] op_sel:[1,0]
	ds_write_b32 v14, v2 offset:3328
	v_pk_fma_f32 v[34:35], v[34:35], v[50:51], v[44:45] op_sel:[1,0,0] neg_lo:[0,0,1] neg_hi:[0,0,1]
	ds_read_b128 v[2:5], v15 offset:43008
	ds_read_b128 v[6:9], v15 offset:43264
	ds_read_b128 v[18:21], v15 offset:43520
	ds_read_b128 v[22:25], v15 offset:43776
	ds_read_b128 v[26:29], v15 offset:44032
	ds_read_b64 v[60:61], v16 offset:44288
	v_pk_fma_f32 v[50:51], v[38:39], v[58:59], v[34:35] op_sel:[1,0,0]
	v_pk_mul_f32 v[34:35], v[48:49], v[42:43] op_sel_hi:[0,1]
	v_pk_fma_f32 v[34:35], v[36:37], v[56:57], v[34:35] op_sel_hi:[0,1,1] neg_lo:[0,0,1] neg_hi:[0,0,1]
	v_mov_b32_e32 v36, v49
	v_pk_fma_f32 v[56:57], v[40:41], v[58:59], v[34:35] op_sel_hi:[0,1,1]
	v_mov_b32_e32 v34, v37
	v_pk_mul_f32 v[36:37], v[36:37], v[42:43] op_sel_hi:[0,1]
	v_pk_fma_f32 v[34:35], v[34:35], v[52:53], v[36:37] op_sel_hi:[0,1,1] neg_lo:[0,0,1] neg_hi:[0,0,1]
	v_mov_b32_e32 v36, v41
	s_waitcnt lgkmcnt(2)
	v_pk_mul_f32 v[62:63], v[22:23], v[50:51] op_sel:[1,0]
	v_pk_fma_f32 v[52:53], v[36:37], v[58:59], v[34:35] op_sel_hi:[0,1,1]
	v_pk_fma_f32 v[22:23], v[22:23], v[54:55], v[62:63] op_sel_hi:[0,1,1]
	v_mov_b32_e32 v62, v25
	v_pk_mul_f32 v[34:35], v[30:31], v[50:51] op_sel:[1,0]
	v_pk_mul_f32 v[62:63], v[62:63], v[52:53] op_sel_hi:[0,1]
	v_pk_fma_f32 v[30:31], v[30:31], v[54:55], v[34:35] op_sel_hi:[0,1,1]
	v_mov_b32_e32 v34, v33
	v_pk_fma_f32 v[24:25], v[24:25], v[56:57], v[62:63] op_sel_hi:[0,1,1]
	v_pk_mul_f32 v[34:35], v[34:35], v[52:53] op_sel_hi:[0,1]
	v_pk_add_f32 v[22:23], v[22:23], v[24:25]
	v_pk_fma_f32 v[32:33], v[32:33], v[56:57], v[34:35] op_sel_hi:[0,1,1]
	s_nop 1
	v_add_f32_dpp v22, v22, v22 quad_perm:[1,0,3,2] row_mask:0xf bank_mask:0xf bound_ctrl:1
	v_add_f32_dpp v23, v23, v23 quad_perm:[1,0,3,2] row_mask:0xf bank_mask:0xf bound_ctrl:1
	v_pk_add_f32 v[30:31], v[30:31], v[32:33]
	s_nop 1
	v_add_f32_dpp v22, v22, v22 quad_perm:[2,3,0,1] row_mask:0xf bank_mask:0xf bound_ctrl:1
	v_add_f32_dpp v23, v23, v23 quad_perm:[2,3,0,1] row_mask:0xf bank_mask:0xf bound_ctrl:1
	s_nop 1
	v_add_f32_dpp v30, v30, v30 quad_perm:[1,0,3,2] row_mask:0xf bank_mask:0xf bound_ctrl:1
	v_add_f32_dpp v31, v31, v31 quad_perm:[1,0,3,2] row_mask:0xf bank_mask:0xf bound_ctrl:1
	s_nop 1
	v_add_f32_dpp v22, v22, v22 row_half_mirror row_mask:0xf bank_mask:0xf bound_ctrl:1
	v_add_f32_dpp v23, v23, v23 row_half_mirror row_mask:0xf bank_mask:0xf bound_ctrl:1
	s_nop 1
	v_add_f32_dpp v30, v30, v30 quad_perm:[2,3,0,1] row_mask:0xf bank_mask:0xf bound_ctrl:1
	v_add_f32_dpp v31, v31, v31 quad_perm:[2,3,0,1] row_mask:0xf bank_mask:0xf bound_ctrl:1
	s_nop 1
	v_add_f32_dpp v22, v22, v22 row_mirror row_mask:0xf bank_mask:0xf bound_ctrl:1
	v_add_f32_dpp v23, v23, v23 row_mirror row_mask:0xf bank_mask:0xf bound_ctrl:1
	s_waitcnt lgkmcnt(1)
	v_pk_mul_f32 v[24:25], v[26:27], v[22:23] op_sel_hi:[0,1]
	s_nop 1
	v_add_f32_dpp v30, v30, v30 row_half_mirror row_mask:0xf bank_mask:0xf bound_ctrl:1
	v_add_f32_dpp v31, v31, v31 row_half_mirror row_mask:0xf bank_mask:0xf bound_ctrl:1
	v_pk_fma_f32 v[24:25], v[6:7], v[54:55], v[24:25] op_sel_hi:[0,1,1] neg_lo:[0,0,1] neg_hi:[0,0,1]
	s_nop 1
	v_add_f32_dpp v30, v30, v30 row_mirror row_mask:0xf bank_mask:0xf bound_ctrl:1
	v_add_f32_dpp v31, v31, v31 row_mirror row_mask:0xf bank_mask:0xf bound_ctrl:1
	s_waitcnt lgkmcnt(0)
; #define LAS __attribute__((address_space(3)))
; DI unsigned pk2(float a, float b) { f32x2 v = {a, b}; bf2_t r = __builtin_convertvector(v, bf2_t); return __builtin_bit_cast(unsigned, r); }
; DI f32x2 red16p(f32x2 x) { float a = x.x, b = x.y; red16x2(a, b); return (f32x2){a, b}; }
; DI void scan_bh2(const Args& a, int l, int bh, int halfsel, LAS unsigned char* lds) {
;     ...
;             for (int st = 0; st < T; ++st) {
;                 f32x4 nr4, nd4, nk4, nkk4, nb4; f32x2 nv2;
;                 if (st < T - 1) {
;                     const LAS float* o = cur + (st + 1) * 384;
;                     nr4 = *(const LAS f32x4*)(o + kq * 4); nd4 = *(const LAS f32x4*)(o + 64 + kq * 4); nk4 = *(const LAS f32x4*)(o + 128 + kq * 4);
;                     nkk4 = *(const LAS f32x4*)(o + 192 + kq * 4); nb4 = *(const LAS f32x4*)(o + 256 + kq * 4); nv2 = *(const LAS f32x2*)(o + 320 + row0);
;                 }
;                 f32x2 sa = S[0] * kk4[0]; sa += S[1] * kk4[1]; f32x2 sb = S[2] * kk4[2]; sb += S[3] * kk4[3]; sa += sb;
;                 sa = red16p(sa); sa = -sa;
; #pragma unroll
;                 for (int j = 0; j < 4; ++j) S[j] = S[j] * d4[j] + sa * b4[j] + v2 * k4[j];
;                 f32x2 y = S[0] * r4[0]; y += S[1] * r4[1]; f32x2 yc = S[2] * r4[2]; yc += S[3] * r4[3]; y += yc;
;                 y = red16p(y);
;                 *(LAS unsigned*)(yb + st * 128 + row0 * 2) = pk2(y.x, y.y);
;                 if (st < T - 1) { r4 = nr4; d4 = nd4; k4 = nk4; kk4 = nkk4; b4 = nb4; v2 = nv2; }
;             }
	v_pk_fma_f32 v[54:55], v[18:19], v[60:61], v[24:25] op_sel_hi:[0,1,1]
	v_cvt_pk_bf16_f32 v17, v30, v31
	v_pk_mul_f32 v[24:25], v[26:27], v[22:23] op_sel:[1,0]
	ds_write_b32 v14, v17 offset:3456
	v_pk_fma_f32 v[6:7], v[6:7], v[50:51], v[24:25] op_sel:[1,0,0] neg_lo:[0,0,1] neg_hi:[0,0,1]
	ds_read_b128 v[30:33], v15 offset:44544
	ds_read_b128 v[34:37], v15 offset:44800
	ds_read_b128 v[38:41], v15 offset:45056
	ds_read_b128 v[42:45], v15 offset:45312
	ds_read_b128 v[46:49], v15 offset:45568
	ds_read_b64 v[58:59], v16 offset:45824
	v_pk_fma_f32 v[50:51], v[18:19], v[60:61], v[6:7] op_sel:[1,0,0]
	v_pk_mul_f32 v[6:7], v[28:29], v[22:23] op_sel_hi:[0,1]
	v_pk_fma_f32 v[6:7], v[8:9], v[56:57], v[6:7] op_sel_hi:[0,1,1] neg_lo:[0,0,1] neg_hi:[0,0,1]
	v_mov_b32_e32 v8, v29
	v_pk_fma_f32 v[56:57], v[20:21], v[60:61], v[6:7] op_sel_hi:[0,1,1]
	v_mov_b32_e32 v6, v9
	v_pk_mul_f32 v[8:9], v[8:9], v[22:23] op_sel_hi:[0,1]
	v_pk_fma_f32 v[6:7], v[6:7], v[52:53], v[8:9] op_sel_hi:[0,1,1] neg_lo:[0,0,1] neg_hi:[0,0,1]
	v_mov_b32_e32 v8, v21
	s_waitcnt lgkmcnt(2)
	v_pk_mul_f32 v[62:63], v[42:43], v[50:51] op_sel:[1,0]
	v_pk_fma_f32 v[52:53], v[8:9], v[60:61], v[6:7] op_sel_hi:[0,1,1]
	v_pk_fma_f32 v[42:43], v[42:43], v[54:55], v[62:63] op_sel_hi:[0,1,1]
	v_mov_b32_e32 v62, v45
	v_pk_mul_f32 v[6:7], v[2:3], v[50:51] op_sel:[1,0]
	v_pk_mul_f32 v[62:63], v[62:63], v[52:53] op_sel_hi:[0,1]
	v_pk_fma_f32 v[2:3], v[2:3], v[54:55], v[6:7] op_sel_hi:[0,1,1]
	v_mov_b32_e32 v6, v5
	v_pk_fma_f32 v[44:45], v[44:45], v[56:57], v[62:63] op_sel_hi:[0,1,1]
	v_pk_mul_f32 v[6:7], v[6:7], v[52:53] op_sel_hi:[0,1]
	v_pk_add_f32 v[42:43], v[42:43], v[44:45]
	v_pk_fma_f32 v[4:5], v[4:5], v[56:57], v[6:7] op_sel_hi:[0,1,1]
	s_nop 1
	v_add_f32_dpp v42, v42, v42 quad_perm:[1,0,3,2] row_mask:0xf bank_mask:0xf bound_ctrl:1
	v_add_f32_dpp v43, v43, v43 quad_perm:[1,0,3,2] row_mask:0xf bank_mask:0xf bound_ctrl:1
	v_pk_add_f32 v[2:3], v[2:3], v[4:5]
	s_nop 1
	v_add_f32_dpp v42, v42, v42 quad_perm:[2,3,0,1] row_mask:0xf bank_mask:0xf bound_ctrl:1
	v_add_f32_dpp v43, v43, v43 quad_perm:[2,3,0,1] row_mask:0xf bank_mask:0xf bound_ctrl:1
	s_nop 1
	v_add_f32_dpp v2, v2, v2 quad_perm:[1,0,3,2] row_mask:0xf bank_mask:0xf bound_ctrl:1
	v_add_f32_dpp v3, v3, v3 quad_perm:[1,0,3,2] row_mask:0xf bank_mask:0xf bound_ctrl:1
	s_nop 1
	v_add_f32_dpp v42, v42, v42 row_half_mirror row_mask:0xf bank_mask:0xf bound_ctrl:1
	v_add_f32_dpp v43, v43, v43 row_half_mirror row_mask:0xf bank_mask:0xf bound_ctrl:1
	s_nop 1
	v_add_f32_dpp v2, v2, v2 quad_perm:[2,3,0,1] row_mask:0xf bank_mask:0xf bound_ctrl:1
	v_add_f32_dpp v3, v3, v3 quad_perm:[2,3,0,1] row_mask:0xf bank_mask:0xf bound_ctrl:1
	s_nop 1
	v_add_f32_dpp v42, v42, v42 row_mirror row_mask:0xf bank_mask:0xf bound_ctrl:1
	v_add_f32_dpp v43, v43, v43 row_mirror row_mask:0xf bank_mask:0xf bound_ctrl:1
	s_waitcnt lgkmcnt(1)
	v_pk_mul_f32 v[44:45], v[46:47], v[42:43] op_sel_hi:[0,1]
	s_nop 1
	v_add_f32_dpp v2, v2, v2 row_half_mirror row_mask:0xf bank_mask:0xf bound_ctrl:1
	v_add_f32_dpp v3, v3, v3 row_half_mirror row_mask:0xf bank_mask:0xf bound_ctrl:1
	v_pk_fma_f32 v[44:45], v[34:35], v[54:55], v[44:45] op_sel_hi:[0,1,1] neg_lo:[0,0,1] neg_hi:[0,0,1]
	s_nop 1
	v_add_f32_dpp v2, v2, v2 row_mirror row_mask:0xf bank_mask:0xf bound_ctrl:1
	v_add_f32_dpp v3, v3, v3 row_mirror row_mask:0xf bank_mask:0xf bound_ctrl:1
	s_waitcnt lgkmcnt(0)
	v_pk_fma_f32 v[54:55], v[38:39], v[58:59], v[44:45] op_sel_hi:[0,1,1]
	v_pk_mul_f32 v[44:45], v[46:47], v[42:43] op_sel:[1,0]
	v_cvt_pk_bf16_f32 v2, v2, v3
	v_pk_fma_f32 v[34:35], v[34:35], v[50:51], v[44:45] op_sel:[1,0,0] neg_lo:[0,0,1] neg_hi:[0,0,1]
	ds_write_b32 v14, v2 offset:3584
	v_pk_fma_f32 v[50:51], v[38:39], v[58:59], v[34:35] op_sel:[1,0,0]
	v_pk_mul_f32 v[34:35], v[48:49], v[42:43] op_sel_hi:[0,1]
	ds_read_b128 v[2:5], v15 offset:46080
	ds_read_b128 v[6:9], v15 offset:46336
	ds_read_b128 v[18:21], v15 offset:46592
	ds_read_b128 v[22:25], v15 offset:46848
	ds_read_b128 v[26:29], v15 offset:47104
	ds_read_b64 v[60:61], v16 offset:47360
	v_pk_fma_f32 v[34:35], v[36:37], v[56:57], v[34:35] op_sel_hi:[0,1,1] neg_lo:[0,0,1] neg_hi:[0,0,1]
	v_mov_b32_e32 v36, v49
	v_pk_fma_f32 v[56:57], v[40:41], v[58:59], v[34:35] op_sel_hi:[0,1,1]
	v_mov_b32_e32 v34, v37
	v_pk_mul_f32 v[36:37], v[36:37], v[42:43] op_sel_hi:[0,1]
	v_pk_fma_f32 v[34:35], v[34:35], v[52:53], v[36:37] op_sel_hi:[0,1,1] neg_lo:[0,0,1] neg_hi:[0,0,1]
	v_mov_b32_e32 v36, v41
	v_pk_fma_f32 v[52:53], v[36:37], v[58:59], v[34:35] op_sel_hi:[0,1,1]
	s_waitcnt lgkmcnt(2)
	v_pk_mul_f32 v[58:59], v[22:23], v[50:51] op_sel:[1,0]
	v_pk_mul_f32 v[34:35], v[30:31], v[50:51] op_sel:[1,0]
	v_pk_fma_f32 v[22:23], v[22:23], v[54:55], v[58:59] op_sel_hi:[0,1,1]
	v_mov_b32_e32 v58, v25
	v_pk_mul_f32 v[58:59], v[58:59], v[52:53] op_sel_hi:[0,1]
	v_pk_fma_f32 v[24:25], v[24:25], v[56:57], v[58:59] op_sel_hi:[0,1,1]
	v_pk_add_f32 v[22:23], v[22:23], v[24:25]
	v_pk_fma_f32 v[30:31], v[30:31], v[54:55], v[34:35] op_sel_hi:[0,1,1]
	s_nop 1
	v_add_f32_dpp v22, v22, v22 quad_perm:[1,0,3,2] row_mask:0xf bank_mask:0xf bound_ctrl:1
	v_add_f32_dpp v23, v23, v23 quad_perm:[1,0,3,2] row_mask:0xf bank_mask:0xf bound_ctrl:1
	v_mov_b32_e32 v34, v33
	s_nop 1
	v_add_f32_dpp v22, v22, v22 quad_perm:[2,3,0,1] row_mask:0xf bank_mask:0xf bound_ctrl:1
	v_add_f32_dpp v23, v23, v23 quad_perm:[2,3,0,1] row_mask:0xf bank_mask:0xf bound_ctrl:1
	v_pk_mul_f32 v[34:35], v[34:35], v[52:53] op_sel_hi:[0,1]
	s_nop 1
	v_add_f32_dpp v22, v22, v22 row_half_mirror row_mask:0xf bank_mask:0xf bound_ctrl:1
	v_add_f32_dpp v23, v23, v23 row_half_mirror row_mask:0xf bank_mask:0xf bound_ctrl:1
	v_pk_fma_f32 v[32:33], v[32:33], v[56:57], v[34:35] op_sel_hi:[0,1,1]
	s_nop 1
	v_add_f32_dpp v22, v22, v22 row_mirror row_mask:0xf bank_mask:0xf bound_ctrl:1
	v_add_f32_dpp v23, v23, v23 row_mirror row_mask:0xf bank_mask:0xf bound_ctrl:1
	v_pk_add_f32 v[30:31], v[30:31], v[32:33]
	s_waitcnt lgkmcnt(1)
; #define LAS __attribute__((address_space(3)))
; DI unsigned pk2(float a, float b) { f32x2 v = {a, b}; bf2_t r = __builtin_convertvector(v, bf2_t); return __builtin_bit_cast(unsigned, r); }
; DI f32x2 red16p(f32x2 x) { float a = x.x, b = x.y; red16x2(a, b); return (f32x2){a, b}; }
; DI void scan_bh2(const Args& a, int l, int bh, int halfsel, LAS unsigned char* lds) {
;     ...
;             for (int st = 0; st < T; ++st) {
;                 f32x4 nr4, nd4, nk4, nkk4, nb4; f32x2 nv2;
;                 if (st < T - 1) {
;                     const LAS float* o = cur + (st + 1) * 384;
;                     nr4 = *(const LAS f32x4*)(o + kq * 4); nd4 = *(const LAS f32x4*)(o + 64 + kq * 4); nk4 = *(const LAS f32x4*)(o + 128 + kq * 4);
;                     nkk4 = *(const LAS f32x4*)(o + 192 + kq * 4); nb4 = *(const LAS f32x4*)(o + 256 + kq * 4); nv2 = *(const LAS f32x2*)(o + 320 + row0);
;                 }
;                 f32x2 sa = S[0] * kk4[0]; sa += S[1] * kk4[1]; f32x2 sb = S[2] * kk4[2]; sb += S[3] * kk4[3]; sa += sb;
;                 sa = red16p(sa); sa = -sa;
; #pragma unroll
;                 for (int j = 0; j < 4; ++j) S[j] = S[j] * d4[j] + sa * b4[j] + v2 * k4[j];
;                 f32x2 y = S[0] * r4[0]; y += S[1] * r4[1]; f32x2 yc = S[2] * r4[2]; yc += S[3] * r4[3]; y += yc;
;                 y = red16p(y);
;                 *(LAS unsigned*)(yb + st * 128 + row0 * 2) = pk2(y.x, y.y);
;                 if (st < T - 1) { r4 = nr4; d4 = nd4; k4 = nk4; kk4 = nkk4; b4 = nb4; v2 = nv2; }
;             }
;             __syncthreads();
;             if (tid < T * 4) { const int rowi = tid >> 2, seg = tid & 3;
;                 *(u32x4*)(Y + ((size_t)b * SEQ + c * T + rowi) * 512 + h * 64 + halfsel * 32 + seg * 8) = *(const LAS u32x4*)(yb + rowi * 128 + halfsel * 64 + seg * 16); }
	v_pk_mul_f32 v[24:25], v[26:27], v[22:23] op_sel_hi:[0,1]
	v_pk_mul_f32 v[26:27], v[26:27], v[22:23] op_sel:[1,0]
	v_pk_fma_f32 v[24:25], v[6:7], v[54:55], v[24:25] op_sel_hi:[0,1,1] neg_lo:[0,0,1] neg_hi:[0,0,1]
	v_pk_fma_f32 v[6:7], v[6:7], v[50:51], v[26:27] op_sel:[1,0,0] neg_lo:[0,0,1] neg_hi:[0,0,1]
	s_waitcnt lgkmcnt(0)
	v_pk_fma_f32 v[24:25], v[18:19], v[60:61], v[24:25] op_sel_hi:[0,1,1]
	v_pk_fma_f32 v[6:7], v[18:19], v[60:61], v[6:7] op_sel:[1,0,0]
	v_pk_mul_f32 v[18:19], v[28:29], v[22:23] op_sel_hi:[0,1]
	v_pk_fma_f32 v[18:19], v[8:9], v[56:57], v[18:19] op_sel_hi:[0,1,1] neg_lo:[0,0,1] neg_hi:[0,0,1]
	v_pk_fma_f32 v[18:19], v[20:21], v[60:61], v[18:19] op_sel_hi:[0,1,1]
	v_mov_b32_e32 v20, v29
	v_mov_b32_e32 v8, v9
	v_pk_mul_f32 v[22:23], v[20:21], v[22:23] op_sel_hi:[0,1]
	v_pk_fma_f32 v[8:9], v[8:9], v[52:53], v[22:23] op_sel_hi:[0,1,1] neg_lo:[0,0,1] neg_hi:[0,0,1]
	v_mov_b32_e32 v20, v21
	s_nop 1
	v_add_f32_dpp v30, v30, v30 quad_perm:[1,0,3,2] row_mask:0xf bank_mask:0xf bound_ctrl:1
	v_add_f32_dpp v31, v31, v31 quad_perm:[1,0,3,2] row_mask:0xf bank_mask:0xf bound_ctrl:1
	v_pk_fma_f32 v[8:9], v[20:21], v[60:61], v[8:9] op_sel_hi:[0,1,1]
	v_pk_mul_f32 v[20:21], v[2:3], v[6:7] op_sel:[1,0]
	s_nop 1
	v_add_f32_dpp v30, v30, v30 quad_perm:[2,3,0,1] row_mask:0xf bank_mask:0xf bound_ctrl:1
	v_add_f32_dpp v31, v31, v31 quad_perm:[2,3,0,1] row_mask:0xf bank_mask:0xf bound_ctrl:1
	s_nop 0
	v_pk_fma_f32 v[2:3], v[2:3], v[24:25], v[20:21] op_sel_hi:[0,1,1]
	v_mov_b32_e32 v20, v5
	s_nop 1
	v_add_f32_dpp v30, v30, v30 row_half_mirror row_mask:0xf bank_mask:0xf bound_ctrl:1
	v_add_f32_dpp v31, v31, v31 row_half_mirror row_mask:0xf bank_mask:0xf bound_ctrl:1
	v_pk_mul_f32 v[20:21], v[20:21], v[8:9] op_sel_hi:[0,1]
	s_nop 1
	v_add_f32_dpp v30, v30, v30 row_mirror row_mask:0xf bank_mask:0xf bound_ctrl:1
	v_add_f32_dpp v31, v31, v31 row_mirror row_mask:0xf bank_mask:0xf bound_ctrl:1
	v_pk_fma_f32 v[4:5], v[4:5], v[18:19], v[20:21] op_sel_hi:[0,1,1]
	v_cvt_pk_bf16_f32 v17, v30, v31
	ds_write_b32 v14, v17 offset:3712
	v_pk_add_f32 v[2:3], v[2:3], v[4:5]
	ds_read_b128 v[30:33], v15 offset:47616
	ds_read_b128 v[34:37], v15 offset:47872
	ds_read_b128 v[38:41], v15 offset:48128
	ds_read_b128 v[42:45], v15 offset:48384
	ds_read_b128 v[46:49], v15 offset:48640
	ds_read_b64 v[16:17], v16 offset:48896
	s_nop 1
	v_add_f32_dpp v2, v2, v2 quad_perm:[1,0,3,2] row_mask:0xf bank_mask:0xf bound_ctrl:1
	v_add_f32_dpp v3, v3, v3 quad_perm:[1,0,3,2] row_mask:0xf bank_mask:0xf bound_ctrl:1
	v_add_u32_e32 v14, 0xc00, v14
	s_nop 1
	v_add_f32_dpp v2, v2, v2 quad_perm:[2,3,0,1] row_mask:0xf bank_mask:0xf bound_ctrl:1
	v_add_f32_dpp v3, v3, v3 quad_perm:[2,3,0,1] row_mask:0xf bank_mask:0xf bound_ctrl:1
	s_waitcnt lgkmcnt(2)
	v_mov_b32_e32 v4, v45
	s_nop 1
	v_add_f32_dpp v2, v2, v2 row_half_mirror row_mask:0xf bank_mask:0xf bound_ctrl:1
	v_add_f32_dpp v3, v3, v3 row_half_mirror row_mask:0xf bank_mask:0xf bound_ctrl:1
	v_pk_mul_f32 v[4:5], v[4:5], v[8:9] op_sel_hi:[0,1]
	s_nop 1
	v_add_f32_dpp v2, v2, v2 row_mirror row_mask:0xf bank_mask:0xf bound_ctrl:1
	v_add_f32_dpp v3, v3, v3 row_mirror row_mask:0xf bank_mask:0xf bound_ctrl:1
	v_pk_fma_f32 v[4:5], v[44:45], v[18:19], v[4:5] op_sel_hi:[0,1,1]
	v_cvt_pk_bf16_f32 v15, v2, v3
	v_pk_mul_f32 v[2:3], v[42:43], v[6:7] op_sel:[1,0]
	s_waitcnt lgkmcnt(1)
	v_mov_b32_e32 v22, v49
	v_pk_fma_f32 v[2:3], v[42:43], v[24:25], v[2:3] op_sel_hi:[0,1,1]
	v_pk_add_f32 v[20:21], v[2:3], v[4:5]
	s_nop 0
	s_nop 1
	v_add_f32_dpp v20, v20, v20 quad_perm:[1,0,3,2] row_mask:0xf bank_mask:0xf bound_ctrl:1
	v_add_f32_dpp v21, v21, v21 quad_perm:[1,0,3,2] row_mask:0xf bank_mask:0xf bound_ctrl:1
	s_nop 1
	v_add_f32_dpp v20, v20, v20 quad_perm:[2,3,0,1] row_mask:0xf bank_mask:0xf bound_ctrl:1
	v_add_f32_dpp v21, v21, v21 quad_perm:[2,3,0,1] row_mask:0xf bank_mask:0xf bound_ctrl:1
	s_nop 1
	v_add_f32_dpp v20, v20, v20 row_half_mirror row_mask:0xf bank_mask:0xf bound_ctrl:1
	v_add_f32_dpp v21, v21, v21 row_half_mirror row_mask:0xf bank_mask:0xf bound_ctrl:1
	s_nop 1
	v_add_f32_dpp v20, v20, v20 row_mirror row_mask:0xf bank_mask:0xf bound_ctrl:1
	v_add_f32_dpp v21, v21, v21 row_mirror row_mask:0xf bank_mask:0xf bound_ctrl:1
	s_nop 0
	v_pk_mul_f32 v[4:5], v[46:47], v[20:21] op_sel:[1,0]
	v_pk_mul_f32 v[2:3], v[46:47], v[20:21] op_sel_hi:[0,1]
	v_pk_fma_f32 v[4:5], v[34:35], v[6:7], v[4:5] op_sel:[1,0,0] neg_lo:[0,0,1] neg_hi:[0,0,1]
	v_pk_mul_f32 v[6:7], v[48:49], v[20:21] op_sel_hi:[0,1]
	v_pk_fma_f32 v[6:7], v[36:37], v[18:19], v[6:7] op_sel_hi:[0,1,1] neg_lo:[0,0,1] neg_hi:[0,0,1]
	v_mov_b32_e32 v18, v37
	v_pk_mul_f32 v[20:21], v[22:23], v[20:21] op_sel_hi:[0,1]
	v_pk_fma_f32 v[8:9], v[18:19], v[8:9], v[20:21] op_sel_hi:[0,1,1] neg_lo:[0,0,1] neg_hi:[0,0,1]
	v_mov_b32_e32 v18, v41
	v_pk_fma_f32 v[2:3], v[34:35], v[24:25], v[2:3] op_sel_hi:[0,1,1] neg_lo:[0,0,1] neg_hi:[0,0,1]
	s_waitcnt lgkmcnt(0)
	v_pk_fma_f32 v[4:5], v[38:39], v[16:17], v[4:5] op_sel:[1,0,0]
	v_pk_fma_f32 v[8:9], v[18:19], v[16:17], v[8:9] op_sel_hi:[0,1,1]
	v_mov_b32_e32 v18, v33
	v_pk_fma_f32 v[2:3], v[38:39], v[16:17], v[2:3] op_sel_hi:[0,1,1]
	v_pk_fma_f32 v[6:7], v[40:41], v[16:17], v[6:7] op_sel_hi:[0,1,1]
	v_pk_mul_f32 v[16:17], v[30:31], v[4:5] op_sel:[1,0]
	v_pk_mul_f32 v[18:19], v[18:19], v[8:9] op_sel_hi:[0,1]
	v_pk_fma_f32 v[16:17], v[30:31], v[2:3], v[16:17] op_sel_hi:[0,1,1]
	v_pk_fma_f32 v[18:19], v[32:33], v[6:7], v[18:19] op_sel_hi:[0,1,1]
	v_pk_add_f32 v[16:17], v[16:17], v[18:19]
	s_nop 0
	s_nop 1
	v_add_f32_dpp v16, v16, v16 quad_perm:[1,0,3,2] row_mask:0xf bank_mask:0xf bound_ctrl:1
	v_add_f32_dpp v17, v17, v17 quad_perm:[1,0,3,2] row_mask:0xf bank_mask:0xf bound_ctrl:1
	s_nop 1
	v_add_f32_dpp v16, v16, v16 quad_perm:[2,3,0,1] row_mask:0xf bank_mask:0xf bound_ctrl:1
	v_add_f32_dpp v17, v17, v17 quad_perm:[2,3,0,1] row_mask:0xf bank_mask:0xf bound_ctrl:1
	s_nop 1
	v_add_f32_dpp v16, v16, v16 row_half_mirror row_mask:0xf bank_mask:0xf bound_ctrl:1
	v_add_f32_dpp v17, v17, v17 row_half_mirror row_mask:0xf bank_mask:0xf bound_ctrl:1
	s_nop 1
	v_add_f32_dpp v16, v16, v16 row_mirror row_mask:0xf bank_mask:0xf bound_ctrl:1
	v_add_f32_dpp v17, v17, v17 row_mirror row_mask:0xf bank_mask:0xf bound_ctrl:1
	s_nop 0
	v_cvt_pk_bf16_f32 v16, v16, v17
	ds_write2_b32 v14, v15, v16 offset0:192 offset1:224
	s_waitcnt lgkmcnt(0)
	s_barrier
	s_and_saveexec_b64 s[2:3], vcc
	s_cbranch_execz .LBB0_496
	v_readlane_b32 s6, v247, 9
	s_add_i32 s5, s6, s5
	v_add3_u32 v14, s5, v13, v128
	ds_read_b128 v[14:17], v14
	s_waitcnt lgkmcnt(0)
	global_store_dwordx4 v[0:1], v[14:17], off
	s_branch .LBB0_496
